# none_rmwait
# speedup vs baseline: 1.0070x; 1.0014x over previous
; #define WAIT_V(n) asm volatile("s_waitcnt vmcnt(" #n ")" ::: "memory")
; #define WAIT_L(n) asm volatile("s_waitcnt lgkmcnt(" #n ")" ::: "memory")
; #define BAR __builtin_amdgcn_s_barrier()
; #define SCHED __builtin_amdgcn_sched_barrier(0)
; __device__ __forceinline__ void mainloop_8phase(const u16* __restrict__ A, const u16* __restrict__ Bt, int K,
;                                                 f32x4 (&acc)[2][2][4][2], int wid_s, int ld) {
;     ...
;     LDB(B0, 0, 0); SCHED; LDA(At, 0, 0); STAGE(SA(1, 1), A, brow + G_HALF, t + 1);
;     WAIT_L(8); BAR; WAIT_L(0); MMA(0, 0, At, B0); BAR; SCHED;
;     LDB(B1, 0, 1); STAGE(SB(0, 0), Bt, bcol, t + 2);
;     BAR; WAIT_L(0); MMA(0, 1, At, B1); BAR;
;     LDA(At, 0, 1); STAGE(SA(0, 0), A, brow, t + 2);
;     BAR; WAIT_L(0); MMA(1, 0, At, B0); BAR; SCHED;
;     STAGE(SB(0, 1), Bt, bcol + G_HALF, t + 2);
;     WAIT_V(6); BAR; MMA(1, 1, At, B1); BAR;
.LBB0_58:
	ds_read_b128 v[156:159], v155
	ds_read_b128 v[160:163], v155 offset:1024
	ds_read_b128 v[164:167], v155 offset:2048
	ds_read_b128 v[168:171], v155 offset:3072
	v_readfirstlane_b32 s7, v145
	s_add_i32 s6, s1, 0xffffff00
	s_mov_b32 m0, s7
	v_readfirstlane_b32 s7, v144
	ds_read_b128 v[172:175], v133
	ds_read_b128 v[176:179], v133 offset:1024
	ds_read_b128 v[180:183], v132
	ds_read_b128 v[184:187], v132 offset:1024
	ds_read_b128 v[188:191], v131
	ds_read_b128 v[192:195], v131 offset:1024
	ds_read_b128 v[196:199], v130
	ds_read_b128 v[200:203], v130 offset:1024
	buffer_load_dwordx4 v137, s[88:91], s6 offen lds
	s_mov_b32 m0, s7
	s_nop 0
	buffer_load_dwordx4 v136, s[88:91], s6 offen lds
	s_waitcnt lgkmcnt(8)
	s_barrier
	s_waitcnt lgkmcnt(0)
	v_mfma_f32_16x16x32_bf16 v[126:129], v[172:175], v[156:159], v[126:129]
	v_mfma_f32_16x16x32_bf16 v[122:125], v[172:175], v[164:167], v[122:125]
	v_mfma_f32_16x16x32_bf16 v[118:121], v[180:183], v[156:159], v[118:121]
	v_mfma_f32_16x16x32_bf16 v[114:117], v[180:183], v[164:167], v[114:117]
	v_mfma_f32_16x16x32_bf16 v[110:113], v[188:191], v[156:159], v[110:113]
	v_mfma_f32_16x16x32_bf16 v[106:109], v[188:191], v[164:167], v[106:109]
	v_mfma_f32_16x16x32_bf16 v[102:105], v[196:199], v[156:159], v[102:105]
	v_mfma_f32_16x16x32_bf16 v[98:101], v[196:199], v[164:167], v[98:101]
	v_mfma_f32_16x16x32_bf16 v[126:129], v[176:179], v[160:163], v[126:129]
	v_mfma_f32_16x16x32_bf16 v[122:125], v[176:179], v[168:171], v[122:125]
	v_mfma_f32_16x16x32_bf16 v[118:121], v[184:187], v[160:163], v[118:121]
	v_mfma_f32_16x16x32_bf16 v[114:117], v[184:187], v[168:171], v[114:117]
	v_mfma_f32_16x16x32_bf16 v[110:113], v[192:195], v[160:163], v[110:113]
	v_mfma_f32_16x16x32_bf16 v[106:109], v[192:195], v[168:171], v[106:109]
	v_mfma_f32_16x16x32_bf16 v[102:105], v[200:203], v[160:163], v[102:105]
	v_mfma_f32_16x16x32_bf16 v[98:101], v[200:203], v[168:171], v[98:101]
	s_barrier
	v_readfirstlane_b32 s16, v148
	s_add_i32 s15, s1, 0xfff7ff80
	s_mov_b32 s6, s90
	s_mov_b32 s7, s91
	s_mov_b32 m0, s16
	v_readfirstlane_b32 s16, v149
	ds_read_b128 v[204:207], v147
	ds_read_b128 v[208:211], v147 offset:1024
	ds_read_b128 v[212:215], v147 offset:2048
	ds_read_b128 v[216:219], v147 offset:3072
	buffer_load_dwordx4 v137, s[4:7], s15 offen lds
	s_mov_b32 m0, s16
	s_nop 0
	buffer_load_dwordx4 v136, s[4:7], s15 offen lds
	s_barrier
	s_waitcnt lgkmcnt(0)
	v_mfma_f32_16x16x32_bf16 v[94:97], v[172:175], v[204:207], v[94:97]
	v_mfma_f32_16x16x32_bf16 v[90:93], v[172:175], v[212:215], v[90:93]
	v_mfma_f32_16x16x32_bf16 v[86:89], v[180:183], v[204:207], v[86:89]
	v_mfma_f32_16x16x32_bf16 v[82:85], v[180:183], v[212:215], v[82:85]
	v_mfma_f32_16x16x32_bf16 v[78:81], v[188:191], v[204:207], v[78:81]
	v_mfma_f32_16x16x32_bf16 v[74:77], v[188:191], v[212:215], v[74:77]
	v_mfma_f32_16x16x32_bf16 v[70:73], v[196:199], v[204:207], v[70:73]
	v_mfma_f32_16x16x32_bf16 v[66:69], v[196:199], v[212:215], v[66:69]
	v_mfma_f32_16x16x32_bf16 v[94:97], v[176:179], v[208:211], v[94:97]
	v_mfma_f32_16x16x32_bf16 v[90:93], v[176:179], v[216:219], v[90:93]
	v_mfma_f32_16x16x32_bf16 v[86:89], v[184:187], v[208:211], v[86:89]
	v_mfma_f32_16x16x32_bf16 v[82:85], v[184:187], v[216:219], v[82:85]
	v_mfma_f32_16x16x32_bf16 v[78:81], v[192:195], v[208:211], v[78:81]
	v_mfma_f32_16x16x32_bf16 v[74:77], v[192:195], v[216:219], v[74:77]
	v_mfma_f32_16x16x32_bf16 v[70:73], v[200:203], v[208:211], v[70:73]
	v_mfma_f32_16x16x32_bf16 v[66:69], v[200:203], v[216:219], v[66:69]
	v_readfirstlane_b32 s16, v140
	s_mov_b32 m0, s16
	v_readfirstlane_b32 s16, v150
	s_barrier
	ds_read_b128 v[172:175], v133 offset:16384
	ds_read_b128 v[176:179], v133 offset:17408
	ds_read_b128 v[180:183], v132 offset:16384
	ds_read_b128 v[184:187], v132 offset:17408
	ds_read_b128 v[188:191], v131 offset:16384
	ds_read_b128 v[192:195], v131 offset:17408
	ds_read_b128 v[196:199], v130 offset:16384
	ds_read_b128 v[200:203], v130 offset:17408
	buffer_load_dwordx4 v137, s[88:91], s15 offen lds
	s_mov_b32 m0, s16
	s_nop 0
	buffer_load_dwordx4 v136, s[88:91], s15 offen lds
	s_barrier
	s_waitcnt lgkmcnt(0)
	v_mfma_f32_16x16x32_bf16 v[62:65], v[172:175], v[156:159], v[62:65]
	v_mfma_f32_16x16x32_bf16 v[58:61], v[172:175], v[164:167], v[58:61]
	v_mfma_f32_16x16x32_bf16 v[54:57], v[180:183], v[156:159], v[54:57]
	v_mfma_f32_16x16x32_bf16 v[50:53], v[180:183], v[164:167], v[50:53]
	v_mfma_f32_16x16x32_bf16 v[46:49], v[188:191], v[156:159], v[46:49]
	v_mfma_f32_16x16x32_bf16 v[42:45], v[188:191], v[164:167], v[42:45]
	v_mfma_f32_16x16x32_bf16 v[38:41], v[196:199], v[156:159], v[38:41]
	v_mfma_f32_16x16x32_bf16 v[34:37], v[196:199], v[164:167], v[34:37]
	v_mfma_f32_16x16x32_bf16 v[62:65], v[176:179], v[160:163], v[62:65]
	v_mfma_f32_16x16x32_bf16 v[58:61], v[176:179], v[168:171], v[58:61]
	v_mfma_f32_16x16x32_bf16 v[54:57], v[184:187], v[160:163], v[54:57]
	v_mfma_f32_16x16x32_bf16 v[50:53], v[184:187], v[168:171], v[50:53]
	v_mfma_f32_16x16x32_bf16 v[46:49], v[192:195], v[160:163], v[46:49]
	v_mfma_f32_16x16x32_bf16 v[42:45], v[192:195], v[168:171], v[42:45]
	v_mfma_f32_16x16x32_bf16 v[38:41], v[200:203], v[160:163], v[38:41]
	v_mfma_f32_16x16x32_bf16 v[34:37], v[200:203], v[168:171], v[34:37]
	s_barrier
	v_readfirstlane_b32 s16, v151
	s_add_i32 s15, s1, 0xffffff80
	s_mov_b32 m0, s16
	v_readfirstlane_b32 s16, v152
	buffer_load_dwordx4 v137, s[4:7], s15 offen lds
	s_mov_b32 m0, s16
	s_nop 0
	buffer_load_dwordx4 v136, s[4:7], s15 offen lds
	s_waitcnt vmcnt(6)
	s_barrier
; #define WAIT_V(n) asm volatile("s_waitcnt vmcnt(" #n ")" ::: "memory")
; #define WAIT_L(n) asm volatile("s_waitcnt lgkmcnt(" #n ")" ::: "memory")
; #define BAR __builtin_amdgcn_s_barrier()
; #define SCHED __builtin_amdgcn_sched_barrier(0)
; __device__ __forceinline__ void mainloop_8phase(const u16* __restrict__ A, const u16* __restrict__ Bt, int K,
;                                                 f32x4 (&acc)[2][2][4][2], int wid_s, int ld) {
;     ...
;     WAIT_V(6); BAR; MMA(1, 1, At, B1); BAR;
;     LDB(B0, 1, 0); SCHED; LDA(At, 1, 0); STAGE(SA(0, 1), A, brow + G_HALF, t + 2);
;     WAIT_L(8); BAR; WAIT_L(0); MMA(0, 0, At, B0); BAR; SCHED;
;     LDB(B1, 1, 1); STAGE(SB(1, 0), Bt, bcol, t + 3);
;     BAR; WAIT_L(0); MMA(0, 1, At, B1); BAR;
;     LDA(At, 1, 1); STAGE(SA(1, 0), A, brow, t + 3);
	v_mfma_f32_16x16x32_bf16 v[30:33], v[172:175], v[204:207], v[30:33]
	v_mfma_f32_16x16x32_bf16 v[26:29], v[172:175], v[212:215], v[26:29]
	v_mfma_f32_16x16x32_bf16 v[22:25], v[180:183], v[204:207], v[22:25]
	v_mfma_f32_16x16x32_bf16 v[18:21], v[180:183], v[212:215], v[18:21]
	v_mfma_f32_16x16x32_bf16 v[14:17], v[188:191], v[204:207], v[14:17]
	v_mfma_f32_16x16x32_bf16 v[10:13], v[188:191], v[212:215], v[10:13]
	v_mfma_f32_16x16x32_bf16 v[6:9], v[196:199], v[204:207], v[6:9]
	v_mfma_f32_16x16x32_bf16 v[2:5], v[196:199], v[212:215], v[2:5]
	v_mfma_f32_16x16x32_bf16 v[30:33], v[176:179], v[208:211], v[30:33]
	v_mfma_f32_16x16x32_bf16 v[26:29], v[176:179], v[216:219], v[26:29]
	v_mfma_f32_16x16x32_bf16 v[22:25], v[184:187], v[208:211], v[22:25]
	v_mfma_f32_16x16x32_bf16 v[18:21], v[184:187], v[216:219], v[18:21]
	v_mfma_f32_16x16x32_bf16 v[14:17], v[192:195], v[208:211], v[14:17]
	v_mfma_f32_16x16x32_bf16 v[10:13], v[192:195], v[216:219], v[10:13]
	v_mfma_f32_16x16x32_bf16 v[6:9], v[200:203], v[208:211], v[6:9]
	v_mfma_f32_16x16x32_bf16 v[2:5], v[200:203], v[216:219], v[2:5]
	s_barrier
	ds_read_b128 v[156:159], v135
	ds_read_b128 v[160:163], v135 offset:1024
	ds_read_b128 v[164:167], v135 offset:2048
	ds_read_b128 v[168:171], v135 offset:3072
	v_readfirstlane_b32 s16, v153
	s_mov_b32 m0, s16
	v_readfirstlane_b32 s16, v154
	ds_read_b128 v[172:175], v133 offset:32768
	ds_read_b128 v[176:179], v133 offset:33792
	ds_read_b128 v[180:183], v132 offset:32768
	ds_read_b128 v[184:187], v132 offset:33792
	ds_read_b128 v[188:191], v131 offset:32768
	ds_read_b128 v[192:195], v131 offset:33792
	ds_read_b128 v[196:199], v130 offset:32768
	ds_read_b128 v[200:203], v130 offset:33792
	buffer_load_dwordx4 v137, s[88:91], s15 offen lds
	s_mov_b32 m0, s16
	s_nop 0
	buffer_load_dwordx4 v136, s[88:91], s15 offen lds
	s_waitcnt lgkmcnt(8)
	s_barrier
	s_waitcnt lgkmcnt(0)
	v_mfma_f32_16x16x32_bf16 v[126:129], v[172:175], v[156:159], v[126:129]
	v_mfma_f32_16x16x32_bf16 v[122:125], v[172:175], v[164:167], v[122:125]
	v_mfma_f32_16x16x32_bf16 v[118:121], v[180:183], v[156:159], v[118:121]
	v_mfma_f32_16x16x32_bf16 v[114:117], v[180:183], v[164:167], v[114:117]
	v_mfma_f32_16x16x32_bf16 v[110:113], v[188:191], v[156:159], v[110:113]
	v_mfma_f32_16x16x32_bf16 v[106:109], v[188:191], v[164:167], v[106:109]
	v_mfma_f32_16x16x32_bf16 v[102:105], v[196:199], v[156:159], v[102:105]
	v_mfma_f32_16x16x32_bf16 v[98:101], v[196:199], v[164:167], v[98:101]
	v_mfma_f32_16x16x32_bf16 v[126:129], v[176:179], v[160:163], v[126:129]
	v_mfma_f32_16x16x32_bf16 v[122:125], v[176:179], v[168:171], v[122:125]
	v_mfma_f32_16x16x32_bf16 v[118:121], v[184:187], v[160:163], v[118:121]
	v_mfma_f32_16x16x32_bf16 v[114:117], v[184:187], v[168:171], v[114:117]
	v_mfma_f32_16x16x32_bf16 v[110:113], v[192:195], v[160:163], v[110:113]
	v_mfma_f32_16x16x32_bf16 v[106:109], v[192:195], v[168:171], v[106:109]
	v_mfma_f32_16x16x32_bf16 v[102:105], v[200:203], v[160:163], v[102:105]
	v_mfma_f32_16x16x32_bf16 v[98:101], v[200:203], v[168:171], v[98:101]
	s_barrier
	v_readfirstlane_b32 s16, v138
	s_add_i32 s15, s1, 0xfff80000
	s_mov_b32 m0, s16
	v_readfirstlane_b32 s16, v139
	ds_read_b128 v[204:207], v134
	ds_read_b128 v[208:211], v134 offset:1024
	ds_read_b128 v[212:215], v134 offset:2048
	ds_read_b128 v[216:219], v134 offset:3072
	buffer_load_dwordx4 v137, s[4:7], s15 offen lds
	s_mov_b32 m0, s16
	s_nop 0
	buffer_load_dwordx4 v136, s[4:7], s15 offen lds
	s_barrier
	s_waitcnt lgkmcnt(0)
	v_mfma_f32_16x16x32_bf16 v[94:97], v[172:175], v[204:207], v[94:97]
	v_mfma_f32_16x16x32_bf16 v[90:93], v[172:175], v[212:215], v[90:93]
	v_mfma_f32_16x16x32_bf16 v[86:89], v[180:183], v[204:207], v[86:89]
	v_mfma_f32_16x16x32_bf16 v[82:85], v[180:183], v[212:215], v[82:85]
	v_mfma_f32_16x16x32_bf16 v[78:81], v[188:191], v[204:207], v[78:81]
	v_mfma_f32_16x16x32_bf16 v[74:77], v[188:191], v[212:215], v[74:77]
	v_mfma_f32_16x16x32_bf16 v[70:73], v[196:199], v[204:207], v[70:73]
	v_mfma_f32_16x16x32_bf16 v[66:69], v[196:199], v[212:215], v[66:69]
	v_mfma_f32_16x16x32_bf16 v[94:97], v[176:179], v[208:211], v[94:97]
	v_mfma_f32_16x16x32_bf16 v[90:93], v[176:179], v[216:219], v[90:93]
	v_mfma_f32_16x16x32_bf16 v[86:89], v[184:187], v[208:211], v[86:89]
	v_mfma_f32_16x16x32_bf16 v[82:85], v[184:187], v[216:219], v[82:85]
	v_mfma_f32_16x16x32_bf16 v[78:81], v[192:195], v[208:211], v[78:81]
	v_mfma_f32_16x16x32_bf16 v[74:77], v[192:195], v[216:219], v[74:77]
	v_mfma_f32_16x16x32_bf16 v[70:73], v[200:203], v[208:211], v[70:73]
	v_mfma_f32_16x16x32_bf16 v[66:69], v[200:203], v[216:219], v[66:69]
	v_readfirstlane_b32 s16, v141
	s_mov_b32 m0, s16
	v_readfirstlane_b32 s16, v142
	s_barrier
	ds_read_b128 v[172:175], v133 offset:49152
	ds_read_b128 v[176:179], v133 offset:50176
	ds_read_b128 v[180:183], v132 offset:49152
	ds_read_b128 v[184:187], v132 offset:50176
	ds_read_b128 v[188:191], v131 offset:49152
	ds_read_b128 v[192:195], v131 offset:50176
	ds_read_b128 v[196:199], v130 offset:49152
	ds_read_b128 v[200:203], v130 offset:50176
	buffer_load_dwordx4 v137, s[88:91], s15 offen lds
	s_mov_b32 m0, s16
	s_nop 0
	buffer_load_dwordx4 v136, s[88:91], s15 offen lds
	s_barrier
; #define WAIT_V(n) asm volatile("s_waitcnt vmcnt(" #n ")" ::: "memory")
; #define WAIT_L(n) asm volatile("s_waitcnt lgkmcnt(" #n ")" ::: "memory")
; #define BAR __builtin_amdgcn_s_barrier()
; #define SCHED __builtin_amdgcn_sched_barrier(0)
; __device__ __forceinline__ void mainloop_8phase(const u16* __restrict__ A, const u16* __restrict__ Bt, int K,
;                                                 f32x4 (&acc)[2][2][4][2], int wid_s, int ld) {
;     ...
;     BAR; WAIT_L(0); MMA(1, 0, At, B0); BAR; SCHED;
;     STAGE(SB(1, 1), Bt, bcol + G_HALF, t + 3);
;     WAIT_V(6); BAR; MMA(1, 1, At, B1); BAR;
;   }
;   { LDB(B0, 0, 0); LDA(At, 0, 0); STAGE(SA(1, 1), A, brow + G_HALF, nt - 1);
;     BAR; WAIT_L(0); MMA(0, 0, At, B0); BAR;
;     LDB(B1, 0, 1); BAR; WAIT_L(0); MMA(0, 1, At, B1); BAR;
	s_waitcnt lgkmcnt(0)
	v_mfma_f32_16x16x32_bf16 v[62:65], v[172:175], v[156:159], v[62:65]
	v_mfma_f32_16x16x32_bf16 v[58:61], v[172:175], v[164:167], v[58:61]
	v_mfma_f32_16x16x32_bf16 v[54:57], v[180:183], v[156:159], v[54:57]
	v_mfma_f32_16x16x32_bf16 v[50:53], v[180:183], v[164:167], v[50:53]
	v_mfma_f32_16x16x32_bf16 v[46:49], v[188:191], v[156:159], v[46:49]
	v_mfma_f32_16x16x32_bf16 v[42:45], v[188:191], v[164:167], v[42:45]
	v_mfma_f32_16x16x32_bf16 v[38:41], v[196:199], v[156:159], v[38:41]
	v_mfma_f32_16x16x32_bf16 v[34:37], v[196:199], v[164:167], v[34:37]
	v_mfma_f32_16x16x32_bf16 v[62:65], v[176:179], v[160:163], v[62:65]
	v_mfma_f32_16x16x32_bf16 v[58:61], v[176:179], v[168:171], v[58:61]
	v_mfma_f32_16x16x32_bf16 v[54:57], v[184:187], v[160:163], v[54:57]
	v_mfma_f32_16x16x32_bf16 v[50:53], v[184:187], v[168:171], v[50:53]
	v_mfma_f32_16x16x32_bf16 v[46:49], v[192:195], v[160:163], v[46:49]
	v_mfma_f32_16x16x32_bf16 v[42:45], v[192:195], v[168:171], v[42:45]
	v_mfma_f32_16x16x32_bf16 v[38:41], v[200:203], v[160:163], v[38:41]
	v_mfma_f32_16x16x32_bf16 v[34:37], v[200:203], v[168:171], v[34:37]
	s_barrier
	v_readfirstlane_b32 s15, v143
	s_mov_b32 m0, s15
	v_readfirstlane_b32 s15, v146
	buffer_load_dwordx4 v137, s[4:7], s1 offen lds
	s_mov_b32 m0, s15
	s_nop 0
	buffer_load_dwordx4 v136, s[4:7], s1 offen lds
	s_waitcnt vmcnt(6)
	s_barrier
	v_mfma_f32_16x16x32_bf16 v[30:33], v[172:175], v[204:207], v[30:33]
	v_mfma_f32_16x16x32_bf16 v[26:29], v[172:175], v[212:215], v[26:29]
	v_mfma_f32_16x16x32_bf16 v[22:25], v[180:183], v[204:207], v[22:25]
	v_mfma_f32_16x16x32_bf16 v[18:21], v[180:183], v[212:215], v[18:21]
	v_mfma_f32_16x16x32_bf16 v[14:17], v[188:191], v[204:207], v[14:17]
	v_mfma_f32_16x16x32_bf16 v[10:13], v[188:191], v[212:215], v[10:13]
	v_mfma_f32_16x16x32_bf16 v[6:9], v[196:199], v[204:207], v[6:9]
	v_mfma_f32_16x16x32_bf16 v[2:5], v[196:199], v[212:215], v[2:5]
	v_mfma_f32_16x16x32_bf16 v[30:33], v[176:179], v[208:211], v[30:33]
	v_mfma_f32_16x16x32_bf16 v[26:29], v[176:179], v[216:219], v[26:29]
	v_mfma_f32_16x16x32_bf16 v[22:25], v[184:187], v[208:211], v[22:25]
	v_mfma_f32_16x16x32_bf16 v[18:21], v[184:187], v[216:219], v[18:21]
	v_mfma_f32_16x16x32_bf16 v[14:17], v[192:195], v[208:211], v[14:17]
	v_mfma_f32_16x16x32_bf16 v[10:13], v[192:195], v[216:219], v[10:13]
	v_mfma_f32_16x16x32_bf16 v[6:9], v[200:203], v[208:211], v[6:9]
	v_mfma_f32_16x16x32_bf16 v[2:5], v[200:203], v[216:219], v[2:5]
	s_add_i32 s0, s0, 2
	s_addk_i32 s1, 0x100
	s_cmp_lt_u32 s0, 28
	s_barrier
	s_cbranch_scc1 .LBB0_58
	v_readfirstlane_b32 s0, v145
	s_mov_b32 m0, s0
	s_mov_b32 s1, 0x80f80
	v_readfirstlane_b32 s0, v144
	ds_read_b128 v[138:141], v155
	ds_read_b128 v[148:151], v155 offset:1024
	ds_read_b128 v[156:159], v155 offset:2048
	ds_read_b128 v[152:155], v155 offset:3072
	ds_read_b128 v[160:163], v133
	ds_read_b128 v[164:167], v133 offset:1024
	ds_read_b128 v[168:171], v132
	ds_read_b128 v[172:175], v132 offset:1024
	ds_read_b128 v[176:179], v131
	ds_read_b128 v[180:183], v131 offset:1024
	ds_read_b128 v[184:187], v130
	ds_read_b128 v[188:191], v130 offset:1024
	buffer_load_dwordx4 v137, s[88:91], s1 offen lds
	s_mov_b32 m0, s0
	s_nop 0
	buffer_load_dwordx4 v136, s[88:91], s1 offen lds
	s_barrier
	s_waitcnt lgkmcnt(0)
	v_mfma_f32_16x16x32_bf16 v[126:129], v[160:163], v[138:141], v[126:129]
	v_mfma_f32_16x16x32_bf16 v[122:125], v[160:163], v[156:159], v[122:125]
	v_mfma_f32_16x16x32_bf16 v[118:121], v[168:171], v[138:141], v[118:121]
	v_mfma_f32_16x16x32_bf16 v[114:117], v[168:171], v[156:159], v[114:117]
	v_mfma_f32_16x16x32_bf16 v[102:105], v[184:187], v[138:141], v[102:105]
	v_mfma_f32_16x16x32_bf16 v[98:101], v[184:187], v[156:159], v[98:101]
	v_mfma_f32_16x16x32_bf16 v[126:129], v[164:167], v[148:151], v[126:129]
	v_mfma_f32_16x16x32_bf16 v[122:125], v[164:167], v[152:155], v[122:125]
	v_mfma_f32_16x16x32_bf16 v[118:121], v[172:175], v[148:151], v[118:121]
	v_mfma_f32_16x16x32_bf16 v[114:117], v[172:175], v[152:155], v[114:117]
	v_mfma_f32_16x16x32_bf16 v[110:113], v[176:179], v[138:141], v[110:113]
	v_mfma_f32_16x16x32_bf16 v[106:109], v[176:179], v[156:159], v[106:109]
	v_mfma_f32_16x16x32_bf16 v[102:105], v[188:191], v[148:151], v[102:105]
	v_mfma_f32_16x16x32_bf16 v[98:101], v[188:191], v[152:155], v[98:101]
	v_mfma_f32_16x16x32_bf16 v[142:145], v[180:183], v[148:151], v[110:113]
	v_mfma_f32_16x16x32_bf16 v[192:195], v[180:183], v[152:155], v[106:109]
	s_barrier
	s_nop 0
	ds_read_b128 v[106:109], v147
	ds_read_b128 v[110:113], v147 offset:1024
	ds_read_b128 v[196:199], v147 offset:2048
	ds_read_b128 v[200:203], v147 offset:3072
	s_barrier
	s_waitcnt lgkmcnt(0)
	v_mfma_f32_16x16x32_bf16 v[86:89], v[168:171], v[106:109], v[86:89]
	v_mfma_f32_16x16x32_bf16 v[82:85], v[168:171], v[196:199], v[82:85]
	v_mfma_f32_16x16x32_bf16 v[70:73], v[184:187], v[106:109], v[70:73]
	v_mfma_f32_16x16x32_bf16 v[66:69], v[184:187], v[196:199], v[66:69]
	v_mfma_f32_16x16x32_bf16 v[94:97], v[160:163], v[106:109], v[94:97]
	v_mfma_f32_16x16x32_bf16 v[90:93], v[160:163], v[196:199], v[90:93]
	v_mfma_f32_16x16x32_bf16 v[86:89], v[172:175], v[110:113], v[86:89]
	v_mfma_f32_16x16x32_bf16 v[82:85], v[172:175], v[200:203], v[82:85]
	v_mfma_f32_16x16x32_bf16 v[78:81], v[176:179], v[106:109], v[78:81]
	v_mfma_f32_16x16x32_bf16 v[74:77], v[176:179], v[196:199], v[74:77]
	v_mfma_f32_16x16x32_bf16 v[70:73], v[188:191], v[110:113], v[70:73]
	v_mfma_f32_16x16x32_bf16 v[66:69], v[188:191], v[200:203], v[66:69]
	v_mfma_f32_16x16x32_bf16 v[204:207], v[164:167], v[110:113], v[94:97]
	v_mfma_f32_16x16x32_bf16 v[160:163], v[164:167], v[200:203], v[90:93]
	v_mfma_f32_16x16x32_bf16 v[164:167], v[180:183], v[110:113], v[78:81]
	v_mfma_f32_16x16x32_bf16 v[168:171], v[180:183], v[200:203], v[74:77]
	s_barrier
; #define WAIT_V(n) asm volatile("s_waitcnt vmcnt(" #n ")" ::: "memory")
; #define WAIT_L(n) asm volatile("s_waitcnt lgkmcnt(" #n ")" ::: "memory")
; #define BAR __builtin_amdgcn_s_barrier()
; __device__ __forceinline__ void mainloop_8phase(const u16* __restrict__ A, const u16* __restrict__ Bt, int K,
;                                                 f32x4 (&acc)[2][2][4][2], int wid_s, int ld) {
;     ...
;     LDA(At, 0, 1); WAIT_V(4); BAR; WAIT_L(0); MMA(1, 0, At, B0); MMA(1, 1, At, B1); BAR; }
;   { LDB(B0, 1, 0); LDA(At, 1, 0); WAIT_V(2); BAR; WAIT_L(0); MMA(0, 0, At, B0); BAR;
	s_nop 0
	ds_read_b128 v[74:77], v133 offset:16384
	ds_read_b128 v[78:81], v133 offset:17408
	ds_read_b128 v[90:93], v132 offset:16384
	ds_read_b128 v[94:97], v132 offset:17408
	ds_read_b128 v[172:175], v131 offset:16384
	ds_read_b128 v[176:179], v131 offset:17408
	ds_read_b128 v[180:183], v130 offset:16384
	ds_read_b128 v[184:187], v130 offset:17408
	s_waitcnt vmcnt(4)
	s_barrier
	s_waitcnt lgkmcnt(0)
	v_mfma_f32_16x16x32_bf16 v[62:65], v[74:77], v[138:141], v[62:65]
	v_mfma_f32_16x16x32_bf16 v[58:61], v[74:77], v[156:159], v[58:61]
	v_mfma_f32_16x16x32_bf16 v[54:57], v[90:93], v[138:141], v[54:57]
	v_mfma_f32_16x16x32_bf16 v[50:53], v[90:93], v[156:159], v[50:53]
	v_mfma_f32_16x16x32_bf16 v[38:41], v[180:183], v[138:141], v[38:41]
	v_mfma_f32_16x16x32_bf16 v[34:37], v[180:183], v[156:159], v[34:37]
	v_mfma_f32_16x16x32_bf16 v[62:65], v[78:81], v[148:151], v[62:65]
	v_mfma_f32_16x16x32_bf16 v[58:61], v[78:81], v[152:155], v[58:61]
	v_mfma_f32_16x16x32_bf16 v[54:57], v[94:97], v[148:151], v[54:57]
	v_mfma_f32_16x16x32_bf16 v[50:53], v[94:97], v[152:155], v[50:53]
	v_mfma_f32_16x16x32_bf16 v[46:49], v[172:175], v[138:141], v[46:49]
	v_mfma_f32_16x16x32_bf16 v[42:45], v[172:175], v[156:159], v[42:45]
	v_mfma_f32_16x16x32_bf16 v[38:41], v[184:187], v[148:151], v[38:41]
	v_mfma_f32_16x16x32_bf16 v[34:37], v[184:187], v[152:155], v[34:37]
	v_mfma_f32_16x16x32_bf16 v[188:191], v[176:179], v[148:151], v[46:49]
	v_mfma_f32_16x16x32_bf16 v[208:211], v[176:179], v[152:155], v[42:45]
	v_mfma_f32_16x16x32_bf16 v[22:25], v[90:93], v[106:109], v[22:25]
	v_mfma_f32_16x16x32_bf16 v[18:21], v[90:93], v[196:199], v[18:21]
	v_mfma_f32_16x16x32_bf16 v[6:9], v[180:183], v[106:109], v[6:9]
	v_mfma_f32_16x16x32_bf16 v[2:5], v[180:183], v[196:199], v[2:5]
	v_mfma_f32_16x16x32_bf16 v[30:33], v[74:77], v[106:109], v[30:33]
	v_mfma_f32_16x16x32_bf16 v[26:29], v[74:77], v[196:199], v[26:29]
	v_mfma_f32_16x16x32_bf16 v[22:25], v[94:97], v[110:113], v[22:25]
	v_mfma_f32_16x16x32_bf16 v[18:21], v[94:97], v[200:203], v[18:21]
	v_mfma_f32_16x16x32_bf16 v[14:17], v[172:175], v[106:109], v[14:17]
	v_mfma_f32_16x16x32_bf16 v[10:13], v[172:175], v[196:199], v[10:13]
	v_mfma_f32_16x16x32_bf16 v[6:9], v[184:187], v[110:113], v[6:9]
	v_mfma_f32_16x16x32_bf16 v[2:5], v[184:187], v[200:203], v[2:5]
	v_mfma_f32_16x16x32_bf16 v[136:139], v[78:81], v[110:113], v[30:33]
	v_mfma_f32_16x16x32_bf16 v[146:149], v[78:81], v[200:203], v[26:29]
	v_mfma_f32_16x16x32_bf16 v[150:153], v[176:179], v[110:113], v[14:17]
	v_mfma_f32_16x16x32_bf16 v[154:157], v[176:179], v[200:203], v[10:13]
	s_barrier
	s_nop 0
	ds_read_b128 v[10:13], v135
	ds_read_b128 v[14:17], v135 offset:1024
	ds_read_b128 v[172:175], v135 offset:2048
	ds_read_b128 v[176:179], v135 offset:3072
	ds_read_b128 v[26:29], v133 offset:32768
	ds_read_b128 v[30:33], v133 offset:33792
	ds_read_b128 v[42:45], v132 offset:32768
	ds_read_b128 v[46:49], v132 offset:33792
	ds_read_b128 v[180:183], v131 offset:32768
	ds_read_b128 v[184:187], v131 offset:33792
	ds_read_b128 v[196:199], v130 offset:32768
	ds_read_b128 v[200:203], v130 offset:33792
	s_waitcnt vmcnt(2)
	s_barrier
	s_waitcnt lgkmcnt(0)
	v_mfma_f32_16x16x32_bf16 v[74:77], v[26:29], v[10:13], v[126:129]
	v_mfma_f32_16x16x32_bf16 v[126:129], v[30:33], v[14:17], v[74:77]
	v_mfma_f32_16x16x32_bf16 v[74:77], v[26:29], v[172:175], v[122:125]
	v_mfma_f32_16x16x32_bf16 v[122:125], v[30:33], v[176:179], v[74:77]
	v_mfma_f32_16x16x32_bf16 v[74:77], v[42:45], v[10:13], v[118:121]
	v_mfma_f32_16x16x32_bf16 v[110:113], v[46:49], v[14:17], v[74:77]
	v_mfma_f32_16x16x32_bf16 v[74:77], v[42:45], v[172:175], v[114:117]
	v_mfma_f32_16x16x32_bf16 v[106:109], v[46:49], v[176:179], v[74:77]
	v_mfma_f32_16x16x32_bf16 v[74:77], v[180:183], v[10:13], v[142:145]
	v_mfma_f32_16x16x32_bf16 v[94:97], v[184:187], v[14:17], v[74:77]
	v_mfma_f32_16x16x32_bf16 v[74:77], v[180:183], v[172:175], v[192:195]
	v_mfma_f32_16x16x32_bf16 v[90:93], v[184:187], v[176:179], v[74:77]
	v_mfma_f32_16x16x32_bf16 v[74:77], v[196:199], v[10:13], v[102:105]
	v_mfma_f32_16x16x32_bf16 v[78:81], v[200:203], v[14:17], v[74:77]
	v_mfma_f32_16x16x32_bf16 v[74:77], v[196:199], v[172:175], v[98:101]
	v_mfma_f32_16x16x32_bf16 v[74:77], v[200:203], v[176:179], v[74:77]
	s_barrier
; #define WAIT_V(n) asm volatile("s_waitcnt vmcnt(" #n ")" ::: "memory")
; #define WAIT_L(n) asm volatile("s_waitcnt lgkmcnt(" #n ")" ::: "memory")
; #define BAR __builtin_amdgcn_s_barrier()
; __device__ __forceinline__ void mainloop_8phase(const u16* __restrict__ A, const u16* __restrict__ Bt, int K,
;                                                 f32x4 (&acc)[2][2][4][2], int wid_s, int ld) {
;     ...
;   { LDB(B0, 1, 0); LDA(At, 1, 0); WAIT_V(2); BAR; WAIT_L(0); MMA(0, 0, At, B0); BAR;
;     LDB(B1, 1, 1); WAIT_V(0); BAR; WAIT_L(0); MMA(0, 1, At, B1); BAR;
;     LDA(At, 1, 1); BAR; WAIT_L(0); MMA(1, 0, At, B0); MMA(1, 1, At, B1); BAR; }
;   if (wr == 0) BAR;
	ds_read_b128 v[140:143], v134
	ds_read_b128 v[192:195], v134 offset:1024
	ds_read_b128 v[212:215], v134 offset:2048
	ds_read_b128 v[216:219], v134 offset:3072
	s_waitcnt vmcnt(0)
	s_barrier
	s_waitcnt lgkmcnt(0)
	v_mfma_f32_16x16x32_bf16 v[98:101], v[26:29], v[140:143], v[204:207]
	v_mfma_f32_16x16x32_bf16 v[26:29], v[26:29], v[212:215], v[160:163]
	v_mfma_f32_16x16x32_bf16 v[114:117], v[30:33], v[216:219], v[26:29]
	v_mfma_f32_16x16x32_bf16 v[26:29], v[42:45], v[140:143], v[86:89]
	v_mfma_f32_16x16x32_bf16 v[102:105], v[46:49], v[192:195], v[26:29]
	v_mfma_f32_16x16x32_bf16 v[26:29], v[42:45], v[212:215], v[82:85]
	v_mfma_f32_16x16x32_bf16 v[118:121], v[30:33], v[192:195], v[98:101]
	v_mfma_f32_16x16x32_bf16 v[98:101], v[46:49], v[216:219], v[26:29]
	v_mfma_f32_16x16x32_bf16 v[26:29], v[180:183], v[140:143], v[164:167]
	v_mfma_f32_16x16x32_bf16 v[86:89], v[184:187], v[192:195], v[26:29]
	v_mfma_f32_16x16x32_bf16 v[26:29], v[180:183], v[212:215], v[168:171]
	v_mfma_f32_16x16x32_bf16 v[82:85], v[184:187], v[216:219], v[26:29]
	v_mfma_f32_16x16x32_bf16 v[26:29], v[196:199], v[140:143], v[70:73]
	v_mfma_f32_16x16x32_bf16 v[70:73], v[200:203], v[192:195], v[26:29]
	v_mfma_f32_16x16x32_bf16 v[26:29], v[196:199], v[212:215], v[66:69]
	v_mfma_f32_16x16x32_bf16 v[66:69], v[200:203], v[216:219], v[26:29]
	s_barrier
	ds_read_b128 v[158:161], v133 offset:49152
	ds_read_b128 v[162:165], v133 offset:50176
	ds_read_b128 v[166:169], v132 offset:49152
	ds_read_b128 v[132:135], v132 offset:50176
	ds_read_b128 v[180:183], v131 offset:49152
	ds_read_b128 v[184:187], v131 offset:50176
	ds_read_b128 v[196:199], v130 offset:49152
	ds_read_b128 v[200:203], v130 offset:50176
	s_barrier
	s_waitcnt lgkmcnt(0)
	v_mfma_f32_16x16x32_bf16 v[26:29], v[158:161], v[10:13], v[62:65]
	v_mfma_f32_16x16x32_bf16 v[62:65], v[162:165], v[14:17], v[26:29]
	v_mfma_f32_16x16x32_bf16 v[26:29], v[158:161], v[172:175], v[58:61]
	v_mfma_f32_16x16x32_bf16 v[58:61], v[162:165], v[176:179], v[26:29]
	v_mfma_f32_16x16x32_bf16 v[26:29], v[166:169], v[10:13], v[54:57]
	v_mfma_f32_16x16x32_bf16 v[46:49], v[132:135], v[14:17], v[26:29]
	v_mfma_f32_16x16x32_bf16 v[26:29], v[166:169], v[172:175], v[50:53]
	v_mfma_f32_16x16x32_bf16 v[42:45], v[132:135], v[176:179], v[26:29]
	v_mfma_f32_16x16x32_bf16 v[26:29], v[180:183], v[10:13], v[188:191]
	v_mfma_f32_16x16x32_bf16 v[10:13], v[196:199], v[10:13], v[38:41]
	v_mfma_f32_16x16x32_bf16 v[30:33], v[184:187], v[14:17], v[26:29]
	v_mfma_f32_16x16x32_bf16 v[26:29], v[180:183], v[172:175], v[208:211]
	v_mfma_f32_16x16x32_bf16 v[14:17], v[200:203], v[14:17], v[10:13]
	v_mfma_f32_16x16x32_bf16 v[10:13], v[196:199], v[172:175], v[34:37]
	v_mfma_f32_16x16x32_bf16 v[26:29], v[184:187], v[176:179], v[26:29]
	v_mfma_f32_16x16x32_bf16 v[10:13], v[200:203], v[176:179], v[10:13]
	v_mfma_f32_16x16x32_bf16 v[34:37], v[158:161], v[140:143], v[136:139]
	v_mfma_f32_16x16x32_bf16 v[54:57], v[162:165], v[192:195], v[34:37]
	v_mfma_f32_16x16x32_bf16 v[34:37], v[158:161], v[212:215], v[146:149]
	v_mfma_f32_16x16x32_bf16 v[18:21], v[166:169], v[212:215], v[18:21]
	v_mfma_f32_16x16x32_bf16 v[50:53], v[162:165], v[216:219], v[34:37]
	v_mfma_f32_16x16x32_bf16 v[22:25], v[166:169], v[140:143], v[22:25]
	v_mfma_f32_16x16x32_bf16 v[34:37], v[132:135], v[216:219], v[18:21]
	v_mfma_f32_16x16x32_bf16 v[18:21], v[180:183], v[140:143], v[150:153]
	v_mfma_f32_16x16x32_bf16 v[38:41], v[132:135], v[192:195], v[22:25]
	v_mfma_f32_16x16x32_bf16 v[22:25], v[184:187], v[192:195], v[18:21]
	v_mfma_f32_16x16x32_bf16 v[18:21], v[180:183], v[212:215], v[154:157]
	v_mfma_f32_16x16x32_bf16 v[6:9], v[196:199], v[140:143], v[6:9]
	v_mfma_f32_16x16x32_bf16 v[2:5], v[196:199], v[212:215], v[2:5]
	v_mfma_f32_16x16x32_bf16 v[18:21], v[184:187], v[216:219], v[18:21]
	v_mfma_f32_16x16x32_bf16 v[6:9], v[200:203], v[192:195], v[6:9]
	v_mfma_f32_16x16x32_bf16 v[2:5], v[200:203], v[216:219], v[2:5]
	s_movk_i32 s0, 0x100
	v_cmp_gt_u32_e32 vcc, s0, v0
	s_barrier
	s_and_saveexec_b64 s[0:1], vcc
	s_cbranch_execz .LBB0_61
	s_barrier

; __device__ __forceinline__ unsigned xb_add(unsigned* p, unsigned v) { return __hip_atomic_fetch_add(p, v, __ATOMIC_RELAXED, __HIP_MEMORY_SCOPE_AGENT); }
; __device__ __forceinline__ void xcd_barrier(XcdBarrier& b, int tid) {
;   asm volatile("s_waitcnt vmcnt(0)" ::: "memory");
;   __syncthreads();
;   if (tid == 0) {
;     unsigned* bar = b.bar;
;     __builtin_amdgcn_s_waitcnt(0);
;     const unsigned old = xb_add(&bar[XB_XSUB(b.x)], 1u);
.LBB0_80:
	v_mbcnt_lo_u32_b32 v0, -1, 0
	v_mbcnt_hi_u32_b32 v0, -1, v0
	s_waitcnt vmcnt(0)
	s_nop 0
	v_or_b32_e32 v0, s33, v0
	v_cmp_eq_u32_e32 vcc, 0, v0
	s_barrier
	s_and_saveexec_b64 s[0:1], vcc
	s_cbranch_execz .LBB0_118
	s_mov_b64 s[2:3], exec
	v_mbcnt_lo_u32_b32 v0, s2, 0
	v_mbcnt_hi_u32_b32 v0, s3, v0
	v_cmp_eq_u32_e32 vcc, 0, v0
	s_waitcnt expcnt(0) lgkmcnt(0)
	s_and_saveexec_b64 s[4:5], vcc
	s_cbranch_execz .LBB0_83
	s_bcnt1_i32_b64 s2, s[2:3]
	v_mov_b32_e32 v2, s2
	v_readlane_b32 s2, v253, 9
	v_readlane_b32 s3, v253, 10
	s_nop 4
	global_atomic_add v2, v1, v2, s[2:3] sc0

; #define WAIT_V(n) asm volatile("s_waitcnt vmcnt(" #n ")" ::: "memory")
; #define SB0 __builtin_amdgcn_sched_barrier(0)
; template <bool FWD>
; __device__ __forceinline__ void ret_sweep(const Params& p, int gs, int s, int g, int h, int sl, int nsegps, float lf, float lb) {
;     ...
; #pragma unroll
;     for (int mb = 0; mb < 2; ++mb)
; #pragma unroll
;       for (int nb = 0; nb < 8; ++nb) {
;         f32x4 a = T[mb][nb];
;         *(uint2*)(Ts + (nb * 16 + fr) * 264 + 32 * w + mb * 16 + fq * 4) = make_uint2(pack2(a[0], a[1]), pack2(a[2], a[3]));
;       }
;     ret_store_vt(vp, VTs, tid);
;     SB0;
;     u32x4* ypriv = (u32x4*)((char*)(Y + (long)t0 * YS + h * 512 + sl * 128) + (unsigned)(((tid >> 2) * YS + (tid & 3) * 32) * 2));
;     SB0;
;     WAIT_V(0);
;     __syncthreads();
;     f32x4 O[2][4];
; #pragma unroll
;     for (int mb = 0; mb < 2; ++mb)
; #pragma unroll
;       for (int nb = 0; nb < 4; ++nb) O[mb][nb] = f32x4{0.f, 0.f, 0.f, 0.f};
; #pragma unroll
;     for (int ks = 0; ks < 8; ++ks)
; #pragma unroll
;       for (int nb = 0; nb < 4; ++nb) {
;         bf16x8 b = *(const bf16x8*)(Ts + (64 * wv + nb * 16 + fr) * 264 + ks * 32 + fq * 8);
; #pragma unroll
;         for (int mb = 0; mb < 2; ++mb) O[mb][nb] = mfma16(qa[mb][ks], b, O[mb][nb]);
;       }
.LBB0_126:
	v_mov_b32_e32 v2, s33
	v_mbcnt_lo_u32_b32 v183, -1, 0
	v_mbcnt_hi_u32_b32 v183, -1, v183
	v_cvt_pk_bf16_f32 v148, v24, v25
	v_and_b32_e32 v181, 15, v183
	v_bfe_u32 v185, v183, 4, 2
	v_bitop3_b32 v2, v183, s57, v2 bitop3:0xc8
	v_add_u32_e32 v2, 16, v2
	v_lshlrev_b32_e32 v150, 3, v185
	v_mul_u32_u24_e32 v151, 0x210, v181
	v_cvt_pk_bf16_f32 v149, v26, v27
	v_add3_u32 v2, v2, v150, v151
	v_cvt_pk_bf16_f32 v164, v4, v5
	v_cvt_pk_bf16_f32 v165, v6, v7
	v_cvt_pk_bf16_f32 v150, v28, v29
	v_cvt_pk_bf16_f32 v151, v30, v31
	ds_write2_b64 v2, v[148:149], v[164:165] offset1:4
	v_cvt_pk_bf16_f32 v148, v8, v9
	v_cvt_pk_bf16_f32 v149, v10, v11
	v_add_u32_e32 v164, 0x2000, v2
	v_cvt_pk_bf16_f32 v152, v36, v37
	v_cvt_pk_bf16_f32 v153, v38, v39
	ds_write2_b64 v164, v[150:151], v[148:149] offset0:32 offset1:36
	v_cvt_pk_bf16_f32 v148, v12, v13
	v_cvt_pk_bf16_f32 v149, v14, v15
	v_add_u32_e32 v150, 0x4000, v2
	v_cvt_pk_bf16_f32 v154, v48, v49
	v_cvt_pk_bf16_f32 v155, v50, v51
	ds_write2_b64 v150, v[152:153], v[148:149] offset0:64 offset1:68
	v_cvt_pk_bf16_f32 v148, v16, v17
	v_cvt_pk_bf16_f32 v149, v18, v19
	v_add_u32_e32 v150, 0x6000, v2
	v_cvt_pk_bf16_f32 v156, v52, v53
	v_cvt_pk_bf16_f32 v157, v54, v55
	ds_write2_b64 v150, v[154:155], v[148:149] offset0:96 offset1:100
	v_cvt_pk_bf16_f32 v148, v20, v21
	v_cvt_pk_bf16_f32 v149, v22, v23
	v_add_u32_e32 v150, 0x8000, v2
	v_cvt_pk_bf16_f32 v158, v56, v57
	v_cvt_pk_bf16_f32 v159, v58, v59
	ds_write2_b64 v150, v[156:157], v[148:149] offset0:128 offset1:132
	v_cvt_pk_bf16_f32 v148, v32, v33
	v_cvt_pk_bf16_f32 v149, v34, v35
	v_add_u32_e32 v150, 0xa000, v2
	v_cvt_pk_bf16_f32 v160, v60, v61
	v_cvt_pk_bf16_f32 v161, v62, v63
	ds_write2_b64 v150, v[158:159], v[148:149] offset0:160 offset1:164
	v_cvt_pk_bf16_f32 v148, v40, v41
	v_cvt_pk_bf16_f32 v149, v42, v43
	v_add_u32_e32 v150, 0xc000, v2
	v_cvt_pk_bf16_f32 v162, v64, v65
	v_cvt_pk_bf16_f32 v163, v66, v67
	ds_write2_b64 v150, v[160:161], v[148:149] offset0:192 offset1:196
	v_cvt_pk_bf16_f32 v148, v44, v45
	v_cvt_pk_bf16_f32 v149, v46, v47
	v_add_u32_e32 v2, 0xe000, v2
	ds_write2_b64 v2, v[162:163], v[148:149] offset0:224 offset1:228
	v_lshlrev_b32_e32 v2, 4, v183
	v_or_b32_e32 v3, s33, v183
	v_and_b32_e32 v2, 0xf0, v2
	v_add_u32_e32 v2, s93, v2
	v_lshrrev_b32_e32 v148, 4, v3
	v_mad_u64_u32 v[148:149], s[52:53], v148, s36, v[2:3]
	s_waitcnt vmcnt(18)
	ds_write_b128 v148, v[124:127]
	v_add_u32_e32 v124, 0x200, v3
	v_lshrrev_b32_e32 v124, 4, v124
	v_mad_u64_u32 v[124:125], s[52:53], v124, s36, v[2:3]
	s_waitcnt vmcnt(18)
	ds_write_b128 v124, v[128:131]
	v_add_u32_e32 v124, 0x400, v3
	v_lshrrev_b32_e32 v124, 4, v124
	s_cmp_lg_u32 s12, 0xfff10000
	v_mad_u64_u32 v[124:125], s[52:53], v124, s36, v[2:3]
	s_cselect_b32 s16, s50, 0
	s_waitcnt vmcnt(17)
	ds_write_b128 v124, v[132:135]
	v_add_u32_e32 v124, 0x600, v3
	s_add_i32 s16, s16, s14
	v_ashrrev_i32_e32 v184, 2, v3
	v_lshrrev_b32_e32 v124, 4, v124
	s_ashr_i32 s17, s16, 31
	v_and_b32_e32 v186, 0xffffffe0, v184
	v_mad_u64_u32 v[124:125], s[52:53], v124, s36, v[2:3]
	s_lshl_b64 s[18:19], s[16:17], 19
	v_or_b32_e32 v0, v186, v181
	v_lshlrev_b32_e32 v182, 4, v185
	s_waitcnt vmcnt(9)
	ds_write_b128 v124, v[144:147]
	v_and_or_b32 v2, v3, 64, v181
	v_mul_u32_u24_e32 v2, 0x210, v2
	v_add3_u32 v2, 16, v182, v2
	s_waitcnt vmcnt(0)
	s_waitcnt lgkmcnt(0)
	s_barrier
	ds_read_b128 v[124:127], v2
	ds_read_b128 v[132:135], v2 offset:8448
	ds_read_b128 v[148:151], v2 offset:16896
	ds_read_b128 v[156:159], v2 offset:25344
	s_waitcnt lgkmcnt(3)
	v_mfma_f32_16x16x32_bf16 v[128:131], v[136:139], v[124:127], 0
	s_add_u32 s18, s28, s18
	s_addc_u32 s19, s29, s19
	v_mfma_f32_16x16x32_bf16 v[124:127], v[140:143], v[124:127], 0
	s_waitcnt lgkmcnt(2)
	v_mfma_f32_16x16x32_bf16 v[144:147], v[136:139], v[132:135], 0
	v_mfma_f32_16x16x32_bf16 v[132:135], v[140:143], v[132:135], 0
	s_waitcnt lgkmcnt(1)
	v_mfma_f32_16x16x32_bf16 v[152:155], v[136:139], v[148:151], 0
	v_mfma_f32_16x16x32_bf16 v[148:151], v[140:143], v[148:151], 0
	s_waitcnt lgkmcnt(0)
	v_mfma_f32_16x16x32_bf16 v[136:139], v[136:139], v[156:159], 0
	v_mfma_f32_16x16x32_bf16 v[140:143], v[140:143], v[156:159], 0
	ds_read_b128 v[156:159], v2 offset:64
	s_waitcnt lgkmcnt(0)
	v_mfma_f32_16x16x32_bf16 v[128:131], v[112:115], v[156:159], v[128:131]
	v_mfma_f32_16x16x32_bf16 v[124:127], v[120:123], v[156:159], v[124:127]
	ds_read_b128 v[156:159], v2 offset:8512
	s_waitcnt lgkmcnt(0)
	v_mfma_f32_16x16x32_bf16 v[144:147], v[112:115], v[156:159], v[144:147]
	v_mfma_f32_16x16x32_bf16 v[132:135], v[120:123], v[156:159], v[132:135]
	ds_read_b128 v[156:159], v2 offset:16960
	s_waitcnt lgkmcnt(0)
	v_mfma_f32_16x16x32_bf16 v[152:155], v[112:115], v[156:159], v[152:155]
	v_mfma_f32_16x16x32_bf16 v[148:151], v[120:123], v[156:159], v[148:151]
	ds_read_b128 v[156:159], v2 offset:25408
	s_waitcnt lgkmcnt(0)
	v_mfma_f32_16x16x32_bf16 v[112:115], v[112:115], v[156:159], v[136:139]
	s_nop 2
	ds_read_b128 v[136:139], v2 offset:128
	s_waitcnt lgkmcnt(0)
	v_mfma_f32_16x16x32_bf16 v[128:131], v[108:111], v[136:139], v[128:131]
	v_mfma_f32_16x16x32_bf16 v[124:127], v[116:119], v[136:139], v[124:127]
	ds_read_b128 v[136:139], v2 offset:8576
	v_mfma_f32_16x16x32_bf16 v[120:123], v[120:123], v[156:159], v[140:143]
	s_waitcnt lgkmcnt(0)
	v_mfma_f32_16x16x32_bf16 v[140:143], v[108:111], v[136:139], v[144:147]
	v_mfma_f32_16x16x32_bf16 v[132:135], v[116:119], v[136:139], v[132:135]
	ds_read_b128 v[136:139], v2 offset:17024
	s_waitcnt lgkmcnt(0)
	v_mfma_f32_16x16x32_bf16 v[144:147], v[108:111], v[136:139], v[152:155]
	v_mfma_f32_16x16x32_bf16 v[136:139], v[116:119], v[136:139], v[148:151]
	s_nop 2
	ds_read_b128 v[148:151], v2 offset:25472
	s_waitcnt lgkmcnt(0)
; template <bool FWD>
; __device__ __forceinline__ void ret_sweep(const Params& p, int gs, int s, int g, int h, int sl, int nsegps, float lf, float lb) {
;     ...
; #pragma unroll
;     for (int ks = 0; ks < 8; ++ks)
; #pragma unroll
;       for (int nb = 0; nb < 4; ++nb) {
;         bf16x8 b = *(const bf16x8*)(Ts + (64 * wv + nb * 16 + fr) * 264 + ks * 32 + fq * 8);
; #pragma unroll
;         for (int mb = 0; mb < 2; ++mb) O[mb][nb] = mfma16(qa[mb][ks], b, O[mb][nb]);
;       }
	v_mfma_f32_16x16x32_bf16 v[108:111], v[108:111], v[148:151], v[112:115]
	v_mfma_f32_16x16x32_bf16 v[112:115], v[116:119], v[148:151], v[120:123]
	ds_read_b128 v[116:119], v2 offset:192
	s_waitcnt lgkmcnt(0)
	v_mfma_f32_16x16x32_bf16 v[120:123], v[96:99], v[116:119], v[128:131]
	v_mfma_f32_16x16x32_bf16 v[116:119], v[104:107], v[116:119], v[124:127]
	s_nop 2
	ds_read_b128 v[124:127], v2 offset:8640
	s_waitcnt lgkmcnt(0)
	v_mfma_f32_16x16x32_bf16 v[128:131], v[96:99], v[124:127], v[140:143]
	v_mfma_f32_16x16x32_bf16 v[124:127], v[104:107], v[124:127], v[132:135]
	s_nop 2
	ds_read_b128 v[132:135], v2 offset:17088
	s_waitcnt lgkmcnt(0)
	v_mfma_f32_16x16x32_bf16 v[140:143], v[96:99], v[132:135], v[144:147]
	v_mfma_f32_16x16x32_bf16 v[132:135], v[104:107], v[132:135], v[136:139]
	s_nop 2
	ds_read_b128 v[136:139], v2 offset:25536
	s_waitcnt lgkmcnt(0)
	v_mfma_f32_16x16x32_bf16 v[96:99], v[96:99], v[136:139], v[108:111]
	s_nop 2
	ds_read_b128 v[108:111], v2 offset:256
	v_mfma_f32_16x16x32_bf16 v[104:107], v[104:107], v[136:139], v[112:115]
	s_waitcnt lgkmcnt(0)
	v_mfma_f32_16x16x32_bf16 v[112:115], v[92:95], v[108:111], v[120:123]
	v_mfma_f32_16x16x32_bf16 v[108:111], v[100:103], v[108:111], v[116:119]
	s_nop 2
	ds_read_b128 v[116:119], v2 offset:8704
	s_waitcnt lgkmcnt(0)
	v_mfma_f32_16x16x32_bf16 v[120:123], v[92:95], v[116:119], v[128:131]
	v_mfma_f32_16x16x32_bf16 v[116:119], v[100:103], v[116:119], v[124:127]
	s_nop 2
	ds_read_b128 v[124:127], v2 offset:17152
	s_waitcnt lgkmcnt(0)
	v_mfma_f32_16x16x32_bf16 v[128:131], v[92:95], v[124:127], v[140:143]
	v_mfma_f32_16x16x32_bf16 v[124:127], v[100:103], v[124:127], v[132:135]
	s_nop 2
	ds_read_b128 v[132:135], v2 offset:25600
	s_waitcnt lgkmcnt(0)
	v_mfma_f32_16x16x32_bf16 v[92:95], v[92:95], v[132:135], v[96:99]
	v_mfma_f32_16x16x32_bf16 v[96:99], v[100:103], v[132:135], v[104:107]
	ds_read_b128 v[100:103], v2 offset:320
	s_waitcnt lgkmcnt(0)
	v_mfma_f32_16x16x32_bf16 v[104:107], v[80:83], v[100:103], v[112:115]
	v_mfma_f32_16x16x32_bf16 v[100:103], v[88:91], v[100:103], v[108:111]
	s_nop 2
	ds_read_b128 v[108:111], v2 offset:8768
	s_waitcnt lgkmcnt(0)
	v_mfma_f32_16x16x32_bf16 v[112:115], v[80:83], v[108:111], v[120:123]
	v_mfma_f32_16x16x32_bf16 v[108:111], v[88:91], v[108:111], v[116:119]
	s_nop 2
	ds_read_b128 v[116:119], v2 offset:17216
	s_waitcnt lgkmcnt(0)
	v_mfma_f32_16x16x32_bf16 v[120:123], v[80:83], v[116:119], v[128:131]
	v_mfma_f32_16x16x32_bf16 v[116:119], v[88:91], v[116:119], v[124:127]
	s_nop 2
	ds_read_b128 v[124:127], v2 offset:25664
	s_waitcnt lgkmcnt(0)
	v_mfma_f32_16x16x32_bf16 v[80:83], v[80:83], v[124:127], v[92:95]
	s_nop 2
	ds_read_b128 v[92:95], v2 offset:384
	v_mfma_f32_16x16x32_bf16 v[88:91], v[88:91], v[124:127], v[96:99]
	s_waitcnt lgkmcnt(0)
	v_mfma_f32_16x16x32_bf16 v[96:99], v[76:79], v[92:95], v[104:107]
	v_mfma_f32_16x16x32_bf16 v[92:95], v[84:87], v[92:95], v[100:103]
	s_nop 2
	ds_read_b128 v[100:103], v2 offset:8832
	s_waitcnt lgkmcnt(0)
	v_mfma_f32_16x16x32_bf16 v[104:107], v[76:79], v[100:103], v[112:115]
	v_mfma_f32_16x16x32_bf16 v[100:103], v[84:87], v[100:103], v[108:111]
	s_nop 2
	ds_read_b128 v[108:111], v2 offset:17280
	s_waitcnt lgkmcnt(0)
	v_mfma_f32_16x16x32_bf16 v[112:115], v[76:79], v[108:111], v[120:123]
	v_mfma_f32_16x16x32_bf16 v[108:111], v[84:87], v[108:111], v[116:119]
	s_nop 2
	ds_read_b128 v[116:119], v2 offset:25728
	s_waitcnt lgkmcnt(0)
	v_mfma_f32_16x16x32_bf16 v[120:123], v[76:79], v[116:119], v[80:83]
	ds_read_b128 v[76:79], v2 offset:448
	s_nop 1
	ds_read_b128 v[80:83], v2 offset:8896
	v_mfma_f32_16x16x32_bf16 v[116:119], v[84:87], v[116:119], v[88:91]
	ds_read_b128 v[84:87], v2 offset:17344
	s_waitcnt lgkmcnt(2)
	v_mfma_f32_16x16x32_bf16 v[88:91], v[68:71], v[76:79], v[96:99]
	v_mfma_f32_16x16x32_bf16 v[76:79], v[72:75], v[76:79], v[92:95]
	s_waitcnt lgkmcnt(1)
	v_mfma_f32_16x16x32_bf16 v[92:95], v[68:71], v[80:83], v[104:107]
	v_mfma_f32_16x16x32_bf16 v[80:83], v[72:75], v[80:83], v[100:103]
	s_nop 2
	ds_read_b128 v[100:103], v2 offset:25792
	s_waitcnt lgkmcnt(1)
	v_mfma_f32_16x16x32_bf16 v[96:99], v[68:71], v[84:87], v[112:115]
	v_lshl_or_b32 v2, v0, 12, v182
	v_mfma_f32_16x16x32_bf16 v[84:87], v[72:75], v[84:87], v[108:111]
	s_waitcnt lgkmcnt(0)
; __device__ __forceinline__ float ex2(float x) { return __builtin_amdgcn_exp2f(x); }
; #define SB0 __builtin_amdgcn_sched_barrier(0)
; template <bool FWD>
; __device__ __forceinline__ void ret_sweep(const Params& p, int gs, int s, int g, int h, int sl, int nsegps, float lf, float lb) {
;     ...
;     bf16x8 kt[2][4];
;     ret_load_kt(kt, KT + (long)(h * 128 + chunk) * 256 * 128, w, fr, fq);
;     SB0;
;     int ibase = 32 * wi + fq * 4;
;     asm volatile("" : "+v"(ibase));
; #pragma unroll
;     for (int mb = 0; mb < 2; ++mb)
; #pragma unroll
;       for (int jj = 0; jj < 4; ++jj) {
;         int i = ibase + mb * 16 + jj;
;         float sc = FWD ? ex2(lf * (float)(i + 128)) : ex2(lb * (float)(255 - i));
; #pragma unroll
;         for (int nb = 0; nb < 4; ++nb) O[mb][nb][jj] *= sc;
;       }
;     if constexpr (FWD) {
; #pragma unroll
;       for (int ks = 0; ks < 4; ++ks) {
; #pragma unroll
;         for (int nb = 0; nb < 4; ++nb) {
;           bf16x8 b = *(const bf16x8*)(VTs + (64 * wv + nb * 16 + fr) * 136 + ks * 32 + fq * 8);
; #pragma unroll
;           for (int mb = 0; mb < 2; ++mb) O[mb][nb] = mfma16(pa[mb][ks], b, O[mb][nb]);
;         }
;       }
;     }
;     SB0;
;     if constexpr (!FWD) {
; #pragma unroll
;       for (int q = 0; q < 4; ++q) {
;         u32x4 pk;
; #pragma unroll
;         for (int e2 = 0; e2 < 4; ++e2) {
;           int e = q * 8 + e2 * 2;
;           pk[e2] = pack2(O[e >> 4][e & 3][(e >> 2) & 3], O[(e + 1) >> 4][(e + 1) & 3][((e + 1) >> 2) & 3]);
;         }
;         ypriv[q] = pk;
;       }
;     ...
;     SB0;
;     ret_load_vt(vp, VT + ((long)(h * 128 + nchunk) * 512 + sl * 128) * 128, tid);
; #pragma unroll
;     for (int mb = 0; mb < 2; ++mb)
; #pragma unroll
;       for (int ks = 0; ks < 8; ++ks) qa[mb][ks] = *(const bf16x8*)(qnext + (mb * 16 * 2048 + ks * 32) * 2 + qofs2);
	v_mfma_f32_16x16x32_bf16 v[104:107], v[68:71], v[100:103], v[120:123]
	v_mfma_f32_16x16x32_bf16 v[68:71], v[72:75], v[100:103], v[116:119]
	v_lshlrev_b32_e32 v0, 7, v3
	v_and_b32_e32 v0, 0xffffe000, v0
	v_lshlrev_b32_e32 v72, 8, v181
	s_add_u32 s52, s48, s12
	v_or3_b32 v0, v0, v72, v182
	s_addc_u32 s53, s49, s13
	v_lshl_add_u64 v[72:73], s[52:53], 0, v[0:1]
	s_mov_b32 s17, 0x148f0000
	v_add_co_u32_e32 v74, vcc, s17, v72
	s_mov_b32 s17, 0x148f1000
	s_nop 0
	v_addc_co_u32_e32 v75, vcc, 0, v73, vcc
	v_add_co_u32_e32 v72, vcc, s17, v72
	s_nop 1
	v_addc_co_u32_e32 v73, vcc, 0, v73, vcc
	global_load_dwordx4 v[164:167], v[74:75], off offset:64
	global_load_dwordx4 v[156:159], v[74:75], off offset:128
	global_load_dwordx4 v[172:175], v[72:73], off offset:-4096
	global_load_dwordx4 v[148:151], v[74:75], off offset:192
	global_load_dwordx4 v[176:179], v[72:73], off
	global_load_dwordx4 v[168:171], v[72:73], off offset:64
	global_load_dwordx4 v[160:163], v[72:73], off offset:128
	global_load_dwordx4 v[152:155], v[72:73], off offset:192
	v_lshl_or_b32 v108, v185, 2, v186
	v_mov_b32_e32 v72, v88
	v_sub_u32_e32 v0, 0xff, v108
	v_cvt_f32_i32_e32 v0, v0
	v_mov_b32_e32 v73, v92
	v_mov_b32_e32 v74, v96
	v_mov_b32_e32 v75, v104
	v_mul_f32_e32 v0, v180, v0
	v_exp_f32_e32 v0, v0
	v_mov_b32_e32 v92, v89
	v_mov_b32_e32 v104, v97
	v_mov_b32_e32 v96, v90
	v_pk_mul_f32 v[72:73], v[72:73], v[0:1] op_sel_hi:[1,0]
	v_pk_mul_f32 v[74:75], v[74:75], v[0:1] op_sel_hi:[1,0]
	v_sub_u32_e32 v0, 0xfe, v108
	v_cvt_f32_i32_e32 v0, v0
	v_mov_b32_e32 v97, v94
	v_mov_b32_e32 v100, v98
	v_mov_b32_e32 v101, v106
	v_mul_f32_e32 v0, v180, v0
	v_exp_f32_e32 v0, v0
	v_mov_b32_e32 v94, v91
	v_mov_b32_e32 v106, v99
	v_mov_b32_e32 v98, v76
	v_pk_mul_f32 v[88:89], v[92:93], v[0:1] op_sel_hi:[1,0]
	v_pk_mul_f32 v[92:93], v[104:105], v[0:1] op_sel_hi:[1,0]
	v_sub_u32_e32 v0, 0xfd, v108
	v_cvt_f32_i32_e32 v0, v0
	v_mov_b32_e32 v99, v80
	v_mov_b32_e32 v102, v84
	v_mov_b32_e32 v103, v68
	v_mul_f32_e32 v0, v180, v0
	v_exp_f32_e32 v0, v0
	v_mov_b32_e32 v80, v77
	v_mov_b32_e32 v68, v85
	v_pk_mul_f32 v[96:97], v[96:97], v[0:1] op_sel_hi:[1,0]
	v_pk_mul_f32 v[100:101], v[100:101], v[0:1] op_sel_hi:[1,0]
	v_sub_u32_e32 v0, 0xfc, v108
	v_cvt_f32_i32_e32 v0, v0
	v_mul_f32_e32 v0, v180, v0
	v_exp_f32_e32 v0, v0
	s_nop 0
	v_pk_mul_f32 v[90:91], v[94:95], v[0:1] op_sel_hi:[1,0]
	v_pk_mul_f32 v[94:95], v[106:107], v[0:1] op_sel_hi:[1,0]
	v_sub_u32_e32 v0, 0xef, v108
	v_cvt_f32_i32_e32 v0, v0
	v_mul_f32_e32 v0, v180, v0
	v_exp_f32_e32 v0, v0
	s_nop 0
	v_pk_mul_f32 v[98:99], v[98:99], v[0:1] op_sel_hi:[1,0]
	v_pk_mul_f32 v[102:103], v[102:103], v[0:1] op_sel_hi:[1,0]
	v_sub_u32_e32 v0, 0xee, v108
	v_cvt_f32_i32_e32 v0, v0
	v_mul_f32_e32 v0, v180, v0
	v_exp_f32_e32 v0, v0
	s_nop 0
	v_pk_mul_f32 v[76:77], v[80:81], v[0:1] op_sel_hi:[1,0]
	v_pk_mul_f32 v[80:81], v[68:69], v[0:1] op_sel_hi:[1,0]
	v_sub_u32_e32 v0, 0xed, v108
	v_cvt_f32_i32_e32 v0, v0
	v_mov_b32_e32 v68, v78
	v_mov_b32_e32 v69, v82
	v_mov_b32_e32 v82, v79
	v_mul_f32_e32 v0, v180, v0
	v_exp_f32_e32 v0, v0
	s_nop 0
	v_pk_mul_f32 v[84:85], v[68:69], v[0:1] op_sel_hi:[1,0]
	v_mov_b32_e32 v68, v86
	v_mov_b32_e32 v69, v70
	v_pk_mul_f32 v[104:105], v[68:69], v[0:1] op_sel_hi:[1,0]
	v_sub_u32_e32 v0, 0xec, v108
	v_cvt_f32_i32_e32 v0, v0
	v_mov_b32_e32 v70, v87
	v_and_b32_e32 v68, 3, v183
	v_mul_f32_e32 v0, v180, v0
	v_exp_f32_e32 v0, v0
	s_nop 0
	v_pk_mul_f32 v[78:79], v[82:83], v[0:1] op_sel_hi:[1,0]
	v_pk_mul_f32 v[82:83], v[70:71], v[0:1] op_sel_hi:[1,0]
	v_mul_lo_u32 v0, v184, s58
	v_lshl_or_b32 v0, v68, 6, v0
	v_cvt_pk_bf16_f32 v68, v72, v73
	v_cvt_pk_bf16_f32 v69, v74, v75
	v_cvt_pk_bf16_f32 v70, v88, v89
	v_cvt_pk_bf16_f32 v71, v92, v93
	global_store_dwordx4 v0, v[68:71], s[4:5] offset:-32
	s_nop 1
	v_cvt_pk_bf16_f32 v68, v96, v97
	v_cvt_pk_bf16_f32 v69, v100, v101
	v_cvt_pk_bf16_f32 v70, v90, v91
	v_cvt_pk_bf16_f32 v71, v94, v95
	global_store_dwordx4 v0, v[68:71], s[4:5] offset:-16
	s_nop 1
	v_cvt_pk_bf16_f32 v68, v98, v99
	v_cvt_pk_bf16_f32 v69, v102, v103
	v_cvt_pk_bf16_f32 v70, v76, v77
	v_cvt_pk_bf16_f32 v71, v80, v81
	global_store_dwordx4 v0, v[68:71], s[4:5]
	s_nop 1
	v_cvt_pk_bf16_f32 v68, v84, v85
	v_cvt_pk_bf16_f32 v69, v104, v105
	v_cvt_pk_bf16_f32 v70, v78, v79
	v_cvt_pk_bf16_f32 v71, v82, v83
	global_store_dwordx4 v0, v[68:71], s[4:5] offset:16
	s_add_i32 s16, s16, s27
	s_ashr_i32 s17, s16, 31
	s_lshl_b64 s[16:17], s[16:17], 17
	s_add_u32 s16, s30, s16
	s_addc_u32 s17, s31, s17
	v_lshlrev_b32_e32 v0, 4, v3
	v_lshl_add_u64 v[68:69], s[16:17], 0, v[0:1]
	v_add_co_u32_e32 v70, vcc, s51, v68
	v_mov_b32_e32 v3, v1
	s_nop 0
	v_addc_co_u32_e32 v71, vcc, 0, v69, vcc
	global_load_dwordx4 v[128:131], v[70:71], off
	v_add_co_u32_e32 v70, vcc, s55, v68
	v_lshl_add_u64 v[72:73], s[18:19], 0, v[2:3]
	s_nop 0
	v_addc_co_u32_e32 v71, vcc, 0, v69, vcc
	v_add_co_u32_e32 v68, vcc, s56, v68
	global_load_dwordx4 v[124:127], v0, s[16:17]
	s_nop 0
	v_addc_co_u32_e32 v69, vcc, 0, v69, vcc
	global_load_dwordx4 v[132:135], v[70:71], off
	global_load_dwordx4 v[144:147], v[68:69], off
	global_load_dwordx4 v[136:139], v2, s[18:19]
	global_load_dwordx4 v[112:115], v2, s[18:19] offset:64
	global_load_dwordx4 v[108:111], v2, s[18:19] offset:128
	global_load_dwordx4 v[96:99], v2, s[18:19] offset:192
	global_load_dwordx4 v[92:95], v2, s[18:19] offset:256
	global_load_dwordx4 v[80:83], v2, s[18:19] offset:320
	global_load_dwordx4 v[76:79], v2, s[18:19] offset:384
	global_load_dwordx4 v[68:71], v2, s[18:19] offset:448
	v_add_co_u32_e32 v2, vcc, s54, v72
	s_nop 1
	v_addc_co_u32_e32 v3, vcc, 0, v73, vcc
	global_load_dwordx4 v[140:143], v[2:3], off
	global_load_dwordx4 v[120:123], v[2:3], off offset:64
	global_load_dwordx4 v[116:119], v[2:3], off offset:128
	global_load_dwordx4 v[104:107], v[2:3], off offset:192
	global_load_dwordx4 v[100:103], v[2:3], off offset:256
	global_load_dwordx4 v[88:91], v[2:3], off offset:320
	global_load_dwordx4 v[84:87], v[2:3], off offset:384
	global_load_dwordx4 v[72:75], v[2:3], off offset:448
	v_mul_u32_u24_e32 v0, 0x110, v181
	v_add3_u32 v0, s93, v182, v0
	ds_read_b128 v[182:185], v0
	v_pk_mul_f32 v[26:27], s[2:3], v[26:27]
	v_pk_mul_f32 v[24:25], s[0:1], v[24:25]
	v_pk_mul_f32 v[6:7], s[2:3], v[6:7]
	v_pk_mul_f32 v[4:5], s[0:1], v[4:5]
	s_waitcnt vmcnt(29) lgkmcnt(0)
; __device__ __forceinline__ void ret_state_mma(f32x4 (&T)[2][8], const bf16x8 (&kt)[2][4], const u16* VTs, float cd,
;                                               int fr, int fq) {
; #pragma unroll
;   for (int mb = 0; mb < 2; ++mb)
; #pragma unroll
;     for (int nb = 0; nb < 8; ++nb) T[mb][nb] *= cd;
; #pragma unroll
;   for (int ks = 0; ks < 4; ++ks)
; #pragma unroll
;     for (int nb = 0; nb < 8; ++nb) {
;       bf16x8 b = *(const bf16x8*)(VTs + (nb * 16 + fr) * 136 + ks * 32 + fq * 8);
; #pragma unroll
;       for (int mb = 0; mb < 2; ++mb) T[mb][nb] = mfma16(kt[mb][ks], b, T[mb][nb]);
;     }
; }
	v_mfma_f32_16x16x32_bf16 v[24:27], v[172:175], v[182:185], v[24:27]
	v_mul_f32_e64 v30, s2, v30
	v_mul_f32_e64 v31, s3, v31
	v_pk_mul_f32 v[28:29], s[0:1], v[28:29]
	v_pk_mul_f32 v[10:11], s[2:3], v[10:11]
	s_waitcnt vmcnt(27)
	v_mfma_f32_16x16x32_bf16 v[182:185], v[176:179], v[182:185], v[4:7]
	v_mul_f32_e64 v8, s0, v8
	v_mul_f32_e64 v9, s1, v9
	v_pk_mul_f32 v[38:39], s[2:3], v[38:39]
	v_pk_mul_f32 v[36:37], s[0:1], v[36:37]
	ds_read_b128 v[2:5], v0 offset:4352
	s_waitcnt lgkmcnt(0)
	v_mfma_f32_16x16x32_bf16 v[28:31], v[172:175], v[2:5], v[28:31]
	v_mul_f32_e64 v14, s2, v14
	v_mul_f32_e64 v15, s3, v15
	v_pk_mul_f32 v[12:13], s[0:1], v[12:13]
	v_pk_mul_f32 v[50:51], s[2:3], v[50:51]
	v_mfma_f32_16x16x32_bf16 v[186:189], v[176:179], v[2:5], v[8:11]
	ds_read_b128 v[2:5], v0 offset:8704
	v_pk_mul_f32 v[48:49], s[0:1], v[48:49]
	v_pk_mul_f32 v[18:19], s[2:3], v[18:19]
	ds_read_b128 v[6:9], v0 offset:30464
	s_waitcnt lgkmcnt(1)
	v_mfma_f32_16x16x32_bf16 v[36:39], v[172:175], v[2:5], v[36:39]
	v_mul_f32_e64 v16, s0, v16
	v_mul_f32_e64 v17, s1, v17
	v_pk_mul_f32 v[54:55], s[2:3], v[54:55]
	v_pk_mul_f32 v[52:53], s[0:1], v[52:53]
	v_mfma_f32_16x16x32_bf16 v[190:193], v[176:179], v[2:5], v[12:15]
	ds_read_b128 v[2:5], v0 offset:13056
	v_pk_mul_f32 v[22:23], s[2:3], v[22:23]
	v_pk_mul_f32 v[20:21], s[0:1], v[20:21]
	s_waitcnt lgkmcnt(0)
	v_mfma_f32_16x16x32_bf16 v[48:51], v[172:175], v[2:5], v[48:51]
	v_mul_f32_e64 v58, s2, v58
	v_mul_f32_e64 v59, s3, v59
	v_pk_mul_f32 v[56:57], s[0:1], v[56:57]
	v_pk_mul_f32 v[34:35], s[2:3], v[34:35]
	v_mfma_f32_16x16x32_bf16 v[194:197], v[176:179], v[2:5], v[16:19]
	ds_read_b128 v[2:5], v0 offset:17408
	v_pk_mul_f32 v[32:33], s[0:1], v[32:33]
	v_pk_mul_f32 v[62:63], s[2:3], v[62:63]
	s_waitcnt lgkmcnt(0)
	v_mfma_f32_16x16x32_bf16 v[52:55], v[172:175], v[2:5], v[52:55]
	v_mul_f32_e64 v60, s0, v60
	v_mul_f32_e64 v61, s1, v61
	v_pk_mul_f32 v[66:67], s[2:3], v[66:67]
	v_pk_mul_f32 v[64:65], s[0:1], v[64:65]
	v_mfma_f32_16x16x32_bf16 v[18:21], v[176:179], v[2:5], v[20:23]
	ds_read_b128 v[2:5], v0 offset:21760
	v_pk_mul_f32 v[42:43], s[2:3], v[42:43]
	v_pk_mul_f32 v[40:41], s[0:1], v[40:41]
	s_waitcnt lgkmcnt(0)
	v_mfma_f32_16x16x32_bf16 v[56:59], v[172:175], v[2:5], v[56:59]
	v_mul_f32_e64 v46, s2, v46
	v_mul_f32_e64 v47, s3, v47
	v_pk_mul_f32 v[44:45], s[0:1], v[44:45]
	s_add_i32 s50, s50, -1
	v_mfma_f32_16x16x32_bf16 v[32:35], v[176:179], v[2:5], v[32:35]
	ds_read_b128 v[2:5], v0 offset:26112
	s_add_u32 s12, s12, 0xffff0000
	s_addc_u32 s13, s13, -1
	s_waitcnt lgkmcnt(0)
	v_mfma_f32_16x16x32_bf16 v[10:13], v[172:175], v[2:5], v[60:63]
	s_add_u32 s4, s4, 0xffef8000
	s_nop 1
	ds_read_b128 v[60:63], v0 offset:8768
	s_addc_u32 s5, s5, -1
	v_mfma_f32_16x16x32_bf16 v[14:17], v[176:179], v[2:5], v[40:43]
	s_cmp_lg_u32 s50, -2
	v_mfma_f32_16x16x32_bf16 v[2:5], v[172:175], v[6:9], v[64:67]
	ds_read_b128 v[172:175], v0 offset:17472
	ds_read_b128 v[40:43], v0 offset:64
	v_mfma_f32_16x16x32_bf16 v[6:9], v[176:179], v[6:9], v[44:47]
	ds_read_b128 v[64:67], v0 offset:13120
	s_nop 1
	ds_read_b128 v[44:47], v0 offset:4416
	s_waitcnt lgkmcnt(3)
	v_mfma_f32_16x16x32_bf16 v[52:55], v[164:167], v[172:175], v[52:55]
	s_waitcnt vmcnt(26)
	v_mfma_f32_16x16x32_bf16 v[18:21], v[168:171], v[172:175], v[18:21]
	ds_read_b128 v[172:175], v0 offset:21824
	s_waitcnt lgkmcnt(3)
	v_mfma_f32_16x16x32_bf16 v[22:25], v[164:167], v[40:43], v[24:27]
	s_waitcnt lgkmcnt(1)
	v_mfma_f32_16x16x32_bf16 v[26:29], v[164:167], v[44:47], v[28:31]
	s_waitcnt lgkmcnt(0)
	v_mfma_f32_16x16x32_bf16 v[56:59], v[164:167], v[172:175], v[56:59]
	v_mfma_f32_16x16x32_bf16 v[30:33], v[168:171], v[172:175], v[32:35]
	ds_read_b128 v[172:175], v0 offset:26176
	s_waitcnt lgkmcnt(0)
	v_mfma_f32_16x16x32_bf16 v[10:13], v[164:167], v[172:175], v[10:13]
	v_mfma_f32_16x16x32_bf16 v[14:17], v[168:171], v[172:175], v[14:17]
	ds_read_b128 v[172:175], v0 offset:30528
	v_mfma_f32_16x16x32_bf16 v[36:39], v[164:167], v[60:63], v[36:39]
	v_mfma_f32_16x16x32_bf16 v[48:51], v[164:167], v[64:67], v[48:51]
	s_waitcnt lgkmcnt(0)
	v_mfma_f32_16x16x32_bf16 v[2:5], v[164:167], v[172:175], v[2:5]
	ds_read_b128 v[164:167], v0 offset:128
	v_mfma_f32_16x16x32_bf16 v[40:43], v[168:171], v[40:43], v[182:185]
	s_waitcnt lgkmcnt(0)
	v_mfma_f32_16x16x32_bf16 v[22:25], v[156:159], v[164:167], v[22:25]
	s_waitcnt vmcnt(25)
	v_mfma_f32_16x16x32_bf16 v[40:43], v[160:163], v[164:167], v[40:43]
	ds_read_b128 v[164:167], v0 offset:4480
	v_mfma_f32_16x16x32_bf16 v[44:47], v[168:171], v[44:47], v[186:189]
	v_mfma_f32_16x16x32_bf16 v[60:63], v[168:171], v[60:63], v[190:193]
	v_mfma_f32_16x16x32_bf16 v[64:67], v[168:171], v[64:67], v[194:197]
	v_mfma_f32_16x16x32_bf16 v[6:9], v[168:171], v[172:175], v[6:9]
	s_waitcnt lgkmcnt(0)
	v_mfma_f32_16x16x32_bf16 v[168:171], v[156:159], v[164:167], v[26:29]
	s_nop 2
	ds_read_b128 v[26:29], v0 offset:8832
	s_waitcnt lgkmcnt(0)
	v_mfma_f32_16x16x32_bf16 v[34:37], v[156:159], v[26:29], v[36:39]
	v_mfma_f32_16x16x32_bf16 v[60:63], v[160:163], v[26:29], v[60:63]
	ds_read_b128 v[26:29], v0 offset:13184
	s_waitcnt lgkmcnt(0)
	v_mfma_f32_16x16x32_bf16 v[48:51], v[156:159], v[26:29], v[48:51]
	v_mfma_f32_16x16x32_bf16 v[64:67], v[160:163], v[26:29], v[64:67]
	ds_read_b128 v[26:29], v0 offset:17536
	v_mfma_f32_16x16x32_bf16 v[44:47], v[160:163], v[164:167], v[44:47]
	s_waitcnt lgkmcnt(0)
	v_mfma_f32_16x16x32_bf16 v[164:167], v[160:163], v[26:29], v[18:21]
	s_nop 2
	ds_read_b128 v[18:21], v0 offset:21888
	s_waitcnt lgkmcnt(0)
	v_mfma_f32_16x16x32_bf16 v[56:59], v[156:159], v[18:21], v[56:59]
	v_mfma_f32_16x16x32_bf16 v[172:175], v[160:163], v[18:21], v[30:33]
	ds_read_b128 v[18:21], v0 offset:26240
	s_waitcnt lgkmcnt(0)
	v_mfma_f32_16x16x32_bf16 v[176:179], v[156:159], v[18:21], v[10:13]
	s_nop 2
	ds_read_b128 v[10:13], v0 offset:30592
	v_mfma_f32_16x16x32_bf16 v[52:55], v[156:159], v[26:29], v[52:55]
	v_mfma_f32_16x16x32_bf16 v[182:185], v[160:163], v[18:21], v[14:17]
	s_waitcnt lgkmcnt(0)
	v_mfma_f32_16x16x32_bf16 v[156:159], v[156:159], v[10:13], v[2:5]
	s_nop 0
	ds_read_b128 v[16:19], v0 offset:13248
	v_mfma_f32_16x16x32_bf16 v[160:163], v[160:163], v[10:13], v[6:9]
	ds_read_b128 v[2:5], v0 offset:192
	ds_read_b128 v[12:15], v0 offset:8896
	s_nop 0
	ds_read_b128 v[8:11], v0 offset:4544
	s_waitcnt lgkmcnt(2)
	v_mfma_f32_16x16x32_bf16 v[24:27], v[148:151], v[2:5], v[22:25]
	s_nop 2
	ds_read_b128 v[20:23], v0 offset:17600
	s_waitcnt vmcnt(24)
	v_mfma_f32_16x16x32_bf16 v[4:7], v[152:155], v[2:5], v[40:43]
	s_waitcnt lgkmcnt(1)
	v_mfma_f32_16x16x32_bf16 v[28:31], v[148:151], v[8:11], v[168:171]
	s_nop 0
	ds_read_b128 v[40:43], v0 offset:26304
	v_mfma_f32_16x16x32_bf16 v[8:11], v[152:155], v[8:11], v[44:47]
	v_mfma_f32_16x16x32_bf16 v[36:39], v[148:151], v[12:15], v[34:37]
	s_nop 1
	ds_read_b128 v[44:47], v0 offset:30656
	ds_read_b128 v[32:35], v0 offset:21952
	v_mfma_f32_16x16x32_bf16 v[12:15], v[152:155], v[12:15], v[60:63]
	s_waitcnt lgkmcnt(0)
	s_barrier
; __device__ __forceinline__ float ex2(float x) { return __builtin_amdgcn_exp2f(x); }
; __device__ __forceinline__ float uni(float x) { return __int_as_float(__builtin_amdgcn_readfirstlane(__float_as_int(x))); }
; template <bool FWD>
; __device__ __forceinline__ void ret_sweep(const Params& p, int gs, int s, int g, int h, int sl, int nsegps, float lf, float lb) {
;     ...
;   const float lg = FWD ? lf : lb;
;   const float cd = uni(ex2(lg * 128.f));
;   f32x4 T[2][8];
; #pragma unroll
;   for (int mb = 0; mb < 2; ++mb)
; #pragma unroll
;     for (int nb = 0; nb < 8; ++nb) T[mb][nb] = f32x4{0.f, 0.f, 0.f, 0.f};
;   {
;     constexpr int dir = FWD ? 0 : 1;
;     float cdS = uni(ex2(lg * (128.f * SEG)));
;     int gp = dir ? nsegps - 1 : 0;
;     int cnt = dir ? nsegps - 1 - g : g;
; #pragma unroll 1
;     for (int q = 0; q < cnt; ++q) {
;       int tq = get_tid(p.wid);
;       const f32x4* src = (const f32x4*)((const char*)(ST + (long)(((((s * nsegps + gp) * 8 + h) * 2 + dir) * 4) + sl) * 32768) + (unsigned)(tq * 256));
; #pragma unroll
;       for (int mb = 0; mb < 2; ++mb)
; #pragma unroll
;         for (int nb = 0; nb < 8; ++nb) T[mb][nb] = T[mb][nb] * cdS + src[mb * 8 + nb];
	v_mfma_f32_16x16x32_bf16 v[48:51], v[148:151], v[16:19], v[48:51]
	v_mfma_f32_16x16x32_bf16 v[16:19], v[152:155], v[16:19], v[64:67]
	v_mfma_f32_16x16x32_bf16 v[52:55], v[148:151], v[20:23], v[52:55]
	v_mfma_f32_16x16x32_bf16 v[20:23], v[152:155], v[20:23], v[164:167]
	v_mfma_f32_16x16x32_bf16 v[56:59], v[148:151], v[32:35], v[56:59]
	v_mfma_f32_16x16x32_bf16 v[32:35], v[152:155], v[32:35], v[172:175]
	v_mfma_f32_16x16x32_bf16 v[60:63], v[148:151], v[40:43], v[176:179]
	v_mfma_f32_16x16x32_bf16 v[40:43], v[152:155], v[40:43], v[182:185]
	v_mfma_f32_16x16x32_bf16 v[64:67], v[148:151], v[44:47], v[156:159]
	v_mfma_f32_16x16x32_bf16 v[44:47], v[152:155], v[44:47], v[160:163]
	s_cbranch_scc1 .LBB0_126
	v_mov_b32_e32 v0, 0x3fb8aa3b
	v_mul_f32_e32 v251, s44, v0
	v_mul_f32_e32 v0, 0x43000000, v251
	v_exp_f32_e32 v0, v0
	s_movk_i32 s49, 0xffc0
	s_movk_i32 s48, 0x6000
	s_cmp_lt_i32 s15, 1
	v_readfirstlane_b32 s12, v0
	v_mul_f32_e32 v0, 0x45000000, v251
	v_exp_f32_e32 v0, v0
	s_nop 0
	v_readfirstlane_b32 s0, v0
	s_cbranch_scc1 .LBB0_130
	s_lshl_b32 s4, s43, s22
	s_lshl_b32 s4, s4, 6
	s_or_b32 s4, s4, s40
	v_mov_b32_e32 v60, 0
	v_readlane_b32 s18, v253, 3
	s_mov_b32 s1, s0
	s_mov_b32 s2, s0
	s_mov_b32 s3, s0
	s_add_i32 s4, s4, s41
	v_mov_b32_e32 v61, v60
	v_mov_b32_e32 v62, v60
	v_mov_b32_e32 v63, v60
	v_mov_b32_e32 v40, v60
	v_mov_b32_e32 v41, v60
	v_mov_b32_e32 v42, v60
	v_mov_b32_e32 v43, v60
	v_mov_b32_e32 v32, v60
	v_mov_b32_e32 v33, v60
	v_mov_b32_e32 v34, v60
	v_mov_b32_e32 v35, v60
	v_mov_b32_e32 v24, v60
	v_mov_b32_e32 v25, v60
	v_mov_b32_e32 v26, v60
	v_mov_b32_e32 v27, v60
	v_mov_b32_e32 v16, v60
	v_mov_b32_e32 v17, v60
	v_mov_b32_e32 v18, v60
	v_mov_b32_e32 v19, v60
	v_mov_b32_e32 v12, v60
	v_mov_b32_e32 v13, v60
	v_mov_b32_e32 v14, v60
	v_mov_b32_e32 v15, v60
	v_mov_b32_e32 v8, v60
	v_mov_b32_e32 v9, v60
	v_mov_b32_e32 v10, v60
	v_mov_b32_e32 v11, v60
	v_mov_b32_e32 v4, v60
	v_mov_b32_e32 v5, v60
	v_mov_b32_e32 v6, v60
	v_mov_b32_e32 v7, v60
	v_mov_b32_e32 v64, v60
	v_mov_b32_e32 v65, v60
	v_mov_b32_e32 v66, v60
	v_mov_b32_e32 v67, v60
	v_mov_b32_e32 v56, v60
	v_mov_b32_e32 v57, v60
	v_mov_b32_e32 v58, v60
	v_mov_b32_e32 v59, v60
	v_mov_b32_e32 v52, v60
	v_mov_b32_e32 v53, v60
	v_mov_b32_e32 v54, v60
	v_mov_b32_e32 v55, v60
	v_mov_b32_e32 v48, v60
	v_mov_b32_e32 v49, v60
	v_mov_b32_e32 v50, v60
	v_mov_b32_e32 v51, v60
	v_mov_b32_e32 v44, v60
	v_mov_b32_e32 v45, v60
	v_mov_b32_e32 v46, v60
	v_mov_b32_e32 v47, v60
	v_mov_b32_e32 v36, v60
	v_mov_b32_e32 v37, v60
	v_mov_b32_e32 v38, v60
	v_mov_b32_e32 v39, v60
	v_mov_b32_e32 v28, v60
	v_mov_b32_e32 v29, v60
	v_mov_b32_e32 v30, v60
	v_mov_b32_e32 v31, v60
	v_mov_b32_e32 v20, v60
	v_mov_b32_e32 v21, v60
	v_mov_b32_e32 v22, v60
	v_mov_b32_e32 v23, v60
	v_readlane_b32 s19, v253, 4
	v_readlane_b32 s13, v253, 8
	v_readlane_b32 s40, v254, 52

; #define WAIT_V(n) asm volatile("s_waitcnt vmcnt(" #n ")" ::: "memory")
; #define SB0 __builtin_amdgcn_sched_barrier(0)
; template <bool FWD>
; __device__ __forceinline__ void ret_sweep(const Params& p, int gs, int s, int g, int h, int sl, int nsegps, float lf, float lb) {
;     ...
; #pragma unroll
;     for (int mb = 0; mb < 2; ++mb)
; #pragma unroll
;       for (int nb = 0; nb < 8; ++nb) {
;         f32x4 a = T[mb][nb];
;         *(uint2*)(Ts + (nb * 16 + fr) * 264 + 32 * w + mb * 16 + fq * 4) = make_uint2(pack2(a[0], a[1]), pack2(a[2], a[3]));
;       }
;     ret_store_vt(vp, VTs, tid);
;     SB0;
;     u32x4* ypriv = (u32x4*)((char*)(Y + (long)t0 * YS + h * 512 + sl * 128) + (unsigned)(((tid >> 2) * YS + (tid & 3) * 32) * 2));
;     SB0;
;     WAIT_V(0);
;     __syncthreads();
;     f32x4 O[2][4];
; #pragma unroll
;     for (int mb = 0; mb < 2; ++mb)
; #pragma unroll
;       for (int nb = 0; nb < 4; ++nb) O[mb][nb] = f32x4{0.f, 0.f, 0.f, 0.f};
; #pragma unroll
;     for (int ks = 0; ks < 8; ++ks)
; #pragma unroll
;       for (int nb = 0; nb < 4; ++nb) {
;         bf16x8 b = *(const bf16x8*)(Ts + (64 * wv + nb * 16 + fr) * 264 + ks * 32 + fq * 8);
; #pragma unroll
;         for (int mb = 0; mb < 2; ++mb) O[mb][nb] = mfma16(qa[mb][ks], b, O[mb][nb]);
;       }
.LBB0_133:
	v_mov_b32_e32 v88, s33
	v_mbcnt_lo_u32_b32 v228, -1, 0
	v_mbcnt_hi_u32_b32 v228, -1, v228
	v_cvt_pk_bf16_f32 v89, v22, v23
	v_and_b32_e32 v250, 15, v228
	v_bfe_u32 v231, v228, 4, 2
	v_bitop3_b32 v88, v228, s49, v88 bitop3:0xc8
	v_add_u32_e32 v90, 16, v88
	v_lshlrev_b32_e32 v91, 3, v231
	v_mul_u32_u24_e32 v92, 0x210, v250
	v_cvt_pk_bf16_f32 v88, v20, v21
	v_add3_u32 v126, v90, v91, v92
	v_cvt_pk_bf16_f32 v124, v4, v5
	v_cvt_pk_bf16_f32 v125, v6, v7
	v_cvt_pk_bf16_f32 v90, v28, v29
	v_cvt_pk_bf16_f32 v91, v30, v31
	ds_write2_b64 v126, v[88:89], v[124:125] offset1:4
	v_cvt_pk_bf16_f32 v88, v8, v9
	v_cvt_pk_bf16_f32 v89, v10, v11
	v_add_u32_e32 v124, 0x2000, v126
	v_cvt_pk_bf16_f32 v92, v36, v37
	v_cvt_pk_bf16_f32 v93, v38, v39
	ds_write2_b64 v124, v[90:91], v[88:89] offset0:32 offset1:36
	v_cvt_pk_bf16_f32 v88, v12, v13
	v_cvt_pk_bf16_f32 v89, v14, v15
	v_add_u32_e32 v90, 0x4000, v126
	v_cvt_pk_bf16_f32 v94, v44, v45
	v_cvt_pk_bf16_f32 v95, v46, v47
	ds_write2_b64 v90, v[92:93], v[88:89] offset0:64 offset1:68
	v_cvt_pk_bf16_f32 v88, v16, v17
	v_cvt_pk_bf16_f32 v89, v18, v19
	v_add_u32_e32 v90, 0x6000, v126
	v_cvt_pk_bf16_f32 v116, v48, v49
	v_cvt_pk_bf16_f32 v117, v50, v51
	ds_write2_b64 v90, v[94:95], v[88:89] offset0:96 offset1:100
	v_cvt_pk_bf16_f32 v88, v24, v25
	v_cvt_pk_bf16_f32 v89, v26, v27
	v_add_u32_e32 v90, 0x8000, v126
	v_cvt_pk_bf16_f32 v118, v52, v53
	v_cvt_pk_bf16_f32 v119, v54, v55
	ds_write2_b64 v90, v[116:117], v[88:89] offset0:128 offset1:132
	v_cvt_pk_bf16_f32 v88, v32, v33
	v_cvt_pk_bf16_f32 v89, v34, v35
	v_add_u32_e32 v90, 0xa000, v126
	v_cvt_pk_bf16_f32 v120, v56, v57
	v_cvt_pk_bf16_f32 v121, v58, v59
	ds_write2_b64 v90, v[118:119], v[88:89] offset0:160 offset1:164
	v_cvt_pk_bf16_f32 v88, v40, v41
	v_cvt_pk_bf16_f32 v89, v42, v43
	v_add_u32_e32 v90, 0xc000, v126
	v_cvt_pk_bf16_f32 v122, v64, v65
	v_cvt_pk_bf16_f32 v123, v66, v67
	ds_write2_b64 v90, v[120:121], v[88:89] offset0:192 offset1:196
	v_cvt_pk_bf16_f32 v88, v60, v61
	v_cvt_pk_bf16_f32 v89, v62, v63
	v_add_u32_e32 v90, 0xe000, v126
	ds_write2_b64 v90, v[122:123], v[88:89] offset0:224 offset1:228
	v_lshlrev_b32_e32 v88, 4, v228
	v_or_b32_e32 v248, s33, v228
	v_and_b32_e32 v88, 0xf0, v88
	v_add_u32_e32 v88, s93, v88
	v_lshrrev_b32_e32 v89, 4, v248
	v_mad_u64_u32 v[90:91], s[2:3], v89, s36, v[88:89]
	v_add_u32_e32 v89, 0x200, v248
	v_lshrrev_b32_e32 v89, 4, v89
	s_waitcnt vmcnt(30)
	ds_write_b128 v90, v[204:207]
	v_mad_u64_u32 v[90:91], s[2:3], v89, s36, v[88:89]
	v_add_u32_e32 v89, 0x400, v248
	v_lshrrev_b32_e32 v89, 4, v89
	s_waitcnt vmcnt(30)
	ds_write_b128 v90, v[208:211]
	v_mad_u64_u32 v[90:91], s[2:3], v89, s36, v[88:89]
	v_add_u32_e32 v89, 0x600, v248
	v_ashrrev_i32_e32 v0, 6, v248
	v_ashrrev_i32_e32 v229, 2, v248
	v_lshrrev_b32_e32 v89, 4, v89
	v_and_b32_e32 v2, 63, v228
	v_and_b32_e32 v3, 1, v0
	v_and_b32_e32 v230, 0xffffffe0, v229
	v_and_b32_e32 v247, 48, v228
	v_mad_u64_u32 v[88:89], s[2:3], v89, s36, v[88:89]
	s_waitcnt vmcnt(28)
	ds_write_b128 v90, v[212:215]
	s_waitcnt vmcnt(28)
	ds_write_b128 v88, v[216:219]
	v_lshlrev_b32_e32 v204, 6, v3
	v_or_b32_e32 v205, v204, v250
	v_mul_u32_u24_e32 v88, 0x210, v205
	v_add3_u32 v210, 16, v247, v88
	s_waitcnt vmcnt(0)
	s_waitcnt lgkmcnt(0)
	s_barrier
	ds_read_b128 v[88:91], v210
	ds_read_b128 v[206:209], v210 offset:64
	s_waitcnt lgkmcnt(1)
	v_mfma_f32_16x16x32_bf16 v[92:95], v[220:223], v[88:91], 0
	ds_read_b128 v[116:119], v210 offset:8448
	ds_read_b128 v[124:127], v210 offset:16896
	ds_read_b128 v[148:151], v210 offset:25344
	v_mfma_f32_16x16x32_bf16 v[88:91], v[224:227], v[88:91], 0
	s_waitcnt lgkmcnt(3)
	v_mfma_f32_16x16x32_bf16 v[92:95], v[192:195], v[206:209], v[92:95]
	v_mfma_f32_16x16x32_bf16 v[88:91], v[200:203], v[206:209], v[88:91]
	ds_read_b128 v[206:209], v210 offset:8512
	s_waitcnt lgkmcnt(3)
	v_mfma_f32_16x16x32_bf16 v[120:123], v[220:223], v[116:119], 0
	v_mfma_f32_16x16x32_bf16 v[116:119], v[224:227], v[116:119], 0
	s_waitcnt lgkmcnt(0)
	v_mfma_f32_16x16x32_bf16 v[120:123], v[192:195], v[206:209], v[120:123]
	v_mfma_f32_16x16x32_bf16 v[116:119], v[200:203], v[206:209], v[116:119]
	ds_read_b128 v[206:209], v210 offset:16960
	v_mfma_f32_16x16x32_bf16 v[128:131], v[220:223], v[124:127], 0
	v_mfma_f32_16x16x32_bf16 v[124:127], v[224:227], v[124:127], 0
	s_waitcnt lgkmcnt(0)
	v_mfma_f32_16x16x32_bf16 v[128:131], v[192:195], v[206:209], v[128:131]
	v_mfma_f32_16x16x32_bf16 v[124:127], v[200:203], v[206:209], v[124:127]
	ds_read_b128 v[206:209], v210 offset:25408
	v_mfma_f32_16x16x32_bf16 v[152:155], v[220:223], v[148:151], 0
	s_waitcnt lgkmcnt(0)
	v_mfma_f32_16x16x32_bf16 v[152:155], v[192:195], v[206:209], v[152:155]
	ds_read_b128 v[192:195], v210 offset:128
	s_waitcnt lgkmcnt(0)
	v_mfma_f32_16x16x32_bf16 v[92:95], v[188:191], v[192:195], v[92:95]
	v_mfma_f32_16x16x32_bf16 v[88:91], v[196:199], v[192:195], v[88:91]
	ds_read_b128 v[192:195], v210 offset:8576
	s_waitcnt lgkmcnt(0)
	v_mfma_f32_16x16x32_bf16 v[120:123], v[188:191], v[192:195], v[120:123]
	v_mfma_f32_16x16x32_bf16 v[116:119], v[196:199], v[192:195], v[116:119]
	ds_read_b128 v[192:195], v210 offset:17024
	s_waitcnt lgkmcnt(0)
	v_mfma_f32_16x16x32_bf16 v[128:131], v[188:191], v[192:195], v[128:131]
	v_mfma_f32_16x16x32_bf16 v[124:127], v[196:199], v[192:195], v[124:127]
	ds_read_b128 v[192:195], v210 offset:25472
	s_waitcnt lgkmcnt(0)
	v_mfma_f32_16x16x32_bf16 v[152:155], v[188:191], v[192:195], v[152:155]
	ds_read_b128 v[188:191], v210 offset:192
	s_waitcnt lgkmcnt(0)
	v_mfma_f32_16x16x32_bf16 v[92:95], v[176:179], v[188:191], v[92:95]
	v_mfma_f32_16x16x32_bf16 v[88:91], v[184:187], v[188:191], v[88:91]
	ds_read_b128 v[188:191], v210 offset:8640
	s_waitcnt lgkmcnt(0)
; __device__ __forceinline__ float ex2(float x) { return __builtin_amdgcn_exp2f(x); }
; #define SB0 __builtin_amdgcn_sched_barrier(0)
; template <bool FWD>
; __device__ __forceinline__ void ret_sweep(const Params& p, int gs, int s, int g, int h, int sl, int nsegps, float lf, float lb) {
;     ...
; #pragma unroll
;     for (int ks = 0; ks < 8; ++ks)
; #pragma unroll
;       for (int nb = 0; nb < 4; ++nb) {
;         bf16x8 b = *(const bf16x8*)(Ts + (64 * wv + nb * 16 + fr) * 264 + ks * 32 + fq * 8);
; #pragma unroll
;         for (int mb = 0; mb < 2; ++mb) O[mb][nb] = mfma16(qa[mb][ks], b, O[mb][nb]);
;       }
;     SB0;
;     bf16x8 kt[2][4];
;     ret_load_kt(kt, KT + (long)(h * 128 + chunk) * 256 * 128, w, fr, fq);
;     SB0;
;     int ibase = 32 * wi + fq * 4;
;     asm volatile("" : "+v"(ibase));
; #pragma unroll
;     for (int mb = 0; mb < 2; ++mb)
; #pragma unroll
;       for (int jj = 0; jj < 4; ++jj) {
;         int i = ibase + mb * 16 + jj;
;         float sc = FWD ? ex2(lf * (float)(i + 128)) : ex2(lb * (float)(255 - i));
; #pragma unroll
;         for (int nb = 0; nb < 4; ++nb) O[mb][nb][jj] *= sc;
;       }
;     if constexpr (FWD) {
; #pragma unroll
;       for (int ks = 0; ks < 4; ++ks) {
; #pragma unroll
;         for (int nb = 0; nb < 4; ++nb) {
;           bf16x8 b = *(const bf16x8*)(VTs + (64 * wv + nb * 16 + fr) * 136 + ks * 32 + fq * 8);
; #pragma unroll
;           for (int mb = 0; mb < 2; ++mb) O[mb][nb] = mfma16(pa[mb][ks], b, O[mb][nb]);
	v_mfma_f32_16x16x32_bf16 v[120:123], v[176:179], v[188:191], v[120:123]
	v_mfma_f32_16x16x32_bf16 v[116:119], v[184:187], v[188:191], v[116:119]
	ds_read_b128 v[188:191], v210 offset:17088
	s_waitcnt lgkmcnt(0)
	v_mfma_f32_16x16x32_bf16 v[128:131], v[176:179], v[188:191], v[128:131]
	v_mfma_f32_16x16x32_bf16 v[124:127], v[184:187], v[188:191], v[124:127]
	ds_read_b128 v[188:191], v210 offset:25536
	s_waitcnt lgkmcnt(0)
	v_mfma_f32_16x16x32_bf16 v[152:155], v[176:179], v[188:191], v[152:155]
	ds_read_b128 v[176:179], v210 offset:256
	s_waitcnt lgkmcnt(0)
	v_mfma_f32_16x16x32_bf16 v[92:95], v[172:175], v[176:179], v[92:95]
	v_mfma_f32_16x16x32_bf16 v[88:91], v[180:183], v[176:179], v[88:91]
	ds_read_b128 v[176:179], v210 offset:8704
	s_waitcnt lgkmcnt(0)
	v_mfma_f32_16x16x32_bf16 v[120:123], v[172:175], v[176:179], v[120:123]
	v_mfma_f32_16x16x32_bf16 v[116:119], v[180:183], v[176:179], v[116:119]
	ds_read_b128 v[176:179], v210 offset:17152
	s_waitcnt lgkmcnt(0)
	v_mfma_f32_16x16x32_bf16 v[128:131], v[172:175], v[176:179], v[128:131]
	v_mfma_f32_16x16x32_bf16 v[124:127], v[180:183], v[176:179], v[124:127]
	ds_read_b128 v[176:179], v210 offset:25600
	s_waitcnt lgkmcnt(0)
	v_mfma_f32_16x16x32_bf16 v[152:155], v[172:175], v[176:179], v[152:155]
	ds_read_b128 v[172:175], v210 offset:320
	s_waitcnt lgkmcnt(0)
	v_mfma_f32_16x16x32_bf16 v[92:95], v[160:163], v[172:175], v[92:95]
	v_mfma_f32_16x16x32_bf16 v[88:91], v[168:171], v[172:175], v[88:91]
	ds_read_b128 v[172:175], v210 offset:8768
	s_waitcnt lgkmcnt(0)
	v_mfma_f32_16x16x32_bf16 v[120:123], v[160:163], v[172:175], v[120:123]
	v_mfma_f32_16x16x32_bf16 v[116:119], v[168:171], v[172:175], v[116:119]
	ds_read_b128 v[172:175], v210 offset:17216
	s_waitcnt lgkmcnt(0)
	v_mfma_f32_16x16x32_bf16 v[128:131], v[160:163], v[172:175], v[128:131]
	v_mfma_f32_16x16x32_bf16 v[124:127], v[168:171], v[172:175], v[124:127]
	ds_read_b128 v[172:175], v210 offset:25664
	s_waitcnt lgkmcnt(0)
	v_mfma_f32_16x16x32_bf16 v[152:155], v[160:163], v[172:175], v[152:155]
	ds_read_b128 v[160:163], v210 offset:384
	v_mfma_f32_16x16x32_bf16 v[148:151], v[224:227], v[148:151], 0
	s_waitcnt lgkmcnt(0)
	v_mfma_f32_16x16x32_bf16 v[92:95], v[156:159], v[160:163], v[92:95]
	v_mfma_f32_16x16x32_bf16 v[88:91], v[164:167], v[160:163], v[88:91]
	ds_read_b128 v[160:163], v210 offset:8832
	v_mfma_f32_16x16x32_bf16 v[148:151], v[200:203], v[206:209], v[148:151]
	s_waitcnt lgkmcnt(0)
	v_mfma_f32_16x16x32_bf16 v[120:123], v[156:159], v[160:163], v[120:123]
	v_mfma_f32_16x16x32_bf16 v[116:119], v[164:167], v[160:163], v[116:119]
	ds_read_b128 v[160:163], v210 offset:17280
	v_mfma_f32_16x16x32_bf16 v[148:151], v[196:199], v[192:195], v[148:151]
	s_waitcnt lgkmcnt(0)
	v_mfma_f32_16x16x32_bf16 v[128:131], v[156:159], v[160:163], v[128:131]
	v_mfma_f32_16x16x32_bf16 v[124:127], v[164:167], v[160:163], v[124:127]
	ds_read_b128 v[160:163], v210 offset:25728
	v_mfma_f32_16x16x32_bf16 v[148:151], v[184:187], v[188:191], v[148:151]
	s_waitcnt lgkmcnt(0)
	v_mfma_f32_16x16x32_bf16 v[152:155], v[156:159], v[160:163], v[152:155]
	ds_read_b128 v[156:159], v210 offset:448
	v_mfma_f32_16x16x32_bf16 v[148:151], v[180:183], v[176:179], v[148:151]
	v_mfma_f32_16x16x32_bf16 v[148:151], v[168:171], v[172:175], v[148:151]
	s_waitcnt lgkmcnt(0)
	v_mfma_f32_16x16x32_bf16 v[168:171], v[140:143], v[156:159], v[92:95]
	v_mfma_f32_16x16x32_bf16 v[156:159], v[144:147], v[156:159], v[88:91]
	s_nop 2
	ds_read_b128 v[88:91], v210 offset:8896
	v_mfma_f32_16x16x32_bf16 v[148:151], v[164:167], v[160:163], v[148:151]
	s_waitcnt lgkmcnt(0)
	v_mfma_f32_16x16x32_bf16 v[172:175], v[140:143], v[88:91], v[120:123]
	v_mfma_f32_16x16x32_bf16 v[160:163], v[144:147], v[88:91], v[116:119]
	ds_read_b128 v[88:91], v210 offset:17344
	s_waitcnt lgkmcnt(0)
	v_mfma_f32_16x16x32_bf16 v[176:179], v[140:143], v[88:91], v[128:131]
	v_mfma_f32_16x16x32_bf16 v[164:167], v[144:147], v[88:91], v[124:127]
	ds_read_b128 v[88:91], v210 offset:25792
	s_waitcnt lgkmcnt(0)
	v_mfma_f32_16x16x32_bf16 v[140:143], v[140:143], v[88:91], v[152:155]
	v_mfma_f32_16x16x32_bf16 v[180:183], v[144:147], v[88:91], v[148:151]
	v_lshlrev_b32_e32 v0, 13, v0
	v_lshlrev_b32_e32 v88, 8, v250
	s_add_u32 s2, s96, s6
	v_or3_b32 v0, v0, v88, v247
	s_addc_u32 s3, s97, s7
	v_lshl_add_u64 v[88:89], s[2:3], 0, v[0:1]
	s_mov_b32 s2, 0x10800000
	v_add_co_u32_e32 v90, vcc, s2, v88
	s_mov_b32 s2, 0x10801000
	s_nop 0
	v_addc_co_u32_e32 v91, vcc, 0, v89, vcc
	v_add_co_u32_e32 v92, vcc, s2, v88
	s_nop 1
	v_addc_co_u32_e32 v93, vcc, 0, v89, vcc
	global_load_dwordx4 v[124:127], v[90:91], off offset:64
	global_load_dwordx4 v[116:119], v[90:91], off offset:128
	global_load_dwordx4 v[148:151], v[92:93], off offset:-4096
	s_nop 0
	global_load_dwordx4 v[88:91], v[90:91], off offset:192
	s_nop 0
	global_load_dwordx4 v[152:155], v[92:93], off
	global_load_dwordx4 v[128:131], v[92:93], off offset:64
	global_load_dwordx4 v[120:123], v[92:93], off offset:128
	s_nop 0
	global_load_dwordx4 v[92:95], v[92:93], off offset:192
	v_lshl_or_b32 v144, v231, 2, v230
	v_mov_b32_e32 v0, v144
	s_nop 0
	v_add_u32_e32 v145, 0x80, v0
	v_cvt_f32_i32_e32 v145, v145
	v_mul_f32_e32 v145, v251, v145
	v_exp_f32_e32 v146, v145
	v_add_u32_e32 v145, 0x81, v0
	v_cvt_f32_i32_e32 v145, v145
	v_mul_f32_e32 v145, v251, v145
	v_exp_f32_e32 v147, v145
	v_add_u32_e32 v145, 0x82, v0
	v_cvt_f32_i32_e32 v145, v145
	v_pk_mul_f32 v[168:169], v[168:169], v[146:147]
	v_pk_mul_f32 v[172:173], v[172:173], v[146:147]
	v_mul_f32_e32 v145, v251, v145
	v_exp_f32_e32 v184, v145
	v_add_u32_e32 v145, 0x83, v0
	v_cvt_f32_i32_e32 v145, v145
	v_pk_mul_f32 v[176:177], v[176:177], v[146:147]
	v_pk_mul_f32 v[140:141], v[140:141], v[146:147]
	v_mul_f32_e32 v145, v251, v145
	v_exp_f32_e32 v185, v145
	v_add_u32_e32 v145, 0x90, v0
	v_cvt_f32_i32_e32 v145, v145
	v_pk_mul_f32 v[170:171], v[170:171], v[184:185]
	v_pk_mul_f32 v[174:175], v[174:175], v[184:185]
	v_mul_f32_e32 v145, v251, v145
	v_exp_f32_e32 v146, v145
	v_add_u32_e32 v145, 0x91, v0
	v_cvt_f32_i32_e32 v145, v145
	v_pk_mul_f32 v[178:179], v[178:179], v[184:185]
	v_pk_mul_f32 v[142:143], v[142:143], v[184:185]
	v_mul_f32_e32 v145, v251, v145
	v_exp_f32_e32 v147, v145
	v_add_u32_e32 v145, 0x92, v0
	v_add_u32_e32 v0, 0x93, v0
	v_cvt_f32_i32_e32 v145, v145
	v_cvt_f32_i32_e32 v0, v0
	v_pk_mul_f32 v[156:157], v[156:157], v[146:147]
	v_pk_mul_f32 v[160:161], v[160:161], v[146:147]
	v_mul_f32_e32 v145, v251, v145
	v_mul_f32_e32 v0, v251, v0
	v_exp_f32_e32 v184, v145
	v_exp_f32_e32 v185, v0
	v_mul_u32_u24_e32 v0, 0x110, v205
	v_add3_u32 v0, s93, v247, v0
	v_pk_mul_f32 v[164:165], v[164:165], v[146:147]
	v_pk_mul_f32 v[158:159], v[158:159], v[184:185]
	v_pk_mul_f32 v[162:163], v[162:163], v[184:185]
	v_pk_mul_f32 v[166:167], v[166:167], v[184:185]
	v_pk_mul_f32 v[182:183], v[182:183], v[184:185]
	ds_read_b128 v[184:187], v0
	s_waitcnt vmcnt(19) lgkmcnt(0)
; __device__ __forceinline__ float bf2f(u16 b) { return __uint_as_float(((unsigned)b) << 16); }
; #define SB0 __builtin_amdgcn_sched_barrier(0)
; template <bool FWD>
; __device__ __forceinline__ void ret_sweep(const Params& p, int gs, int s, int g, int h, int sl, int nsegps, float lf, float lb) {
;     ...
;     if constexpr (FWD) {
; #pragma unroll
;       for (int ks = 0; ks < 4; ++ks) {
; #pragma unroll
;         for (int nb = 0; nb < 4; ++nb) {
;           bf16x8 b = *(const bf16x8*)(VTs + (64 * wv + nb * 16 + fr) * 136 + ks * 32 + fq * 8);
; #pragma unroll
;           for (int mb = 0; mb < 2; ++mb) O[mb][nb] = mfma16(pa[mb][ks], b, O[mb][nb]);
;         }
;       }
;     }
;     SB0;
;     if constexpr (!FWD) {
; #pragma unroll
;       for (int q = 0; q < 4; ++q) {
;         u32x4 pk;
; #pragma unroll
;         for (int e2 = 0; e2 < 4; ++e2) {
;           int e = q * 8 + e2 * 2;
;           pk[e2] = pack2(O[e >> 4][e & 3][(e >> 2) & 3], O[(e + 1) >> 4][(e + 1) & 3][((e + 1) >> 2) & 3]);
;         }
;         ypriv[q] = pk;
;       }
;     } else {
; #pragma unroll
;       for (int mb = 0; mb < 2; ++mb)
; #pragma unroll
;         for (int jj = 0; jj < 4; ++jj) {
;           int i = 32 * wi + mb * 16 + fq * 4 + jj;
;           u16* yp = (u16*)((char*)(Y + (long)t0 * YS + h * 512 + sl * 128) + (unsigned)((i * YS + 64 * wv + fr) * 2));
;           float s1 = 0.f, s2 = 0.f;
; #pragma unroll
;           for (int nb = 0; nb < 4; ++nb) {
;             int e = (mb * 4 + jj) * 4 + nb;
;             unsigned pw = yb[e >> 3][(e >> 1) & 3];
;             float prev = bf2f((u16)((e & 1) ? (pw >> 16) : (pw & 0xffffu)));
;             float v = O[mb][nb][jj] + prev;
;             yp[nb * 16] = f2bf(v);
;             s1 += v; s2 += v * v;
;           }
; #pragma unroll
;           for (int o = 1; o < 16; o <<= 1) { s1 += shx(s1, o, lane); s2 += shx(s2, o, lane); }
;           if (fr == 0) { red[(i * 2 + wv) * 2] = s1; red[(i * 2 + wv) * 2 + 1] = s2; }
	v_mfma_f32_16x16x32_bf16 v[168:171], v[132:135], v[184:187], v[168:171]
	v_mul_f32_e64 v180, v180, v146
	v_mul_f32_e64 v181, v181, v147
	s_waitcnt vmcnt(15)
	v_mfma_f32_16x16x32_bf16 v[156:159], v[136:139], v[184:187], v[156:159]
	ds_read_b128 v[184:187], v0 offset:4352
	s_waitcnt lgkmcnt(0)
	v_mfma_f32_16x16x32_bf16 v[172:175], v[132:135], v[184:187], v[172:175]
	v_mfma_f32_16x16x32_bf16 v[160:163], v[136:139], v[184:187], v[160:163]
	ds_read_b128 v[184:187], v0 offset:8704
	s_waitcnt lgkmcnt(0)
	v_mfma_f32_16x16x32_bf16 v[176:179], v[132:135], v[184:187], v[176:179]
	v_mfma_f32_16x16x32_bf16 v[164:167], v[136:139], v[184:187], v[164:167]
	ds_read_b128 v[184:187], v0 offset:13056
	s_waitcnt lgkmcnt(0)
	v_mfma_f32_16x16x32_bf16 v[132:135], v[132:135], v[184:187], v[140:143]
	s_nop 2
	ds_read_b128 v[140:143], v0 offset:64
	s_waitcnt lgkmcnt(0)
	v_mfma_f32_16x16x32_bf16 v[168:171], v[104:107], v[140:143], v[168:171]
	s_waitcnt vmcnt(14)
	v_mfma_f32_16x16x32_bf16 v[140:143], v[112:115], v[140:143], v[156:159]
	s_nop 2
	ds_read_b128 v[156:159], v0 offset:4416
	s_waitcnt lgkmcnt(0)
	v_mfma_f32_16x16x32_bf16 v[172:175], v[104:107], v[156:159], v[172:175]
	v_mfma_f32_16x16x32_bf16 v[156:159], v[112:115], v[156:159], v[160:163]
	s_nop 2
	ds_read_b128 v[160:163], v0 offset:8768
	s_waitcnt lgkmcnt(0)
	v_mfma_f32_16x16x32_bf16 v[176:179], v[104:107], v[160:163], v[176:179]
	v_mfma_f32_16x16x32_bf16 v[160:163], v[112:115], v[160:163], v[164:167]
	s_nop 2
	ds_read_b128 v[164:167], v0 offset:13120
	s_waitcnt lgkmcnt(0)
	v_mfma_f32_16x16x32_bf16 v[104:107], v[104:107], v[164:167], v[132:135]
	s_nop 2
	ds_read_b128 v[132:135], v0 offset:128
	v_mfma_f32_16x16x32_bf16 v[136:139], v[136:139], v[184:187], v[180:183]
	v_mfma_f32_16x16x32_bf16 v[112:115], v[112:115], v[164:167], v[136:139]
	s_waitcnt lgkmcnt(0)
	v_mfma_f32_16x16x32_bf16 v[136:139], v[100:103], v[132:135], v[168:171]
	s_waitcnt vmcnt(13)
	v_mfma_f32_16x16x32_bf16 v[140:143], v[108:111], v[132:135], v[140:143]
	ds_read_b128 v[132:135], v0 offset:4480
	s_waitcnt lgkmcnt(0)
	v_mfma_f32_16x16x32_bf16 v[164:167], v[100:103], v[132:135], v[172:175]
	v_mfma_f32_16x16x32_bf16 v[156:159], v[108:111], v[132:135], v[156:159]
	ds_read_b128 v[132:135], v0 offset:8832
	s_waitcnt lgkmcnt(0)
	v_mfma_f32_16x16x32_bf16 v[168:171], v[100:103], v[132:135], v[176:179]
	v_mfma_f32_16x16x32_bf16 v[160:163], v[108:111], v[132:135], v[160:163]
	ds_read_b128 v[132:135], v0 offset:13184
	s_waitcnt lgkmcnt(0)
	v_mfma_f32_16x16x32_bf16 v[172:175], v[100:103], v[132:135], v[104:107]
	ds_read_b128 v[100:103], v0 offset:192
	v_mfma_f32_16x16x32_bf16 v[176:179], v[108:111], v[132:135], v[112:115]
	ds_read_b128 v[108:111], v0 offset:8896
	s_waitcnt lgkmcnt(1)
	v_mfma_f32_16x16x32_bf16 v[132:135], v[84:87], v[100:103], v[136:139]
	s_waitcnt vmcnt(12)
	v_mfma_f32_16x16x32_bf16 v[104:107], v[96:99], v[100:103], v[140:143]
	ds_read_b128 v[100:103], v0 offset:4544
	s_waitcnt lgkmcnt(0)
	v_mfma_f32_16x16x32_bf16 v[112:115], v[84:87], v[100:103], v[164:167]
	v_mfma_f32_16x16x32_bf16 v[100:103], v[96:99], v[100:103], v[156:159]
	s_nop 2
	ds_read_b128 v[156:159], v0 offset:13248
	v_mfma_f32_16x16x32_bf16 v[136:139], v[84:87], v[108:111], v[168:171]
	v_mfma_f32_16x16x32_bf16 v[108:111], v[96:99], v[108:111], v[160:163]
	s_waitcnt lgkmcnt(0)
	v_mfma_f32_16x16x32_bf16 v[140:143], v[84:87], v[156:159], v[172:175]
	v_mfma_f32_16x16x32_bf16 v[84:87], v[96:99], v[156:159], v[176:179]
	v_readlane_b32 s2, v254, 45
	s_waitcnt vmcnt(8)
	v_and_b32_e32 v96, 0xffff0000, v81
	v_lshlrev_b32_e32 v81, 16, v81
	v_lshl_add_u32 v97, v3, 3, s2
	v_lshlrev_b32_e32 v3, 16, v80
	v_and_b32_e32 v80, 0xffff0000, v80
	v_mov_b32_e32 v156, v112
	v_mov_b32_e32 v157, v136
	v_pk_add_f32 v[156:157], v[156:157], v[80:81]
	v_add_f32_e32 v98, v132, v3
	v_pk_mul_f32 v[158:159], v[156:157], v[156:157]
	v_mov_b32_e32 v99, v136
	v_mov_b32_e32 v160, v1
	v_mov_b32_e32 v161, v81
	v_mul_f32_e32 v3, v98, v98
	v_lshlrev_b32_e32 v132, 2, v2
	v_pk_add_f32 v[160:161], v[98:99], v[160:161]
	v_mov_b32_e32 v2, v136
	v_pk_mov_b32 v[80:81], v[80:81], v[158:159] op_sel:[1,0]
	v_pk_mul_f32 v[158:159], v[156:157], v[160:161]
	v_pk_add_f32 v[2:3], v[2:3], v[80:81]
	v_pk_add_f32 v[80:81], v[156:157], v[160:161]
	v_add_f32_e32 v146, v140, v96
	v_mov_b32_e32 v81, v159
	v_mul_f32_e32 v147, v146, v146
	v_pk_add_f32 v[2:3], v[80:81], v[2:3]
	v_xor_b32_e32 v96, 4, v132
	v_pk_add_f32 v[2:3], v[2:3], v[146:147]
	ds_bpermute_b32 v80, v96, v2
	ds_bpermute_b32 v81, v96, v3
	v_xor_b32_e32 v99, 8, v132
	v_xor_b32_e32 v112, 16, v132
	s_movk_i32 s2, 0x1080
	v_mul_lo_u32 v145, v144, s2
	s_waitcnt lgkmcnt(0)
	v_pk_add_f32 v[2:3], v[2:3], v[80:81]
	ds_bpermute_b32 v80, v99, v2
	ds_bpermute_b32 v81, v99, v3
	v_or_b32_e32 v0, v205, v145
	s_add_u32 s2, s96, s38
	v_lshlrev_b32_e32 v0, 1, v0
	s_addc_u32 s3, s97, s35
	s_waitcnt lgkmcnt(0)
	v_pk_add_f32 v[2:3], v[2:3], v[80:81]
	ds_bpermute_b32 v80, v112, v2
	ds_bpermute_b32 v81, v112, v3
	v_lshl_add_u64 v[158:159], s[2:3], 0, v[0:1]
	v_cvt_pk_bf16_f32 v0, v98, s0
	v_xor_b32_e32 v98, 32, v132
	v_add_co_u32_e32 v158, vcc, s37, v158
	s_waitcnt lgkmcnt(0)
	v_pk_add_f32 v[2:3], v[2:3], v[80:81]
	ds_bpermute_b32 v80, v98, v2
	ds_bpermute_b32 v81, v98, v3
	v_addc_co_u32_e32 v159, vcc, 0, v159, vcc
	global_store_short v[158:159], v0, off
	v_cvt_pk_bf16_f32 v0, v146, s0
	global_store_short v[158:159], v0, off offset:96
	v_cvt_pk_bf16_f32 v0, v156, s0
	v_cmp_eq_u32_e64 s[4:5], 0, v250
	global_store_short v[158:159], v0, off offset:32
	v_cvt_pk_bf16_f32 v0, v157, s0
	v_lshl_add_u32 v97, v144, 4, v97
	global_store_short v[158:159], v0, off offset:64
	s_and_saveexec_b64 s[2:3], s[4:5]
	s_cbranch_execz .LBB0_135
	s_waitcnt lgkmcnt(0)
	v_pk_add_f32 v[2:3], v[2:3], v[80:81]
	ds_write_b64 v97, v[2:3]

; #define WAIT_V(n) asm volatile("s_waitcnt vmcnt(" #n ")" ::: "memory")
; #define WAIT_L(n) asm volatile("s_waitcnt lgkmcnt(" #n ")" ::: "memory")
; #define BAR __builtin_amdgcn_s_barrier()
; #define SCHED __builtin_amdgcn_sched_barrier(0)
; __device__ __forceinline__ void mainloop_8phase(const u16* __restrict__ A, const u16* __restrict__ Bt, int K,
;                                                 f32x4 (&acc)[2][2][4][2], int wid_s, int ld) {
;     ...
;     LDB(B0, 0, 0); SCHED; LDA(At, 0, 0); STAGE(SA(1, 1), A, brow + G_HALF, t + 1);
;     WAIT_L(8); BAR; WAIT_L(0); MMA(0, 0, At, B0); BAR; SCHED;
;     LDB(B1, 0, 1); STAGE(SB(0, 0), Bt, bcol, t + 2);
;     BAR; WAIT_L(0); MMA(0, 1, At, B1); BAR;
;     LDA(At, 0, 1); STAGE(SA(0, 0), A, brow, t + 2);
;     BAR; WAIT_L(0); MMA(1, 0, At, B0); BAR; SCHED;
;     STAGE(SB(0, 1), Bt, bcol + G_HALF, t + 2);
;     WAIT_V(6); BAR; MMA(1, 1, At, B1); BAR;
;     LDB(B0, 1, 0); SCHED; LDA(At, 1, 0); STAGE(SA(0, 1), A, brow + G_HALF, t + 2);
;     WAIT_L(8); BAR; WAIT_L(0); MMA(0, 0, At, B0); BAR; SCHED;
;     LDB(B1, 1, 1); STAGE(SB(1, 0), Bt, bcol, t + 3);
;     BAR; WAIT_L(0); MMA(0, 1, At, B1); BAR;
.LBB0_162:
	ds_read_b128 v[156:159], v148
	ds_read_b128 v[160:163], v148 offset:1024
	ds_read_b128 v[164:167], v148 offset:2048
	ds_read_b128 v[168:171], v148 offset:3072
	v_readfirstlane_b32 s7, v150
	s_add_i32 s6, s3, 0xffffff00
	s_mov_b32 m0, s7
	v_readfirstlane_b32 s7, v149
	ds_read_b128 v[172:175], v133
	ds_read_b128 v[176:179], v133 offset:1024
	ds_read_b128 v[180:183], v132
	ds_read_b128 v[184:187], v132 offset:1024
	ds_read_b128 v[188:191], v131
	ds_read_b128 v[192:195], v131 offset:1024
	ds_read_b128 v[196:199], v130
	ds_read_b128 v[200:203], v130 offset:1024
	buffer_load_dwordx4 v137, s[88:91], s6 offen lds
	s_mov_b32 m0, s7
	s_nop 0
	buffer_load_dwordx4 v136, s[88:91], s6 offen lds
	s_waitcnt lgkmcnt(8)
	s_barrier
	s_waitcnt lgkmcnt(0)
	v_mfma_f32_16x16x32_bf16 v[126:129], v[172:175], v[156:159], v[126:129]
	v_mfma_f32_16x16x32_bf16 v[122:125], v[172:175], v[164:167], v[122:125]
	v_mfma_f32_16x16x32_bf16 v[118:121], v[180:183], v[156:159], v[118:121]
	v_mfma_f32_16x16x32_bf16 v[114:117], v[180:183], v[164:167], v[114:117]
	v_mfma_f32_16x16x32_bf16 v[110:113], v[188:191], v[156:159], v[110:113]
	v_mfma_f32_16x16x32_bf16 v[106:109], v[188:191], v[164:167], v[106:109]
	v_mfma_f32_16x16x32_bf16 v[102:105], v[196:199], v[156:159], v[102:105]
	v_mfma_f32_16x16x32_bf16 v[98:101], v[196:199], v[164:167], v[98:101]
	v_mfma_f32_16x16x32_bf16 v[126:129], v[176:179], v[160:163], v[126:129]
	v_mfma_f32_16x16x32_bf16 v[122:125], v[176:179], v[168:171], v[122:125]
	v_mfma_f32_16x16x32_bf16 v[118:121], v[184:187], v[160:163], v[118:121]
	v_mfma_f32_16x16x32_bf16 v[114:117], v[184:187], v[168:171], v[114:117]
	v_mfma_f32_16x16x32_bf16 v[110:113], v[192:195], v[160:163], v[110:113]
	v_mfma_f32_16x16x32_bf16 v[106:109], v[192:195], v[168:171], v[106:109]
	v_mfma_f32_16x16x32_bf16 v[102:105], v[200:203], v[160:163], v[102:105]
	v_mfma_f32_16x16x32_bf16 v[98:101], v[200:203], v[168:171], v[98:101]
	s_barrier
	v_readfirstlane_b32 s16, v146
	s_add_i32 s15, s3, 0xfff7ff80
	s_mov_b32 s6, s90
	s_mov_b32 s7, s91
	s_mov_b32 m0, s16
	v_readfirstlane_b32 s16, v151
	ds_read_b128 v[204:207], v145
	ds_read_b128 v[208:211], v145 offset:1024
	ds_read_b128 v[212:215], v145 offset:2048
	ds_read_b128 v[216:219], v145 offset:3072
	buffer_load_dwordx4 v137, s[4:7], s15 offen lds
	s_mov_b32 m0, s16
	s_nop 0
	buffer_load_dwordx4 v136, s[4:7], s15 offen lds
	s_barrier
	s_waitcnt lgkmcnt(0)
	v_mfma_f32_16x16x32_bf16 v[94:97], v[172:175], v[204:207], v[94:97]
	v_mfma_f32_16x16x32_bf16 v[90:93], v[172:175], v[212:215], v[90:93]
	v_mfma_f32_16x16x32_bf16 v[86:89], v[180:183], v[204:207], v[86:89]
	v_mfma_f32_16x16x32_bf16 v[82:85], v[180:183], v[212:215], v[82:85]
	v_mfma_f32_16x16x32_bf16 v[78:81], v[188:191], v[204:207], v[78:81]
	v_mfma_f32_16x16x32_bf16 v[74:77], v[188:191], v[212:215], v[74:77]
	v_mfma_f32_16x16x32_bf16 v[70:73], v[196:199], v[204:207], v[70:73]
	v_mfma_f32_16x16x32_bf16 v[66:69], v[196:199], v[212:215], v[66:69]
	v_mfma_f32_16x16x32_bf16 v[94:97], v[176:179], v[208:211], v[94:97]
	v_mfma_f32_16x16x32_bf16 v[90:93], v[176:179], v[216:219], v[90:93]
	v_mfma_f32_16x16x32_bf16 v[86:89], v[184:187], v[208:211], v[86:89]
	v_mfma_f32_16x16x32_bf16 v[82:85], v[184:187], v[216:219], v[82:85]
	v_mfma_f32_16x16x32_bf16 v[78:81], v[192:195], v[208:211], v[78:81]
	v_mfma_f32_16x16x32_bf16 v[74:77], v[192:195], v[216:219], v[74:77]
	v_mfma_f32_16x16x32_bf16 v[70:73], v[200:203], v[208:211], v[70:73]
	v_mfma_f32_16x16x32_bf16 v[66:69], v[200:203], v[216:219], v[66:69]
	v_readfirstlane_b32 s16, v140
	s_mov_b32 m0, s16
	v_readfirstlane_b32 s16, v152
	s_barrier
	ds_read_b128 v[172:175], v133 offset:16384
	ds_read_b128 v[176:179], v133 offset:17408
	ds_read_b128 v[180:183], v132 offset:16384
	ds_read_b128 v[184:187], v132 offset:17408
	ds_read_b128 v[188:191], v131 offset:16384
	ds_read_b128 v[192:195], v131 offset:17408
	ds_read_b128 v[196:199], v130 offset:16384
	ds_read_b128 v[200:203], v130 offset:17408
	buffer_load_dwordx4 v137, s[88:91], s15 offen lds
	s_mov_b32 m0, s16
	s_nop 0
	buffer_load_dwordx4 v136, s[88:91], s15 offen lds
	s_barrier
	s_waitcnt lgkmcnt(0)
	v_mfma_f32_16x16x32_bf16 v[62:65], v[172:175], v[156:159], v[62:65]
	v_mfma_f32_16x16x32_bf16 v[58:61], v[172:175], v[164:167], v[58:61]
	v_mfma_f32_16x16x32_bf16 v[54:57], v[180:183], v[156:159], v[54:57]
	v_mfma_f32_16x16x32_bf16 v[50:53], v[180:183], v[164:167], v[50:53]
	v_mfma_f32_16x16x32_bf16 v[46:49], v[188:191], v[156:159], v[46:49]
	v_mfma_f32_16x16x32_bf16 v[42:45], v[188:191], v[164:167], v[42:45]
	v_mfma_f32_16x16x32_bf16 v[38:41], v[196:199], v[156:159], v[38:41]
	v_mfma_f32_16x16x32_bf16 v[34:37], v[196:199], v[164:167], v[34:37]
	v_mfma_f32_16x16x32_bf16 v[62:65], v[176:179], v[160:163], v[62:65]
	v_mfma_f32_16x16x32_bf16 v[58:61], v[176:179], v[168:171], v[58:61]
	v_mfma_f32_16x16x32_bf16 v[54:57], v[184:187], v[160:163], v[54:57]
	v_mfma_f32_16x16x32_bf16 v[50:53], v[184:187], v[168:171], v[50:53]
	v_mfma_f32_16x16x32_bf16 v[46:49], v[192:195], v[160:163], v[46:49]
	v_mfma_f32_16x16x32_bf16 v[42:45], v[192:195], v[168:171], v[42:45]
	v_mfma_f32_16x16x32_bf16 v[38:41], v[200:203], v[160:163], v[38:41]
	v_mfma_f32_16x16x32_bf16 v[34:37], v[200:203], v[168:171], v[34:37]
	s_barrier
	v_readfirstlane_b32 s16, v147
	s_add_i32 s15, s3, 0xffffff80
	s_mov_b32 m0, s16
	v_readfirstlane_b32 s16, v153
	buffer_load_dwordx4 v137, s[4:7], s15 offen lds
	s_mov_b32 m0, s16
	s_nop 0
	buffer_load_dwordx4 v136, s[4:7], s15 offen lds
	s_waitcnt vmcnt(6)
	s_barrier
; #define WAIT_V(n) asm volatile("s_waitcnt vmcnt(" #n ")" ::: "memory")
; #define WAIT_L(n) asm volatile("s_waitcnt lgkmcnt(" #n ")" ::: "memory")
; #define BAR __builtin_amdgcn_s_barrier()
; #define SCHED __builtin_amdgcn_sched_barrier(0)
; __device__ __forceinline__ void mainloop_8phase(const u16* __restrict__ A, const u16* __restrict__ Bt, int K,
;                                                 f32x4 (&acc)[2][2][4][2], int wid_s, int ld) {
;     ...
;     WAIT_V(6); BAR; MMA(1, 1, At, B1); BAR;
;     LDB(B0, 1, 0); SCHED; LDA(At, 1, 0); STAGE(SA(0, 1), A, brow + G_HALF, t + 2);
;     WAIT_L(8); BAR; WAIT_L(0); MMA(0, 0, At, B0); BAR; SCHED;
;     LDB(B1, 1, 1); STAGE(SB(1, 0), Bt, bcol, t + 3);
;     BAR; WAIT_L(0); MMA(0, 1, At, B1); BAR;
;     LDA(At, 1, 1); STAGE(SA(1, 0), A, brow, t + 3);
	v_mfma_f32_16x16x32_bf16 v[30:33], v[172:175], v[204:207], v[30:33]
	v_mfma_f32_16x16x32_bf16 v[26:29], v[172:175], v[212:215], v[26:29]
	v_mfma_f32_16x16x32_bf16 v[22:25], v[180:183], v[204:207], v[22:25]
	v_mfma_f32_16x16x32_bf16 v[18:21], v[180:183], v[212:215], v[18:21]
	v_mfma_f32_16x16x32_bf16 v[14:17], v[188:191], v[204:207], v[14:17]
	v_mfma_f32_16x16x32_bf16 v[10:13], v[188:191], v[212:215], v[10:13]
	v_mfma_f32_16x16x32_bf16 v[6:9], v[196:199], v[204:207], v[6:9]
	v_mfma_f32_16x16x32_bf16 v[2:5], v[196:199], v[212:215], v[2:5]
	v_mfma_f32_16x16x32_bf16 v[30:33], v[176:179], v[208:211], v[30:33]
	v_mfma_f32_16x16x32_bf16 v[26:29], v[176:179], v[216:219], v[26:29]
	v_mfma_f32_16x16x32_bf16 v[22:25], v[184:187], v[208:211], v[22:25]
	v_mfma_f32_16x16x32_bf16 v[18:21], v[184:187], v[216:219], v[18:21]
	v_mfma_f32_16x16x32_bf16 v[14:17], v[192:195], v[208:211], v[14:17]
	v_mfma_f32_16x16x32_bf16 v[10:13], v[192:195], v[216:219], v[10:13]
	v_mfma_f32_16x16x32_bf16 v[6:9], v[200:203], v[208:211], v[6:9]
	v_mfma_f32_16x16x32_bf16 v[2:5], v[200:203], v[216:219], v[2:5]
	s_barrier
	ds_read_b128 v[156:159], v135
	ds_read_b128 v[160:163], v135 offset:1024
	ds_read_b128 v[164:167], v135 offset:2048
	ds_read_b128 v[168:171], v135 offset:3072
	v_readfirstlane_b32 s16, v154
	s_mov_b32 m0, s16
	v_readfirstlane_b32 s16, v155
	ds_read_b128 v[172:175], v133 offset:32768
	ds_read_b128 v[176:179], v133 offset:33792
	ds_read_b128 v[180:183], v132 offset:32768
	ds_read_b128 v[184:187], v132 offset:33792
	ds_read_b128 v[188:191], v131 offset:32768
	ds_read_b128 v[192:195], v131 offset:33792
	ds_read_b128 v[196:199], v130 offset:32768
	ds_read_b128 v[200:203], v130 offset:33792
	buffer_load_dwordx4 v137, s[88:91], s15 offen lds
	s_mov_b32 m0, s16
	s_nop 0
	buffer_load_dwordx4 v136, s[88:91], s15 offen lds
	s_waitcnt lgkmcnt(8)
	s_barrier
	s_waitcnt lgkmcnt(0)
	v_mfma_f32_16x16x32_bf16 v[126:129], v[172:175], v[156:159], v[126:129]
	v_mfma_f32_16x16x32_bf16 v[122:125], v[172:175], v[164:167], v[122:125]
	v_mfma_f32_16x16x32_bf16 v[118:121], v[180:183], v[156:159], v[118:121]
	v_mfma_f32_16x16x32_bf16 v[114:117], v[180:183], v[164:167], v[114:117]
	v_mfma_f32_16x16x32_bf16 v[110:113], v[188:191], v[156:159], v[110:113]
	v_mfma_f32_16x16x32_bf16 v[106:109], v[188:191], v[164:167], v[106:109]
	v_mfma_f32_16x16x32_bf16 v[102:105], v[196:199], v[156:159], v[102:105]
	v_mfma_f32_16x16x32_bf16 v[98:101], v[196:199], v[164:167], v[98:101]
	v_mfma_f32_16x16x32_bf16 v[126:129], v[176:179], v[160:163], v[126:129]
	v_mfma_f32_16x16x32_bf16 v[122:125], v[176:179], v[168:171], v[122:125]
	v_mfma_f32_16x16x32_bf16 v[118:121], v[184:187], v[160:163], v[118:121]
	v_mfma_f32_16x16x32_bf16 v[114:117], v[184:187], v[168:171], v[114:117]
	v_mfma_f32_16x16x32_bf16 v[110:113], v[192:195], v[160:163], v[110:113]
	v_mfma_f32_16x16x32_bf16 v[106:109], v[192:195], v[168:171], v[106:109]
	v_mfma_f32_16x16x32_bf16 v[102:105], v[200:203], v[160:163], v[102:105]
	v_mfma_f32_16x16x32_bf16 v[98:101], v[200:203], v[168:171], v[98:101]
	s_barrier
	v_readfirstlane_b32 s16, v138
	s_add_i32 s15, s3, 0xfff80000
	s_mov_b32 m0, s16
	v_readfirstlane_b32 s16, v139
	ds_read_b128 v[204:207], v134
	ds_read_b128 v[208:211], v134 offset:1024
	ds_read_b128 v[212:215], v134 offset:2048
	ds_read_b128 v[216:219], v134 offset:3072
	buffer_load_dwordx4 v137, s[4:7], s15 offen lds
	s_mov_b32 m0, s16
	s_nop 0
	buffer_load_dwordx4 v136, s[4:7], s15 offen lds
	s_barrier
	s_waitcnt lgkmcnt(0)
	v_mfma_f32_16x16x32_bf16 v[94:97], v[172:175], v[204:207], v[94:97]
	v_mfma_f32_16x16x32_bf16 v[90:93], v[172:175], v[212:215], v[90:93]
	v_mfma_f32_16x16x32_bf16 v[86:89], v[180:183], v[204:207], v[86:89]
	v_mfma_f32_16x16x32_bf16 v[82:85], v[180:183], v[212:215], v[82:85]
	v_mfma_f32_16x16x32_bf16 v[78:81], v[188:191], v[204:207], v[78:81]
	v_mfma_f32_16x16x32_bf16 v[74:77], v[188:191], v[212:215], v[74:77]
	v_mfma_f32_16x16x32_bf16 v[70:73], v[196:199], v[204:207], v[70:73]
	v_mfma_f32_16x16x32_bf16 v[66:69], v[196:199], v[212:215], v[66:69]
	v_mfma_f32_16x16x32_bf16 v[94:97], v[176:179], v[208:211], v[94:97]
	v_mfma_f32_16x16x32_bf16 v[90:93], v[176:179], v[216:219], v[90:93]
	v_mfma_f32_16x16x32_bf16 v[86:89], v[184:187], v[208:211], v[86:89]
	v_mfma_f32_16x16x32_bf16 v[82:85], v[184:187], v[216:219], v[82:85]
	v_mfma_f32_16x16x32_bf16 v[78:81], v[192:195], v[208:211], v[78:81]
	v_mfma_f32_16x16x32_bf16 v[74:77], v[192:195], v[216:219], v[74:77]
	v_mfma_f32_16x16x32_bf16 v[70:73], v[200:203], v[208:211], v[70:73]
	v_mfma_f32_16x16x32_bf16 v[66:69], v[200:203], v[216:219], v[66:69]
	v_readfirstlane_b32 s16, v141
	s_mov_b32 m0, s16
	v_readfirstlane_b32 s16, v142
	s_barrier
	ds_read_b128 v[172:175], v133 offset:49152
	ds_read_b128 v[176:179], v133 offset:50176
	ds_read_b128 v[180:183], v132 offset:49152
	ds_read_b128 v[184:187], v132 offset:50176
	ds_read_b128 v[188:191], v131 offset:49152
	ds_read_b128 v[192:195], v131 offset:50176
	ds_read_b128 v[196:199], v130 offset:49152
	ds_read_b128 v[200:203], v130 offset:50176
	buffer_load_dwordx4 v137, s[88:91], s15 offen lds
	s_mov_b32 m0, s16
	s_nop 0
	buffer_load_dwordx4 v136, s[88:91], s15 offen lds
	s_barrier
; #define WAIT_V(n) asm volatile("s_waitcnt vmcnt(" #n ")" ::: "memory")
; #define WAIT_L(n) asm volatile("s_waitcnt lgkmcnt(" #n ")" ::: "memory")
; #define BAR __builtin_amdgcn_s_barrier()
; #define SCHED __builtin_amdgcn_sched_barrier(0)
; __device__ __forceinline__ void mainloop_8phase(const u16* __restrict__ A, const u16* __restrict__ Bt, int K,
;                                                 f32x4 (&acc)[2][2][4][2], int wid_s, int ld) {
;     ...
;     BAR; WAIT_L(0); MMA(1, 0, At, B0); BAR; SCHED;
;     STAGE(SB(1, 1), Bt, bcol + G_HALF, t + 3);
;     WAIT_V(6); BAR; MMA(1, 1, At, B1); BAR;
;   }
;   { LDB(B0, 0, 0); LDA(At, 0, 0); STAGE(SA(1, 1), A, brow + G_HALF, nt - 1);
;     BAR; WAIT_L(0); MMA(0, 0, At, B0); BAR;
;     LDB(B1, 0, 1); BAR; WAIT_L(0); MMA(0, 1, At, B1); BAR;
	s_waitcnt lgkmcnt(0)
	v_mfma_f32_16x16x32_bf16 v[62:65], v[172:175], v[156:159], v[62:65]
	v_mfma_f32_16x16x32_bf16 v[58:61], v[172:175], v[164:167], v[58:61]
	v_mfma_f32_16x16x32_bf16 v[54:57], v[180:183], v[156:159], v[54:57]
	v_mfma_f32_16x16x32_bf16 v[50:53], v[180:183], v[164:167], v[50:53]
	v_mfma_f32_16x16x32_bf16 v[46:49], v[188:191], v[156:159], v[46:49]
	v_mfma_f32_16x16x32_bf16 v[42:45], v[188:191], v[164:167], v[42:45]
	v_mfma_f32_16x16x32_bf16 v[38:41], v[196:199], v[156:159], v[38:41]
	v_mfma_f32_16x16x32_bf16 v[34:37], v[196:199], v[164:167], v[34:37]
	v_mfma_f32_16x16x32_bf16 v[62:65], v[176:179], v[160:163], v[62:65]
	v_mfma_f32_16x16x32_bf16 v[58:61], v[176:179], v[168:171], v[58:61]
	v_mfma_f32_16x16x32_bf16 v[54:57], v[184:187], v[160:163], v[54:57]
	v_mfma_f32_16x16x32_bf16 v[50:53], v[184:187], v[168:171], v[50:53]
	v_mfma_f32_16x16x32_bf16 v[46:49], v[192:195], v[160:163], v[46:49]
	v_mfma_f32_16x16x32_bf16 v[42:45], v[192:195], v[168:171], v[42:45]
	v_mfma_f32_16x16x32_bf16 v[38:41], v[200:203], v[160:163], v[38:41]
	v_mfma_f32_16x16x32_bf16 v[34:37], v[200:203], v[168:171], v[34:37]
	s_barrier
	v_readfirstlane_b32 s15, v143
	s_mov_b32 m0, s15
	v_readfirstlane_b32 s15, v144
	buffer_load_dwordx4 v137, s[4:7], s3 offen lds
	s_mov_b32 m0, s15
	s_nop 0
	buffer_load_dwordx4 v136, s[4:7], s3 offen lds
	s_waitcnt vmcnt(6)
	s_barrier
	v_mfma_f32_16x16x32_bf16 v[30:33], v[172:175], v[204:207], v[30:33]
	v_mfma_f32_16x16x32_bf16 v[26:29], v[172:175], v[212:215], v[26:29]
	v_mfma_f32_16x16x32_bf16 v[22:25], v[180:183], v[204:207], v[22:25]
	v_mfma_f32_16x16x32_bf16 v[18:21], v[180:183], v[212:215], v[18:21]
	v_mfma_f32_16x16x32_bf16 v[14:17], v[188:191], v[204:207], v[14:17]
	v_mfma_f32_16x16x32_bf16 v[10:13], v[188:191], v[212:215], v[10:13]
	v_mfma_f32_16x16x32_bf16 v[6:9], v[196:199], v[204:207], v[6:9]
	v_mfma_f32_16x16x32_bf16 v[2:5], v[196:199], v[212:215], v[2:5]
	v_mfma_f32_16x16x32_bf16 v[30:33], v[176:179], v[208:211], v[30:33]
	v_mfma_f32_16x16x32_bf16 v[26:29], v[176:179], v[216:219], v[26:29]
	v_mfma_f32_16x16x32_bf16 v[22:25], v[184:187], v[208:211], v[22:25]
	v_mfma_f32_16x16x32_bf16 v[18:21], v[184:187], v[216:219], v[18:21]
	v_mfma_f32_16x16x32_bf16 v[14:17], v[192:195], v[208:211], v[14:17]
	v_mfma_f32_16x16x32_bf16 v[10:13], v[192:195], v[216:219], v[10:13]
	v_mfma_f32_16x16x32_bf16 v[6:9], v[200:203], v[208:211], v[6:9]
	v_mfma_f32_16x16x32_bf16 v[2:5], v[200:203], v[216:219], v[2:5]
	s_add_i32 s2, s2, 2
	s_addk_i32 s3, 0x100
	s_cmp_lt_u32 s2, 28
	s_barrier
	s_cbranch_scc1 .LBB0_162
	v_readfirstlane_b32 s2, v150
	s_mov_b32 m0, s2
	s_mov_b32 s3, 0x80f80
	v_readfirstlane_b32 s2, v149
	ds_read_b128 v[138:141], v148
	ds_read_b128 v[152:155], v148 offset:1024
	ds_read_b128 v[156:159], v148 offset:2048
	ds_read_b128 v[160:163], v148 offset:3072
	ds_read_b128 v[164:167], v133
	ds_read_b128 v[168:171], v133 offset:1024
	ds_read_b128 v[172:175], v132
	ds_read_b128 v[176:179], v132 offset:1024
	ds_read_b128 v[180:183], v131
	ds_read_b128 v[184:187], v131 offset:1024
	ds_read_b128 v[188:191], v130
	ds_read_b128 v[192:195], v130 offset:1024
	buffer_load_dwordx4 v137, s[88:91], s3 offen lds
	s_mov_b32 m0, s2
	s_nop 0
	buffer_load_dwordx4 v136, s[88:91], s3 offen lds
	s_barrier
	s_waitcnt lgkmcnt(0)
	v_mfma_f32_16x16x32_bf16 v[126:129], v[164:167], v[138:141], v[126:129]
	v_mfma_f32_16x16x32_bf16 v[118:121], v[172:175], v[138:141], v[118:121]
	v_mfma_f32_16x16x32_bf16 v[110:113], v[180:183], v[138:141], v[110:113]
	v_mfma_f32_16x16x32_bf16 v[102:105], v[188:191], v[138:141], v[102:105]
	v_mfma_f32_16x16x32_bf16 v[126:129], v[168:171], v[152:155], v[126:129]
	v_mfma_f32_16x16x32_bf16 v[122:125], v[164:167], v[156:159], v[122:125]
	v_mfma_f32_16x16x32_bf16 v[118:121], v[176:179], v[152:155], v[118:121]
	v_mfma_f32_16x16x32_bf16 v[114:117], v[172:175], v[156:159], v[114:117]
	v_mfma_f32_16x16x32_bf16 v[110:113], v[184:187], v[152:155], v[110:113]
	v_mfma_f32_16x16x32_bf16 v[106:109], v[180:183], v[156:159], v[106:109]
	v_mfma_f32_16x16x32_bf16 v[102:105], v[192:195], v[152:155], v[102:105]
	v_mfma_f32_16x16x32_bf16 v[98:101], v[188:191], v[156:159], v[98:101]
	v_mfma_f32_16x16x32_bf16 v[146:149], v[168:171], v[160:163], v[122:125]
	v_mfma_f32_16x16x32_bf16 v[196:199], v[176:179], v[160:163], v[114:117]
	v_mfma_f32_16x16x32_bf16 v[200:203], v[184:187], v[160:163], v[106:109]
	v_mfma_f32_16x16x32_bf16 v[204:207], v[192:195], v[160:163], v[98:101]
	s_barrier
	s_nop 1
	ds_read_b128 v[98:101], v145
	ds_read_b128 v[106:109], v145 offset:1024
	ds_read_b128 v[114:117], v145 offset:2048
	ds_read_b128 v[122:125], v145 offset:3072
	s_barrier
	s_waitcnt lgkmcnt(0)
	v_mfma_f32_16x16x32_bf16 v[94:97], v[164:167], v[98:101], v[94:97]
	v_mfma_f32_16x16x32_bf16 v[90:93], v[164:167], v[114:117], v[90:93]
	v_mfma_f32_16x16x32_bf16 v[86:89], v[172:175], v[98:101], v[86:89]
	v_mfma_f32_16x16x32_bf16 v[82:85], v[172:175], v[114:117], v[82:85]
	v_mfma_f32_16x16x32_bf16 v[78:81], v[180:183], v[98:101], v[78:81]
	v_mfma_f32_16x16x32_bf16 v[74:77], v[180:183], v[114:117], v[74:77]
	v_mfma_f32_16x16x32_bf16 v[70:73], v[188:191], v[98:101], v[70:73]
	v_mfma_f32_16x16x32_bf16 v[66:69], v[188:191], v[114:117], v[66:69]
	v_mfma_f32_16x16x32_bf16 v[94:97], v[168:171], v[106:109], v[94:97]
	v_mfma_f32_16x16x32_bf16 v[90:93], v[168:171], v[122:125], v[90:93]
	v_mfma_f32_16x16x32_bf16 v[86:89], v[176:179], v[106:109], v[86:89]
	v_mfma_f32_16x16x32_bf16 v[82:85], v[176:179], v[122:125], v[82:85]
	v_mfma_f32_16x16x32_bf16 v[78:81], v[184:187], v[106:109], v[78:81]
	v_mfma_f32_16x16x32_bf16 v[74:77], v[184:187], v[122:125], v[74:77]
	v_mfma_f32_16x16x32_bf16 v[70:73], v[192:195], v[106:109], v[70:73]
	v_mfma_f32_16x16x32_bf16 v[66:69], v[192:195], v[122:125], v[66:69]
	s_barrier
; #define WAIT_V(n) asm volatile("s_waitcnt vmcnt(" #n ")" ::: "memory")
; #define WAIT_L(n) asm volatile("s_waitcnt lgkmcnt(" #n ")" ::: "memory")
; #define BAR __builtin_amdgcn_s_barrier()
; __device__ __forceinline__ void mainloop_8phase(const u16* __restrict__ A, const u16* __restrict__ Bt, int K,
;                                                 f32x4 (&acc)[2][2][4][2], int wid_s, int ld) {
;     ...
;     LDA(At, 0, 1); WAIT_V(4); BAR; WAIT_L(0); MMA(1, 0, At, B0); MMA(1, 1, At, B1); BAR; }
;   { LDB(B0, 1, 0); LDA(At, 1, 0); WAIT_V(2); BAR; WAIT_L(0); MMA(0, 0, At, B0); BAR;
	ds_read_b128 v[142:145], v133 offset:16384
	ds_read_b128 v[164:167], v133 offset:17408
	ds_read_b128 v[168:171], v132 offset:16384
	ds_read_b128 v[172:175], v132 offset:17408
	ds_read_b128 v[176:179], v131 offset:16384
	ds_read_b128 v[180:183], v131 offset:17408
	ds_read_b128 v[184:187], v130 offset:16384
	ds_read_b128 v[188:191], v130 offset:17408
	s_waitcnt vmcnt(4)
	s_barrier
	s_waitcnt lgkmcnt(0)
	v_mfma_f32_16x16x32_bf16 v[62:65], v[142:145], v[138:141], v[62:65]
	v_mfma_f32_16x16x32_bf16 v[58:61], v[142:145], v[156:159], v[58:61]
	v_mfma_f32_16x16x32_bf16 v[54:57], v[168:171], v[138:141], v[54:57]
	v_mfma_f32_16x16x32_bf16 v[50:53], v[168:171], v[156:159], v[50:53]
	v_mfma_f32_16x16x32_bf16 v[46:49], v[176:179], v[138:141], v[46:49]
	v_mfma_f32_16x16x32_bf16 v[42:45], v[176:179], v[156:159], v[42:45]
	v_mfma_f32_16x16x32_bf16 v[38:41], v[184:187], v[138:141], v[38:41]
	v_mfma_f32_16x16x32_bf16 v[34:37], v[184:187], v[156:159], v[34:37]
	v_mfma_f32_16x16x32_bf16 v[192:195], v[164:167], v[152:155], v[62:65]
	v_mfma_f32_16x16x32_bf16 v[208:211], v[164:167], v[160:163], v[58:61]
	v_mfma_f32_16x16x32_bf16 v[212:215], v[172:175], v[152:155], v[54:57]
	v_mfma_f32_16x16x32_bf16 v[216:219], v[172:175], v[160:163], v[50:53]
	v_mfma_f32_16x16x32_bf16 v[220:223], v[180:183], v[152:155], v[46:49]
	v_mfma_f32_16x16x32_bf16 v[224:227], v[180:183], v[160:163], v[42:45]
	v_mfma_f32_16x16x32_bf16 v[136:139], v[188:191], v[152:155], v[38:41]
	v_mfma_f32_16x16x32_bf16 v[150:153], v[188:191], v[160:163], v[34:37]
	v_mfma_f32_16x16x32_bf16 v[30:33], v[142:145], v[98:101], v[30:33]
	v_mfma_f32_16x16x32_bf16 v[22:25], v[168:171], v[98:101], v[22:25]
	v_mfma_f32_16x16x32_bf16 v[14:17], v[176:179], v[98:101], v[14:17]
	v_mfma_f32_16x16x32_bf16 v[6:9], v[184:187], v[98:101], v[6:9]
	v_mfma_f32_16x16x32_bf16 v[30:33], v[164:167], v[106:109], v[30:33]
	v_mfma_f32_16x16x32_bf16 v[26:29], v[142:145], v[114:117], v[26:29]
	v_mfma_f32_16x16x32_bf16 v[22:25], v[172:175], v[106:109], v[22:25]
	v_mfma_f32_16x16x32_bf16 v[18:21], v[168:171], v[114:117], v[18:21]
	v_mfma_f32_16x16x32_bf16 v[14:17], v[180:183], v[106:109], v[14:17]
	v_mfma_f32_16x16x32_bf16 v[10:13], v[176:179], v[114:117], v[10:13]
	v_mfma_f32_16x16x32_bf16 v[6:9], v[188:191], v[106:109], v[6:9]
	v_mfma_f32_16x16x32_bf16 v[2:5], v[184:187], v[114:117], v[2:5]
	v_mfma_f32_16x16x32_bf16 v[140:143], v[164:167], v[122:125], v[26:29]
	v_mfma_f32_16x16x32_bf16 v[154:157], v[172:175], v[122:125], v[18:21]
	v_mfma_f32_16x16x32_bf16 v[158:161], v[180:183], v[122:125], v[10:13]
	v_mfma_f32_16x16x32_bf16 v[162:165], v[188:191], v[122:125], v[2:5]
	s_barrier
	s_nop 1
	ds_read_b128 v[2:5], v135
	ds_read_b128 v[166:169], v135 offset:1024
	ds_read_b128 v[170:173], v135 offset:2048
	ds_read_b128 v[174:177], v135 offset:3072
	ds_read_b128 v[10:13], v133 offset:32768
	ds_read_b128 v[18:21], v133 offset:33792
	ds_read_b128 v[26:29], v132 offset:32768
	ds_read_b128 v[38:41], v132 offset:33792
	ds_read_b128 v[46:49], v131 offset:32768
	ds_read_b128 v[178:181], v131 offset:33792
	ds_read_b128 v[182:185], v130 offset:32768
	ds_read_b128 v[186:189], v130 offset:33792
	s_waitcnt vmcnt(2)
	s_barrier
	s_waitcnt lgkmcnt(0)
	v_mfma_f32_16x16x32_bf16 v[34:37], v[10:13], v[2:5], v[126:129]
	v_mfma_f32_16x16x32_bf16 v[122:125], v[18:21], v[166:169], v[34:37]
	v_mfma_f32_16x16x32_bf16 v[34:37], v[10:13], v[170:173], v[146:149]
	v_mfma_f32_16x16x32_bf16 v[58:61], v[18:21], v[174:177], v[34:37]
	v_mfma_f32_16x16x32_bf16 v[34:37], v[26:29], v[2:5], v[118:121]
	v_mfma_f32_16x16x32_bf16 v[114:117], v[38:41], v[166:169], v[34:37]
	v_mfma_f32_16x16x32_bf16 v[34:37], v[26:29], v[170:173], v[196:199]
	v_mfma_f32_16x16x32_bf16 v[50:53], v[38:41], v[174:177], v[34:37]
	v_mfma_f32_16x16x32_bf16 v[34:37], v[46:49], v[2:5], v[110:113]
	v_mfma_f32_16x16x32_bf16 v[106:109], v[178:181], v[166:169], v[34:37]
	v_mfma_f32_16x16x32_bf16 v[34:37], v[46:49], v[170:173], v[200:203]
	v_mfma_f32_16x16x32_bf16 v[42:45], v[178:181], v[174:177], v[34:37]
	v_mfma_f32_16x16x32_bf16 v[34:37], v[182:185], v[2:5], v[102:105]
	v_mfma_f32_16x16x32_bf16 v[98:101], v[186:189], v[166:169], v[34:37]
	v_mfma_f32_16x16x32_bf16 v[34:37], v[182:185], v[170:173], v[204:207]
	v_mfma_f32_16x16x32_bf16 v[34:37], v[186:189], v[174:177], v[34:37]
	s_barrier
; #define WAIT_V(n) asm volatile("s_waitcnt vmcnt(" #n ")" ::: "memory")
; #define WAIT_L(n) asm volatile("s_waitcnt lgkmcnt(" #n ")" ::: "memory")
; #define BAR __builtin_amdgcn_s_barrier()
; __device__ __forceinline__ void mainloop_8phase(const u16* __restrict__ A, const u16* __restrict__ Bt, int K,
;                                                 f32x4 (&acc)[2][2][4][2], int wid_s, int ld) {
;     ...
;     LDB(B1, 1, 1); WAIT_V(0); BAR; WAIT_L(0); MMA(0, 1, At, B1); BAR;
;     LDA(At, 1, 1); BAR; WAIT_L(0); MMA(1, 0, At, B0); MMA(1, 1, At, B1); BAR; }
;   if (wr == 0) BAR;
	ds_read_b128 v[144:147], v134
	ds_read_b128 v[196:199], v134 offset:1024
	ds_read_b128 v[200:203], v134 offset:2048
	ds_read_b128 v[204:207], v134 offset:3072
	s_waitcnt vmcnt(0)
	s_barrier
	s_waitcnt lgkmcnt(0)
	v_mfma_f32_16x16x32_bf16 v[54:57], v[10:13], v[144:147], v[94:97]
	v_mfma_f32_16x16x32_bf16 v[10:13], v[10:13], v[200:203], v[90:93]
	v_mfma_f32_16x16x32_bf16 v[62:65], v[18:21], v[204:207], v[10:13]
	v_mfma_f32_16x16x32_bf16 v[10:13], v[26:29], v[144:147], v[86:89]
	v_mfma_f32_16x16x32_bf16 v[118:121], v[38:41], v[196:199], v[10:13]
	v_mfma_f32_16x16x32_bf16 v[10:13], v[26:29], v[200:203], v[82:85]
	v_mfma_f32_16x16x32_bf16 v[126:129], v[18:21], v[196:199], v[54:57]
	v_mfma_f32_16x16x32_bf16 v[54:57], v[38:41], v[204:207], v[10:13]
	v_mfma_f32_16x16x32_bf16 v[10:13], v[46:49], v[144:147], v[78:81]
	v_mfma_f32_16x16x32_bf16 v[110:113], v[178:181], v[196:199], v[10:13]
	v_mfma_f32_16x16x32_bf16 v[10:13], v[46:49], v[200:203], v[74:77]
	v_mfma_f32_16x16x32_bf16 v[46:49], v[178:181], v[204:207], v[10:13]
	v_mfma_f32_16x16x32_bf16 v[10:13], v[182:185], v[144:147], v[70:73]
	v_mfma_f32_16x16x32_bf16 v[102:105], v[186:189], v[196:199], v[10:13]
	v_mfma_f32_16x16x32_bf16 v[10:13], v[182:185], v[200:203], v[66:69]
	v_mfma_f32_16x16x32_bf16 v[38:41], v[186:189], v[204:207], v[10:13]
	s_barrier
	ds_read_b128 v[70:73], v133 offset:49152
	ds_read_b128 v[78:81], v133 offset:50176
	ds_read_b128 v[178:181], v132 offset:49152
	ds_read_b128 v[132:135], v132 offset:50176
	ds_read_b128 v[182:185], v131 offset:49152
	ds_read_b128 v[186:189], v131 offset:50176
	ds_read_b128 v[228:231], v130 offset:49152
	ds_read_b128 v[232:235], v130 offset:50176
	s_barrier
	s_waitcnt lgkmcnt(0)
	v_mfma_f32_16x16x32_bf16 v[10:13], v[70:73], v[2:5], v[192:195]
	v_mfma_f32_16x16x32_bf16 v[90:93], v[78:81], v[166:169], v[10:13]
	v_mfma_f32_16x16x32_bf16 v[10:13], v[70:73], v[170:173], v[208:211]
	v_mfma_f32_16x16x32_bf16 v[26:29], v[78:81], v[174:177], v[10:13]
	v_mfma_f32_16x16x32_bf16 v[10:13], v[178:181], v[2:5], v[212:215]
	v_mfma_f32_16x16x32_bf16 v[82:85], v[132:135], v[166:169], v[10:13]
	v_mfma_f32_16x16x32_bf16 v[10:13], v[178:181], v[170:173], v[216:219]
	v_mfma_f32_16x16x32_bf16 v[18:21], v[132:135], v[174:177], v[10:13]
	v_mfma_f32_16x16x32_bf16 v[10:13], v[182:185], v[2:5], v[220:223]
	v_mfma_f32_16x16x32_bf16 v[2:5], v[228:231], v[2:5], v[136:139]
	v_mfma_f32_16x16x32_bf16 v[74:77], v[186:189], v[166:169], v[10:13]
	v_mfma_f32_16x16x32_bf16 v[10:13], v[182:185], v[170:173], v[224:227]
	v_mfma_f32_16x16x32_bf16 v[66:69], v[232:235], v[166:169], v[2:5]
	v_mfma_f32_16x16x32_bf16 v[2:5], v[228:231], v[170:173], v[150:153]
	v_mfma_f32_16x16x32_bf16 v[10:13], v[186:189], v[174:177], v[10:13]
	v_mfma_f32_16x16x32_bf16 v[2:5], v[232:235], v[174:177], v[2:5]
	v_mfma_f32_16x16x32_bf16 v[30:33], v[70:73], v[144:147], v[30:33]
	v_mfma_f32_16x16x32_bf16 v[94:97], v[78:81], v[196:199], v[30:33]
	v_mfma_f32_16x16x32_bf16 v[30:33], v[70:73], v[200:203], v[140:143]
	v_mfma_f32_16x16x32_bf16 v[22:25], v[178:181], v[144:147], v[22:25]
	v_mfma_f32_16x16x32_bf16 v[14:17], v[182:185], v[144:147], v[14:17]
	v_mfma_f32_16x16x32_bf16 v[6:9], v[228:231], v[144:147], v[6:9]
	v_mfma_f32_16x16x32_bf16 v[30:33], v[78:81], v[204:207], v[30:33]
	v_mfma_f32_16x16x32_bf16 v[86:89], v[132:135], v[196:199], v[22:25]
	v_mfma_f32_16x16x32_bf16 v[22:25], v[178:181], v[200:203], v[154:157]
	v_mfma_f32_16x16x32_bf16 v[78:81], v[186:189], v[196:199], v[14:17]
	v_mfma_f32_16x16x32_bf16 v[14:17], v[182:185], v[200:203], v[158:161]
	v_mfma_f32_16x16x32_bf16 v[70:73], v[232:235], v[196:199], v[6:9]
	v_mfma_f32_16x16x32_bf16 v[6:9], v[228:231], v[200:203], v[162:165]
	v_mfma_f32_16x16x32_bf16 v[22:25], v[132:135], v[204:207], v[22:25]
	v_mfma_f32_16x16x32_bf16 v[14:17], v[186:189], v[204:207], v[14:17]
	v_mfma_f32_16x16x32_bf16 v[6:9], v[232:235], v[204:207], v[6:9]
	s_movk_i32 s2, 0x100
	v_cmp_gt_u32_e32 vcc, s2, v0
	s_barrier
	s_and_saveexec_b64 s[2:3], vcc
	s_cbranch_execz .LBB0_165
	s_barrier

; #define WAIT_V(n) asm volatile("s_waitcnt vmcnt(" #n ")" ::: "memory")
; #define WAIT_L(n) asm volatile("s_waitcnt lgkmcnt(" #n ")" ::: "memory")
; #define BAR __builtin_amdgcn_s_barrier()
; #define SCHED __builtin_amdgcn_sched_barrier(0)
; __device__ __forceinline__ void mainloop_8phase(const u16* __restrict__ A, const u16* __restrict__ Bt, int K,
;                                                 f32x4 (&acc)[2][2][4][2], int wid_s, int ld) {
;     ...
;     LDB(B0, 0, 0); SCHED; LDA(At, 0, 0); STAGE(SA(1, 1), A, brow + G_HALF, t + 1);
;     WAIT_L(8); BAR; WAIT_L(0); MMA(0, 0, At, B0); BAR; SCHED;
;     LDB(B1, 0, 1); STAGE(SB(0, 0), Bt, bcol, t + 2);
;     BAR; WAIT_L(0); MMA(0, 1, At, B1); BAR;
;     LDA(At, 0, 1); STAGE(SA(0, 0), A, brow, t + 2);
;     BAR; WAIT_L(0); MMA(1, 0, At, B0); BAR; SCHED;
;     STAGE(SB(0, 1), Bt, bcol + G_HALF, t + 2);
;     WAIT_V(6); BAR; MMA(1, 1, At, B1); BAR;
.LBB0_247:
	ds_read_b128 v[156:159], v155
	ds_read_b128 v[160:163], v155 offset:1024
	ds_read_b128 v[164:167], v155 offset:2048
	ds_read_b128 v[168:171], v155 offset:3072
	v_readfirstlane_b32 s6, v145
	s_add_i32 s3, s1, 0xffffff00
	s_mov_b32 m0, s6
	v_readfirstlane_b32 s6, v144
	ds_read_b128 v[172:175], v133
	ds_read_b128 v[176:179], v133 offset:1024
	ds_read_b128 v[180:183], v132
	ds_read_b128 v[184:187], v132 offset:1024
	ds_read_b128 v[188:191], v131
	ds_read_b128 v[192:195], v131 offset:1024
	ds_read_b128 v[196:199], v130
	ds_read_b128 v[200:203], v130 offset:1024
	buffer_load_dwordx4 v137, s[88:91], s3 offen lds
	s_mov_b32 m0, s6
	s_nop 0
	buffer_load_dwordx4 v136, s[88:91], s3 offen lds
	s_waitcnt lgkmcnt(8)
	s_barrier
	s_waitcnt lgkmcnt(0)
	v_mfma_f32_16x16x32_bf16 v[126:129], v[172:175], v[156:159], v[126:129]
	v_mfma_f32_16x16x32_bf16 v[122:125], v[172:175], v[164:167], v[122:125]
	v_mfma_f32_16x16x32_bf16 v[118:121], v[180:183], v[156:159], v[118:121]
	v_mfma_f32_16x16x32_bf16 v[114:117], v[180:183], v[164:167], v[114:117]
	v_mfma_f32_16x16x32_bf16 v[110:113], v[188:191], v[156:159], v[110:113]
	v_mfma_f32_16x16x32_bf16 v[106:109], v[188:191], v[164:167], v[106:109]
	v_mfma_f32_16x16x32_bf16 v[102:105], v[196:199], v[156:159], v[102:105]
	v_mfma_f32_16x16x32_bf16 v[98:101], v[196:199], v[164:167], v[98:101]
	v_mfma_f32_16x16x32_bf16 v[126:129], v[176:179], v[160:163], v[126:129]
	v_mfma_f32_16x16x32_bf16 v[122:125], v[176:179], v[168:171], v[122:125]
	v_mfma_f32_16x16x32_bf16 v[118:121], v[184:187], v[160:163], v[118:121]
	v_mfma_f32_16x16x32_bf16 v[114:117], v[184:187], v[168:171], v[114:117]
	v_mfma_f32_16x16x32_bf16 v[110:113], v[192:195], v[160:163], v[110:113]
	v_mfma_f32_16x16x32_bf16 v[106:109], v[192:195], v[168:171], v[106:109]
	v_mfma_f32_16x16x32_bf16 v[102:105], v[200:203], v[160:163], v[102:105]
	v_mfma_f32_16x16x32_bf16 v[98:101], v[200:203], v[168:171], v[98:101]
	s_barrier
	v_readfirstlane_b32 s14, v148
	s_add_i32 s3, s1, 0xfff7ff80
	s_mov_b32 s6, s90
	s_mov_b32 s7, s91
	s_mov_b32 m0, s14
	v_readfirstlane_b32 s14, v149
	ds_read_b128 v[204:207], v147
	ds_read_b128 v[208:211], v147 offset:1024
	ds_read_b128 v[212:215], v147 offset:2048
	ds_read_b128 v[216:219], v147 offset:3072
	buffer_load_dwordx4 v137, s[4:7], s3 offen lds
	s_mov_b32 m0, s14
	s_nop 0
	buffer_load_dwordx4 v136, s[4:7], s3 offen lds
	s_barrier
	s_waitcnt lgkmcnt(0)
	v_mfma_f32_16x16x32_bf16 v[94:97], v[172:175], v[204:207], v[94:97]
	v_mfma_f32_16x16x32_bf16 v[90:93], v[172:175], v[212:215], v[90:93]
	v_mfma_f32_16x16x32_bf16 v[86:89], v[180:183], v[204:207], v[86:89]
	v_mfma_f32_16x16x32_bf16 v[82:85], v[180:183], v[212:215], v[82:85]
	v_mfma_f32_16x16x32_bf16 v[78:81], v[188:191], v[204:207], v[78:81]
	v_mfma_f32_16x16x32_bf16 v[74:77], v[188:191], v[212:215], v[74:77]
	v_mfma_f32_16x16x32_bf16 v[70:73], v[196:199], v[204:207], v[70:73]
	v_mfma_f32_16x16x32_bf16 v[66:69], v[196:199], v[212:215], v[66:69]
	v_mfma_f32_16x16x32_bf16 v[94:97], v[176:179], v[208:211], v[94:97]
	v_mfma_f32_16x16x32_bf16 v[90:93], v[176:179], v[216:219], v[90:93]
	v_mfma_f32_16x16x32_bf16 v[86:89], v[184:187], v[208:211], v[86:89]
	v_mfma_f32_16x16x32_bf16 v[82:85], v[184:187], v[216:219], v[82:85]
	v_mfma_f32_16x16x32_bf16 v[78:81], v[192:195], v[208:211], v[78:81]
	v_mfma_f32_16x16x32_bf16 v[74:77], v[192:195], v[216:219], v[74:77]
	v_mfma_f32_16x16x32_bf16 v[70:73], v[200:203], v[208:211], v[70:73]
	v_mfma_f32_16x16x32_bf16 v[66:69], v[200:203], v[216:219], v[66:69]
	v_readfirstlane_b32 s14, v140
	s_mov_b32 m0, s14
	v_readfirstlane_b32 s14, v150
	s_barrier
	ds_read_b128 v[172:175], v133 offset:16384
	ds_read_b128 v[176:179], v133 offset:17408
	ds_read_b128 v[180:183], v132 offset:16384
	ds_read_b128 v[184:187], v132 offset:17408
	ds_read_b128 v[188:191], v131 offset:16384
	ds_read_b128 v[192:195], v131 offset:17408
	ds_read_b128 v[196:199], v130 offset:16384
	ds_read_b128 v[200:203], v130 offset:17408
	buffer_load_dwordx4 v137, s[88:91], s3 offen lds
	s_mov_b32 m0, s14
	s_nop 0
	buffer_load_dwordx4 v136, s[88:91], s3 offen lds
	s_barrier
	s_waitcnt lgkmcnt(0)
	v_mfma_f32_16x16x32_bf16 v[62:65], v[172:175], v[156:159], v[62:65]
	v_mfma_f32_16x16x32_bf16 v[58:61], v[172:175], v[164:167], v[58:61]
	v_mfma_f32_16x16x32_bf16 v[54:57], v[180:183], v[156:159], v[54:57]
	v_mfma_f32_16x16x32_bf16 v[50:53], v[180:183], v[164:167], v[50:53]
	v_mfma_f32_16x16x32_bf16 v[46:49], v[188:191], v[156:159], v[46:49]
	v_mfma_f32_16x16x32_bf16 v[42:45], v[188:191], v[164:167], v[42:45]
	v_mfma_f32_16x16x32_bf16 v[38:41], v[196:199], v[156:159], v[38:41]
	v_mfma_f32_16x16x32_bf16 v[34:37], v[196:199], v[164:167], v[34:37]
	v_mfma_f32_16x16x32_bf16 v[62:65], v[176:179], v[160:163], v[62:65]
	v_mfma_f32_16x16x32_bf16 v[58:61], v[176:179], v[168:171], v[58:61]
	v_mfma_f32_16x16x32_bf16 v[54:57], v[184:187], v[160:163], v[54:57]
	v_mfma_f32_16x16x32_bf16 v[50:53], v[184:187], v[168:171], v[50:53]
	v_mfma_f32_16x16x32_bf16 v[46:49], v[192:195], v[160:163], v[46:49]
	v_mfma_f32_16x16x32_bf16 v[42:45], v[192:195], v[168:171], v[42:45]
	v_mfma_f32_16x16x32_bf16 v[38:41], v[200:203], v[160:163], v[38:41]
	v_mfma_f32_16x16x32_bf16 v[34:37], v[200:203], v[168:171], v[34:37]
	s_barrier
	v_readfirstlane_b32 s14, v151
	s_add_i32 s3, s1, 0xffffff80
	s_mov_b32 m0, s14
	v_readfirstlane_b32 s14, v152
	buffer_load_dwordx4 v137, s[4:7], s3 offen lds
	s_mov_b32 m0, s14
	s_nop 0
	buffer_load_dwordx4 v136, s[4:7], s3 offen lds
	s_waitcnt vmcnt(6)
	s_barrier
; #define WAIT_V(n) asm volatile("s_waitcnt vmcnt(" #n ")" ::: "memory")
; #define WAIT_L(n) asm volatile("s_waitcnt lgkmcnt(" #n ")" ::: "memory")
; #define BAR __builtin_amdgcn_s_barrier()
; #define SCHED __builtin_amdgcn_sched_barrier(0)
; __device__ __forceinline__ void mainloop_8phase(const u16* __restrict__ A, const u16* __restrict__ Bt, int K,
;                                                 f32x4 (&acc)[2][2][4][2], int wid_s, int ld) {
;     ...
;     WAIT_V(6); BAR; MMA(1, 1, At, B1); BAR;
;     LDB(B0, 1, 0); SCHED; LDA(At, 1, 0); STAGE(SA(0, 1), A, brow + G_HALF, t + 2);
;     WAIT_L(8); BAR; WAIT_L(0); MMA(0, 0, At, B0); BAR; SCHED;
;     LDB(B1, 1, 1); STAGE(SB(1, 0), Bt, bcol, t + 3);
;     BAR; WAIT_L(0); MMA(0, 1, At, B1); BAR;
;     LDA(At, 1, 1); STAGE(SA(1, 0), A, brow, t + 3);
	v_mfma_f32_16x16x32_bf16 v[30:33], v[172:175], v[204:207], v[30:33]
	v_mfma_f32_16x16x32_bf16 v[26:29], v[172:175], v[212:215], v[26:29]
	v_mfma_f32_16x16x32_bf16 v[22:25], v[180:183], v[204:207], v[22:25]
	v_mfma_f32_16x16x32_bf16 v[18:21], v[180:183], v[212:215], v[18:21]
	v_mfma_f32_16x16x32_bf16 v[14:17], v[188:191], v[204:207], v[14:17]
	v_mfma_f32_16x16x32_bf16 v[10:13], v[188:191], v[212:215], v[10:13]
	v_mfma_f32_16x16x32_bf16 v[6:9], v[196:199], v[204:207], v[6:9]
	v_mfma_f32_16x16x32_bf16 v[2:5], v[196:199], v[212:215], v[2:5]
	v_mfma_f32_16x16x32_bf16 v[30:33], v[176:179], v[208:211], v[30:33]
	v_mfma_f32_16x16x32_bf16 v[26:29], v[176:179], v[216:219], v[26:29]
	v_mfma_f32_16x16x32_bf16 v[22:25], v[184:187], v[208:211], v[22:25]
	v_mfma_f32_16x16x32_bf16 v[18:21], v[184:187], v[216:219], v[18:21]
	v_mfma_f32_16x16x32_bf16 v[14:17], v[192:195], v[208:211], v[14:17]
	v_mfma_f32_16x16x32_bf16 v[10:13], v[192:195], v[216:219], v[10:13]
	v_mfma_f32_16x16x32_bf16 v[6:9], v[200:203], v[208:211], v[6:9]
	v_mfma_f32_16x16x32_bf16 v[2:5], v[200:203], v[216:219], v[2:5]
	s_barrier
	ds_read_b128 v[156:159], v135
	ds_read_b128 v[160:163], v135 offset:1024
	ds_read_b128 v[164:167], v135 offset:2048
	ds_read_b128 v[168:171], v135 offset:3072
	v_readfirstlane_b32 s14, v153
	s_mov_b32 m0, s14
	v_readfirstlane_b32 s14, v154
	ds_read_b128 v[172:175], v133 offset:32768
	ds_read_b128 v[176:179], v133 offset:33792
	ds_read_b128 v[180:183], v132 offset:32768
	ds_read_b128 v[184:187], v132 offset:33792
	ds_read_b128 v[188:191], v131 offset:32768
	ds_read_b128 v[192:195], v131 offset:33792
	ds_read_b128 v[196:199], v130 offset:32768
	ds_read_b128 v[200:203], v130 offset:33792
	buffer_load_dwordx4 v137, s[88:91], s3 offen lds
	s_mov_b32 m0, s14
	s_nop 0
	buffer_load_dwordx4 v136, s[88:91], s3 offen lds
	s_waitcnt lgkmcnt(8)
	s_barrier
	s_waitcnt lgkmcnt(0)
	v_mfma_f32_16x16x32_bf16 v[126:129], v[172:175], v[156:159], v[126:129]
	v_mfma_f32_16x16x32_bf16 v[122:125], v[172:175], v[164:167], v[122:125]
	v_mfma_f32_16x16x32_bf16 v[118:121], v[180:183], v[156:159], v[118:121]
	v_mfma_f32_16x16x32_bf16 v[114:117], v[180:183], v[164:167], v[114:117]
	v_mfma_f32_16x16x32_bf16 v[110:113], v[188:191], v[156:159], v[110:113]
	v_mfma_f32_16x16x32_bf16 v[106:109], v[188:191], v[164:167], v[106:109]
	v_mfma_f32_16x16x32_bf16 v[102:105], v[196:199], v[156:159], v[102:105]
	v_mfma_f32_16x16x32_bf16 v[98:101], v[196:199], v[164:167], v[98:101]
	v_mfma_f32_16x16x32_bf16 v[126:129], v[176:179], v[160:163], v[126:129]
	v_mfma_f32_16x16x32_bf16 v[122:125], v[176:179], v[168:171], v[122:125]
	v_mfma_f32_16x16x32_bf16 v[118:121], v[184:187], v[160:163], v[118:121]
	v_mfma_f32_16x16x32_bf16 v[114:117], v[184:187], v[168:171], v[114:117]
	v_mfma_f32_16x16x32_bf16 v[110:113], v[192:195], v[160:163], v[110:113]
	v_mfma_f32_16x16x32_bf16 v[106:109], v[192:195], v[168:171], v[106:109]
	v_mfma_f32_16x16x32_bf16 v[102:105], v[200:203], v[160:163], v[102:105]
	v_mfma_f32_16x16x32_bf16 v[98:101], v[200:203], v[168:171], v[98:101]
	s_barrier
	v_readfirstlane_b32 s14, v138
	s_add_i32 s3, s1, 0xfff80000
	s_mov_b32 m0, s14
	v_readfirstlane_b32 s14, v139
	ds_read_b128 v[204:207], v134
	ds_read_b128 v[208:211], v134 offset:1024
	ds_read_b128 v[212:215], v134 offset:2048
	ds_read_b128 v[216:219], v134 offset:3072
	buffer_load_dwordx4 v137, s[4:7], s3 offen lds
	s_mov_b32 m0, s14
	s_nop 0
	buffer_load_dwordx4 v136, s[4:7], s3 offen lds
	s_barrier
	s_waitcnt lgkmcnt(0)
	v_mfma_f32_16x16x32_bf16 v[94:97], v[172:175], v[204:207], v[94:97]
	v_mfma_f32_16x16x32_bf16 v[90:93], v[172:175], v[212:215], v[90:93]
	v_mfma_f32_16x16x32_bf16 v[86:89], v[180:183], v[204:207], v[86:89]
	v_mfma_f32_16x16x32_bf16 v[82:85], v[180:183], v[212:215], v[82:85]
	v_mfma_f32_16x16x32_bf16 v[78:81], v[188:191], v[204:207], v[78:81]
	v_mfma_f32_16x16x32_bf16 v[74:77], v[188:191], v[212:215], v[74:77]
	v_mfma_f32_16x16x32_bf16 v[70:73], v[196:199], v[204:207], v[70:73]
	v_mfma_f32_16x16x32_bf16 v[66:69], v[196:199], v[212:215], v[66:69]
	v_mfma_f32_16x16x32_bf16 v[94:97], v[176:179], v[208:211], v[94:97]
	v_mfma_f32_16x16x32_bf16 v[90:93], v[176:179], v[216:219], v[90:93]
	v_mfma_f32_16x16x32_bf16 v[86:89], v[184:187], v[208:211], v[86:89]
	v_mfma_f32_16x16x32_bf16 v[82:85], v[184:187], v[216:219], v[82:85]
	v_mfma_f32_16x16x32_bf16 v[78:81], v[192:195], v[208:211], v[78:81]
	v_mfma_f32_16x16x32_bf16 v[74:77], v[192:195], v[216:219], v[74:77]
	v_mfma_f32_16x16x32_bf16 v[70:73], v[200:203], v[208:211], v[70:73]
	v_mfma_f32_16x16x32_bf16 v[66:69], v[200:203], v[216:219], v[66:69]
	v_readfirstlane_b32 s14, v141
	s_mov_b32 m0, s14
	v_readfirstlane_b32 s14, v142
	s_barrier
	ds_read_b128 v[172:175], v133 offset:49152
	ds_read_b128 v[176:179], v133 offset:50176
	ds_read_b128 v[180:183], v132 offset:49152
	ds_read_b128 v[184:187], v132 offset:50176
	ds_read_b128 v[188:191], v131 offset:49152
	ds_read_b128 v[192:195], v131 offset:50176
	ds_read_b128 v[196:199], v130 offset:49152
	ds_read_b128 v[200:203], v130 offset:50176
	buffer_load_dwordx4 v137, s[88:91], s3 offen lds
	s_mov_b32 m0, s14
	s_nop 0
	buffer_load_dwordx4 v136, s[88:91], s3 offen lds
	s_barrier
; #define WAIT_V(n) asm volatile("s_waitcnt vmcnt(" #n ")" ::: "memory")
; #define WAIT_L(n) asm volatile("s_waitcnt lgkmcnt(" #n ")" ::: "memory")
; #define BAR __builtin_amdgcn_s_barrier()
; #define SCHED __builtin_amdgcn_sched_barrier(0)
; __device__ __forceinline__ void mainloop_8phase(const u16* __restrict__ A, const u16* __restrict__ Bt, int K,
;                                                 f32x4 (&acc)[2][2][4][2], int wid_s, int ld) {
;     ...
;     BAR; WAIT_L(0); MMA(1, 0, At, B0); BAR; SCHED;
;     STAGE(SB(1, 1), Bt, bcol + G_HALF, t + 3);
;     WAIT_V(6); BAR; MMA(1, 1, At, B1); BAR;
;   }
;   { LDB(B0, 0, 0); LDA(At, 0, 0); STAGE(SA(1, 1), A, brow + G_HALF, nt - 1);
;     BAR; WAIT_L(0); MMA(0, 0, At, B0); BAR;
;     LDB(B1, 0, 1); BAR; WAIT_L(0); MMA(0, 1, At, B1); BAR;
	s_waitcnt lgkmcnt(0)
	v_mfma_f32_16x16x32_bf16 v[62:65], v[172:175], v[156:159], v[62:65]
	v_mfma_f32_16x16x32_bf16 v[58:61], v[172:175], v[164:167], v[58:61]
	v_mfma_f32_16x16x32_bf16 v[54:57], v[180:183], v[156:159], v[54:57]
	v_mfma_f32_16x16x32_bf16 v[50:53], v[180:183], v[164:167], v[50:53]
	v_mfma_f32_16x16x32_bf16 v[46:49], v[188:191], v[156:159], v[46:49]
	v_mfma_f32_16x16x32_bf16 v[42:45], v[188:191], v[164:167], v[42:45]
	v_mfma_f32_16x16x32_bf16 v[38:41], v[196:199], v[156:159], v[38:41]
	v_mfma_f32_16x16x32_bf16 v[34:37], v[196:199], v[164:167], v[34:37]
	v_mfma_f32_16x16x32_bf16 v[62:65], v[176:179], v[160:163], v[62:65]
	v_mfma_f32_16x16x32_bf16 v[58:61], v[176:179], v[168:171], v[58:61]
	v_mfma_f32_16x16x32_bf16 v[54:57], v[184:187], v[160:163], v[54:57]
	v_mfma_f32_16x16x32_bf16 v[50:53], v[184:187], v[168:171], v[50:53]
	v_mfma_f32_16x16x32_bf16 v[46:49], v[192:195], v[160:163], v[46:49]
	v_mfma_f32_16x16x32_bf16 v[42:45], v[192:195], v[168:171], v[42:45]
	v_mfma_f32_16x16x32_bf16 v[38:41], v[200:203], v[160:163], v[38:41]
	v_mfma_f32_16x16x32_bf16 v[34:37], v[200:203], v[168:171], v[34:37]
	s_barrier
	v_readfirstlane_b32 s3, v143
	s_mov_b32 m0, s3
	v_readfirstlane_b32 s3, v146
	buffer_load_dwordx4 v137, s[4:7], s1 offen lds
	s_mov_b32 m0, s3
	s_nop 0
	buffer_load_dwordx4 v136, s[4:7], s1 offen lds
	s_waitcnt vmcnt(6)
	s_barrier
	v_mfma_f32_16x16x32_bf16 v[30:33], v[172:175], v[204:207], v[30:33]
	v_mfma_f32_16x16x32_bf16 v[26:29], v[172:175], v[212:215], v[26:29]
	v_mfma_f32_16x16x32_bf16 v[22:25], v[180:183], v[204:207], v[22:25]
	v_mfma_f32_16x16x32_bf16 v[18:21], v[180:183], v[212:215], v[18:21]
	v_mfma_f32_16x16x32_bf16 v[14:17], v[188:191], v[204:207], v[14:17]
	v_mfma_f32_16x16x32_bf16 v[10:13], v[188:191], v[212:215], v[10:13]
	v_mfma_f32_16x16x32_bf16 v[6:9], v[196:199], v[204:207], v[6:9]
	v_mfma_f32_16x16x32_bf16 v[2:5], v[196:199], v[212:215], v[2:5]
	v_mfma_f32_16x16x32_bf16 v[30:33], v[176:179], v[208:211], v[30:33]
	v_mfma_f32_16x16x32_bf16 v[26:29], v[176:179], v[216:219], v[26:29]
	v_mfma_f32_16x16x32_bf16 v[22:25], v[184:187], v[208:211], v[22:25]
	v_mfma_f32_16x16x32_bf16 v[18:21], v[184:187], v[216:219], v[18:21]
	v_mfma_f32_16x16x32_bf16 v[14:17], v[192:195], v[208:211], v[14:17]
	v_mfma_f32_16x16x32_bf16 v[10:13], v[192:195], v[216:219], v[10:13]
	v_mfma_f32_16x16x32_bf16 v[6:9], v[200:203], v[208:211], v[6:9]
	v_mfma_f32_16x16x32_bf16 v[2:5], v[200:203], v[216:219], v[2:5]
	s_add_i32 s0, s0, 2
	s_addk_i32 s1, 0x100
	s_cmp_lt_u32 s0, 28
	s_barrier
	s_cbranch_scc1 .LBB0_247
	v_readfirstlane_b32 s0, v145
	s_mov_b32 m0, s0
	s_mov_b32 s1, 0x80f80
	v_readfirstlane_b32 s0, v144
	ds_read_b128 v[138:141], v155
	ds_read_b128 v[148:151], v155 offset:1024
	ds_read_b128 v[156:159], v155 offset:2048
	ds_read_b128 v[152:155], v155 offset:3072
	ds_read_b128 v[160:163], v133
	ds_read_b128 v[164:167], v133 offset:1024
	ds_read_b128 v[168:171], v132
	ds_read_b128 v[172:175], v132 offset:1024
	ds_read_b128 v[176:179], v131
	ds_read_b128 v[180:183], v131 offset:1024
	ds_read_b128 v[184:187], v130
	ds_read_b128 v[188:191], v130 offset:1024
	buffer_load_dwordx4 v137, s[88:91], s1 offen lds
	s_mov_b32 m0, s0
	s_nop 0
	buffer_load_dwordx4 v136, s[88:91], s1 offen lds
	s_barrier
	s_waitcnt lgkmcnt(0)
	v_mfma_f32_16x16x32_bf16 v[126:129], v[160:163], v[138:141], v[126:129]
	v_mfma_f32_16x16x32_bf16 v[118:121], v[168:171], v[138:141], v[118:121]
	v_mfma_f32_16x16x32_bf16 v[110:113], v[176:179], v[138:141], v[110:113]
	v_mfma_f32_16x16x32_bf16 v[102:105], v[184:187], v[138:141], v[102:105]
	v_mfma_f32_16x16x32_bf16 v[126:129], v[164:167], v[148:151], v[126:129]
	v_mfma_f32_16x16x32_bf16 v[122:125], v[160:163], v[156:159], v[122:125]
	v_mfma_f32_16x16x32_bf16 v[118:121], v[172:175], v[148:151], v[118:121]
	v_mfma_f32_16x16x32_bf16 v[114:117], v[168:171], v[156:159], v[114:117]
	v_mfma_f32_16x16x32_bf16 v[110:113], v[180:183], v[148:151], v[110:113]
	v_mfma_f32_16x16x32_bf16 v[106:109], v[176:179], v[156:159], v[106:109]
	v_mfma_f32_16x16x32_bf16 v[102:105], v[188:191], v[148:151], v[102:105]
	v_mfma_f32_16x16x32_bf16 v[98:101], v[184:187], v[156:159], v[98:101]
	v_mfma_f32_16x16x32_bf16 v[142:145], v[164:167], v[152:155], v[122:125]
	v_mfma_f32_16x16x32_bf16 v[192:195], v[172:175], v[152:155], v[114:117]
	v_mfma_f32_16x16x32_bf16 v[196:199], v[180:183], v[152:155], v[106:109]
	v_mfma_f32_16x16x32_bf16 v[200:203], v[188:191], v[152:155], v[98:101]
	s_barrier
	s_nop 1
	ds_read_b128 v[98:101], v147
	ds_read_b128 v[106:109], v147 offset:1024
	ds_read_b128 v[114:117], v147 offset:2048
	ds_read_b128 v[122:125], v147 offset:3072
	s_barrier
	s_waitcnt lgkmcnt(0)
	v_mfma_f32_16x16x32_bf16 v[94:97], v[160:163], v[98:101], v[94:97]
	v_mfma_f32_16x16x32_bf16 v[90:93], v[160:163], v[114:117], v[90:93]
	v_mfma_f32_16x16x32_bf16 v[86:89], v[168:171], v[98:101], v[86:89]
	v_mfma_f32_16x16x32_bf16 v[82:85], v[168:171], v[114:117], v[82:85]
	v_mfma_f32_16x16x32_bf16 v[78:81], v[176:179], v[98:101], v[78:81]
	v_mfma_f32_16x16x32_bf16 v[74:77], v[176:179], v[114:117], v[74:77]
	v_mfma_f32_16x16x32_bf16 v[70:73], v[184:187], v[98:101], v[70:73]
	v_mfma_f32_16x16x32_bf16 v[66:69], v[184:187], v[114:117], v[66:69]
	v_mfma_f32_16x16x32_bf16 v[94:97], v[164:167], v[106:109], v[94:97]
	v_mfma_f32_16x16x32_bf16 v[90:93], v[164:167], v[122:125], v[90:93]
	v_mfma_f32_16x16x32_bf16 v[86:89], v[172:175], v[106:109], v[86:89]
	v_mfma_f32_16x16x32_bf16 v[82:85], v[172:175], v[122:125], v[82:85]
	v_mfma_f32_16x16x32_bf16 v[78:81], v[180:183], v[106:109], v[78:81]
	v_mfma_f32_16x16x32_bf16 v[74:77], v[180:183], v[122:125], v[74:77]
	v_mfma_f32_16x16x32_bf16 v[70:73], v[188:191], v[106:109], v[70:73]
	v_mfma_f32_16x16x32_bf16 v[66:69], v[188:191], v[122:125], v[66:69]
	s_barrier
; #define WAIT_V(n) asm volatile("s_waitcnt vmcnt(" #n ")" ::: "memory")
; #define WAIT_L(n) asm volatile("s_waitcnt lgkmcnt(" #n ")" ::: "memory")
; #define BAR __builtin_amdgcn_s_barrier()
; __device__ __forceinline__ void mainloop_8phase(const u16* __restrict__ A, const u16* __restrict__ Bt, int K,
;                                                 f32x4 (&acc)[2][2][4][2], int wid_s, int ld) {
;     ...
;     LDA(At, 0, 1); WAIT_V(4); BAR; WAIT_L(0); MMA(1, 0, At, B0); MMA(1, 1, At, B1); BAR; }
;   { LDB(B0, 1, 0); LDA(At, 1, 0); WAIT_V(2); BAR; WAIT_L(0); MMA(0, 0, At, B0); BAR;
	ds_read_b128 v[160:163], v133 offset:16384
	ds_read_b128 v[164:167], v133 offset:17408
	ds_read_b128 v[168:171], v132 offset:16384
	ds_read_b128 v[172:175], v132 offset:17408
	ds_read_b128 v[176:179], v131 offset:16384
	ds_read_b128 v[180:183], v131 offset:17408
	ds_read_b128 v[184:187], v130 offset:16384
	ds_read_b128 v[188:191], v130 offset:17408
	s_waitcnt vmcnt(4)
	s_barrier
	s_waitcnt lgkmcnt(0)
	v_mfma_f32_16x16x32_bf16 v[62:65], v[160:163], v[138:141], v[62:65]
	v_mfma_f32_16x16x32_bf16 v[58:61], v[160:163], v[156:159], v[58:61]
	v_mfma_f32_16x16x32_bf16 v[54:57], v[168:171], v[138:141], v[54:57]
	v_mfma_f32_16x16x32_bf16 v[50:53], v[168:171], v[156:159], v[50:53]
	v_mfma_f32_16x16x32_bf16 v[46:49], v[176:179], v[138:141], v[46:49]
	v_mfma_f32_16x16x32_bf16 v[42:45], v[176:179], v[156:159], v[42:45]
	v_mfma_f32_16x16x32_bf16 v[38:41], v[184:187], v[138:141], v[38:41]
	v_mfma_f32_16x16x32_bf16 v[34:37], v[184:187], v[156:159], v[34:37]
	v_mfma_f32_16x16x32_bf16 v[204:207], v[164:167], v[148:151], v[62:65]
	v_mfma_f32_16x16x32_bf16 v[208:211], v[164:167], v[152:155], v[58:61]
	v_mfma_f32_16x16x32_bf16 v[212:215], v[172:175], v[148:151], v[54:57]
	v_mfma_f32_16x16x32_bf16 v[216:219], v[172:175], v[152:155], v[50:53]
	v_mfma_f32_16x16x32_bf16 v[220:223], v[180:183], v[148:151], v[46:49]
	v_mfma_f32_16x16x32_bf16 v[224:227], v[180:183], v[152:155], v[42:45]
	v_mfma_f32_16x16x32_bf16 v[136:139], v[188:191], v[148:151], v[38:41]
	v_mfma_f32_16x16x32_bf16 v[146:149], v[188:191], v[152:155], v[34:37]
	v_mfma_f32_16x16x32_bf16 v[30:33], v[160:163], v[98:101], v[30:33]
	v_mfma_f32_16x16x32_bf16 v[22:25], v[168:171], v[98:101], v[22:25]
	v_mfma_f32_16x16x32_bf16 v[14:17], v[176:179], v[98:101], v[14:17]
	v_mfma_f32_16x16x32_bf16 v[6:9], v[184:187], v[98:101], v[6:9]
	v_mfma_f32_16x16x32_bf16 v[30:33], v[164:167], v[106:109], v[30:33]
	v_mfma_f32_16x16x32_bf16 v[26:29], v[160:163], v[114:117], v[26:29]
	v_mfma_f32_16x16x32_bf16 v[22:25], v[172:175], v[106:109], v[22:25]
	v_mfma_f32_16x16x32_bf16 v[18:21], v[168:171], v[114:117], v[18:21]
	v_mfma_f32_16x16x32_bf16 v[14:17], v[180:183], v[106:109], v[14:17]
	v_mfma_f32_16x16x32_bf16 v[10:13], v[176:179], v[114:117], v[10:13]
	v_mfma_f32_16x16x32_bf16 v[6:9], v[188:191], v[106:109], v[6:9]
	v_mfma_f32_16x16x32_bf16 v[2:5], v[184:187], v[114:117], v[2:5]
	v_mfma_f32_16x16x32_bf16 v[150:153], v[164:167], v[122:125], v[26:29]
	v_mfma_f32_16x16x32_bf16 v[154:157], v[172:175], v[122:125], v[18:21]
	v_mfma_f32_16x16x32_bf16 v[158:161], v[180:183], v[122:125], v[10:13]
	v_mfma_f32_16x16x32_bf16 v[162:165], v[188:191], v[122:125], v[2:5]
	s_barrier
	s_nop 1
	ds_read_b128 v[2:5], v135
	ds_read_b128 v[10:13], v135 offset:1024
	ds_read_b128 v[18:21], v135 offset:2048
	ds_read_b128 v[26:29], v135 offset:3072
	ds_read_b128 v[34:37], v133 offset:32768
	ds_read_b128 v[38:41], v133 offset:33792
	ds_read_b128 v[42:45], v132 offset:32768
	ds_read_b128 v[46:49], v132 offset:33792
	ds_read_b128 v[166:169], v131 offset:32768
	ds_read_b128 v[170:173], v131 offset:33792
	ds_read_b128 v[174:177], v130 offset:32768
	ds_read_b128 v[178:181], v130 offset:33792
	s_waitcnt vmcnt(2)
	s_barrier
	s_waitcnt lgkmcnt(0)
	v_mfma_f32_16x16x32_bf16 v[50:53], v[34:37], v[2:5], v[126:129]
	v_mfma_f32_16x16x32_bf16 v[122:125], v[38:41], v[10:13], v[50:53]
	v_mfma_f32_16x16x32_bf16 v[50:53], v[34:37], v[18:21], v[142:145]
	v_mfma_f32_16x16x32_bf16 v[126:129], v[38:41], v[26:29], v[50:53]
	v_mfma_f32_16x16x32_bf16 v[50:53], v[42:45], v[2:5], v[118:121]
	v_mfma_f32_16x16x32_bf16 v[114:117], v[46:49], v[10:13], v[50:53]
	v_mfma_f32_16x16x32_bf16 v[50:53], v[42:45], v[18:21], v[192:195]
	v_mfma_f32_16x16x32_bf16 v[118:121], v[46:49], v[26:29], v[50:53]
	v_mfma_f32_16x16x32_bf16 v[50:53], v[166:169], v[2:5], v[110:113]
	v_mfma_f32_16x16x32_bf16 v[106:109], v[170:173], v[10:13], v[50:53]
	v_mfma_f32_16x16x32_bf16 v[50:53], v[166:169], v[18:21], v[196:199]
	v_mfma_f32_16x16x32_bf16 v[110:113], v[170:173], v[26:29], v[50:53]
	v_mfma_f32_16x16x32_bf16 v[50:53], v[174:177], v[2:5], v[102:105]
	v_mfma_f32_16x16x32_bf16 v[98:101], v[178:181], v[10:13], v[50:53]
	v_mfma_f32_16x16x32_bf16 v[50:53], v[174:177], v[18:21], v[200:203]
	v_mfma_f32_16x16x32_bf16 v[102:105], v[178:181], v[26:29], v[50:53]
	s_barrier
; #define WAIT_V(n) asm volatile("s_waitcnt vmcnt(" #n ")" ::: "memory")
; #define WAIT_L(n) asm volatile("s_waitcnt lgkmcnt(" #n ")" ::: "memory")
; #define BAR __builtin_amdgcn_s_barrier()
; __device__ __forceinline__ void mainloop_8phase(const u16* __restrict__ A, const u16* __restrict__ Bt, int K,
;                                                 f32x4 (&acc)[2][2][4][2], int wid_s, int ld) {
;     ...
;     LDB(B1, 1, 1); WAIT_V(0); BAR; WAIT_L(0); MMA(0, 1, At, B1); BAR;
;     LDA(At, 1, 1); BAR; WAIT_L(0); MMA(1, 0, At, B0); MMA(1, 1, At, B1); BAR; }
;   if (wr == 0) BAR;
	ds_read_b128 v[140:143], v134
	ds_read_b128 v[182:185], v134 offset:1024
	ds_read_b128 v[186:189], v134 offset:2048
	ds_read_b128 v[190:193], v134 offset:3072
	s_waitcnt vmcnt(0)
	s_barrier
	s_waitcnt lgkmcnt(0)
	v_mfma_f32_16x16x32_bf16 v[50:53], v[34:37], v[140:143], v[94:97]
	v_mfma_f32_16x16x32_bf16 v[34:37], v[34:37], v[186:189], v[90:93]
	v_mfma_f32_16x16x32_bf16 v[62:65], v[38:41], v[190:193], v[34:37]
	v_mfma_f32_16x16x32_bf16 v[34:37], v[42:45], v[140:143], v[86:89]
	v_mfma_f32_16x16x32_bf16 v[58:61], v[38:41], v[182:185], v[50:53]
	v_mfma_f32_16x16x32_bf16 v[50:53], v[46:49], v[182:185], v[34:37]
	v_mfma_f32_16x16x32_bf16 v[34:37], v[42:45], v[186:189], v[82:85]
	v_mfma_f32_16x16x32_bf16 v[54:57], v[46:49], v[190:193], v[34:37]
	v_mfma_f32_16x16x32_bf16 v[34:37], v[166:169], v[140:143], v[78:81]
	v_mfma_f32_16x16x32_bf16 v[42:45], v[170:173], v[182:185], v[34:37]
	v_mfma_f32_16x16x32_bf16 v[34:37], v[166:169], v[186:189], v[74:77]
	v_mfma_f32_16x16x32_bf16 v[46:49], v[170:173], v[190:193], v[34:37]
	v_mfma_f32_16x16x32_bf16 v[34:37], v[174:177], v[140:143], v[70:73]
	v_mfma_f32_16x16x32_bf16 v[38:41], v[174:177], v[186:189], v[66:69]
	v_mfma_f32_16x16x32_bf16 v[34:37], v[178:181], v[182:185], v[34:37]
	v_mfma_f32_16x16x32_bf16 v[38:41], v[178:181], v[190:193], v[38:41]
	s_barrier
	ds_read_b128 v[166:169], v133 offset:49152
	ds_read_b128 v[170:173], v133 offset:50176
	ds_read_b128 v[174:177], v132 offset:49152
	ds_read_b128 v[132:135], v132 offset:50176
	ds_read_b128 v[178:181], v131 offset:49152
	ds_read_b128 v[194:197], v131 offset:50176
	ds_read_b128 v[198:201], v130 offset:49152
	ds_read_b128 v[228:231], v130 offset:50176
	s_barrier
	s_waitcnt lgkmcnt(0)
	v_mfma_f32_16x16x32_bf16 v[66:69], v[166:169], v[2:5], v[204:207]
	v_mfma_f32_16x16x32_bf16 v[90:93], v[170:173], v[10:13], v[66:69]
	v_mfma_f32_16x16x32_bf16 v[66:69], v[166:169], v[18:21], v[208:211]
	v_mfma_f32_16x16x32_bf16 v[94:97], v[170:173], v[26:29], v[66:69]
	v_mfma_f32_16x16x32_bf16 v[66:69], v[174:177], v[2:5], v[212:215]
	v_mfma_f32_16x16x32_bf16 v[82:85], v[132:135], v[10:13], v[66:69]
	v_mfma_f32_16x16x32_bf16 v[66:69], v[174:177], v[18:21], v[216:219]
	v_mfma_f32_16x16x32_bf16 v[86:89], v[132:135], v[26:29], v[66:69]
	v_mfma_f32_16x16x32_bf16 v[66:69], v[178:181], v[2:5], v[220:223]
	v_mfma_f32_16x16x32_bf16 v[74:77], v[194:197], v[10:13], v[66:69]
	v_mfma_f32_16x16x32_bf16 v[66:69], v[178:181], v[18:21], v[224:227]
	v_mfma_f32_16x16x32_bf16 v[2:5], v[198:201], v[2:5], v[136:139]
	v_mfma_f32_16x16x32_bf16 v[78:81], v[194:197], v[26:29], v[66:69]
	v_mfma_f32_16x16x32_bf16 v[66:69], v[228:231], v[10:13], v[2:5]
	v_mfma_f32_16x16x32_bf16 v[2:5], v[198:201], v[18:21], v[146:149]
	v_mfma_f32_16x16x32_bf16 v[70:73], v[228:231], v[26:29], v[2:5]
	v_mfma_f32_16x16x32_bf16 v[2:5], v[166:169], v[140:143], v[30:33]
	v_mfma_f32_16x16x32_bf16 v[26:29], v[170:173], v[182:185], v[2:5]
	v_mfma_f32_16x16x32_bf16 v[2:5], v[166:169], v[186:189], v[150:153]
	v_mfma_f32_16x16x32_bf16 v[30:33], v[170:173], v[190:193], v[2:5]
	v_mfma_f32_16x16x32_bf16 v[2:5], v[174:177], v[140:143], v[22:25]
	v_mfma_f32_16x16x32_bf16 v[18:21], v[132:135], v[182:185], v[2:5]
	v_mfma_f32_16x16x32_bf16 v[2:5], v[174:177], v[186:189], v[154:157]
	v_mfma_f32_16x16x32_bf16 v[22:25], v[132:135], v[190:193], v[2:5]
	v_mfma_f32_16x16x32_bf16 v[2:5], v[178:181], v[140:143], v[14:17]
	v_mfma_f32_16x16x32_bf16 v[10:13], v[194:197], v[182:185], v[2:5]
	v_mfma_f32_16x16x32_bf16 v[2:5], v[178:181], v[186:189], v[158:161]
	v_mfma_f32_16x16x32_bf16 v[14:17], v[194:197], v[190:193], v[2:5]
	v_mfma_f32_16x16x32_bf16 v[2:5], v[198:201], v[140:143], v[6:9]
	v_mfma_f32_16x16x32_bf16 v[6:9], v[198:201], v[186:189], v[162:165]
	v_mfma_f32_16x16x32_bf16 v[2:5], v[228:231], v[182:185], v[2:5]
	v_mfma_f32_16x16x32_bf16 v[6:9], v[228:231], v[190:193], v[6:9]
	s_movk_i32 s0, 0x100
	v_cmp_gt_u32_e32 vcc, s0, v0
	s_barrier
	s_and_saveexec_b64 s[0:1], vcc
	s_cbranch_execz .LBB0_250
	s_barrier

; #define WAIT_V(n) asm volatile("s_waitcnt vmcnt(" #n ")" ::: "memory")
; #define WAIT_L(n) asm volatile("s_waitcnt lgkmcnt(" #n ")" ::: "memory")
; #define BAR __builtin_amdgcn_s_barrier()
; #define SCHED __builtin_amdgcn_sched_barrier(0)
; __device__ __forceinline__ void mainloop_8phase(const u16* __restrict__ A, const u16* __restrict__ Bt, int K,
;                                                 f32x4 (&acc)[2][2][4][2], int wid_s, int ld) {
;     ...
;     LDB(B0, 0, 0); SCHED; LDA(At, 0, 0); STAGE(SA(1, 1), A, brow + G_HALF, t + 1);
;     WAIT_L(8); BAR; WAIT_L(0); MMA(0, 0, At, B0); BAR; SCHED;
;     LDB(B1, 0, 1); STAGE(SB(0, 0), Bt, bcol, t + 2);
;     BAR; WAIT_L(0); MMA(0, 1, At, B1); BAR;
;     LDA(At, 0, 1); STAGE(SA(0, 0), A, brow, t + 2);
;     BAR; WAIT_L(0); MMA(1, 0, At, B0); BAR; SCHED;
;     STAGE(SB(0, 1), Bt, bcol + G_HALF, t + 2);
;     WAIT_V(6); BAR; MMA(1, 1, At, B1); BAR;
.LBB0_342:
	ds_read_b128 v[156:159], v155
	ds_read_b128 v[160:163], v155 offset:1024
	ds_read_b128 v[164:167], v155 offset:2048
	ds_read_b128 v[168:171], v155 offset:3072
	v_readfirstlane_b32 s6, v145
	s_add_i32 s3, s2, 0xffffff00
	s_mov_b32 m0, s6
	v_readfirstlane_b32 s6, v144
	ds_read_b128 v[172:175], v133
	ds_read_b128 v[176:179], v133 offset:1024
	ds_read_b128 v[180:183], v132
	ds_read_b128 v[184:187], v132 offset:1024
	ds_read_b128 v[188:191], v131
	ds_read_b128 v[192:195], v131 offset:1024
	ds_read_b128 v[196:199], v130
	ds_read_b128 v[200:203], v130 offset:1024
	buffer_load_dwordx4 v136, s[88:91], s3 offen lds
	s_mov_b32 m0, s6
	s_nop 0
	buffer_load_dwordx4 v135, s[88:91], s3 offen lds
	s_waitcnt lgkmcnt(8)
	s_barrier
	s_waitcnt lgkmcnt(0)
	v_mfma_f32_16x16x32_bf16 v[126:129], v[172:175], v[156:159], v[126:129]
	v_mfma_f32_16x16x32_bf16 v[122:125], v[172:175], v[164:167], v[122:125]
	v_mfma_f32_16x16x32_bf16 v[118:121], v[180:183], v[156:159], v[118:121]
	v_mfma_f32_16x16x32_bf16 v[114:117], v[180:183], v[164:167], v[114:117]
	v_mfma_f32_16x16x32_bf16 v[110:113], v[188:191], v[156:159], v[110:113]
	v_mfma_f32_16x16x32_bf16 v[106:109], v[188:191], v[164:167], v[106:109]
	v_mfma_f32_16x16x32_bf16 v[102:105], v[196:199], v[156:159], v[102:105]
	v_mfma_f32_16x16x32_bf16 v[98:101], v[196:199], v[164:167], v[98:101]
	v_mfma_f32_16x16x32_bf16 v[126:129], v[176:179], v[160:163], v[126:129]
	v_mfma_f32_16x16x32_bf16 v[122:125], v[176:179], v[168:171], v[122:125]
	v_mfma_f32_16x16x32_bf16 v[118:121], v[184:187], v[160:163], v[118:121]
	v_mfma_f32_16x16x32_bf16 v[114:117], v[184:187], v[168:171], v[114:117]
	v_mfma_f32_16x16x32_bf16 v[110:113], v[192:195], v[160:163], v[110:113]
	v_mfma_f32_16x16x32_bf16 v[106:109], v[192:195], v[168:171], v[106:109]
	v_mfma_f32_16x16x32_bf16 v[102:105], v[200:203], v[160:163], v[102:105]
	v_mfma_f32_16x16x32_bf16 v[98:101], v[200:203], v[168:171], v[98:101]
	s_barrier
	v_readfirstlane_b32 s9, v148
	s_add_i32 s3, s2, 0xfff7ff80
	s_mov_b32 s6, s90
	s_mov_b32 s7, s91
	s_mov_b32 m0, s9
	v_readfirstlane_b32 s9, v149
	ds_read_b128 v[204:207], v147
	ds_read_b128 v[208:211], v147 offset:1024
	ds_read_b128 v[212:215], v147 offset:2048
	ds_read_b128 v[216:219], v147 offset:3072
	buffer_load_dwordx4 v136, s[4:7], s3 offen lds
	s_mov_b32 m0, s9
	s_nop 0
	buffer_load_dwordx4 v135, s[4:7], s3 offen lds
	s_barrier
	s_waitcnt lgkmcnt(0)
	v_mfma_f32_16x16x32_bf16 v[94:97], v[172:175], v[204:207], v[94:97]
	v_mfma_f32_16x16x32_bf16 v[90:93], v[172:175], v[212:215], v[90:93]
	v_mfma_f32_16x16x32_bf16 v[86:89], v[180:183], v[204:207], v[86:89]
	v_mfma_f32_16x16x32_bf16 v[82:85], v[180:183], v[212:215], v[82:85]
	v_mfma_f32_16x16x32_bf16 v[78:81], v[188:191], v[204:207], v[78:81]
	v_mfma_f32_16x16x32_bf16 v[74:77], v[188:191], v[212:215], v[74:77]
	v_mfma_f32_16x16x32_bf16 v[70:73], v[196:199], v[204:207], v[70:73]
	v_mfma_f32_16x16x32_bf16 v[66:69], v[196:199], v[212:215], v[66:69]
	v_mfma_f32_16x16x32_bf16 v[94:97], v[176:179], v[208:211], v[94:97]
	v_mfma_f32_16x16x32_bf16 v[90:93], v[176:179], v[216:219], v[90:93]
	v_mfma_f32_16x16x32_bf16 v[86:89], v[184:187], v[208:211], v[86:89]
	v_mfma_f32_16x16x32_bf16 v[82:85], v[184:187], v[216:219], v[82:85]
	v_mfma_f32_16x16x32_bf16 v[78:81], v[192:195], v[208:211], v[78:81]
	v_mfma_f32_16x16x32_bf16 v[74:77], v[192:195], v[216:219], v[74:77]
	v_mfma_f32_16x16x32_bf16 v[70:73], v[200:203], v[208:211], v[70:73]
	v_mfma_f32_16x16x32_bf16 v[66:69], v[200:203], v[216:219], v[66:69]
	v_readfirstlane_b32 s9, v140
	s_mov_b32 m0, s9
	v_readfirstlane_b32 s9, v150
	s_barrier
	ds_read_b128 v[172:175], v133 offset:16384
	ds_read_b128 v[176:179], v133 offset:17408
	ds_read_b128 v[180:183], v132 offset:16384
	ds_read_b128 v[184:187], v132 offset:17408
	ds_read_b128 v[188:191], v131 offset:16384
	ds_read_b128 v[192:195], v131 offset:17408
	ds_read_b128 v[196:199], v130 offset:16384
	ds_read_b128 v[200:203], v130 offset:17408
	buffer_load_dwordx4 v136, s[88:91], s3 offen lds
	s_mov_b32 m0, s9
	s_nop 0
	buffer_load_dwordx4 v135, s[88:91], s3 offen lds
	s_barrier
	s_waitcnt lgkmcnt(0)
	v_mfma_f32_16x16x32_bf16 v[62:65], v[172:175], v[156:159], v[62:65]
	v_mfma_f32_16x16x32_bf16 v[58:61], v[172:175], v[164:167], v[58:61]
	v_mfma_f32_16x16x32_bf16 v[54:57], v[180:183], v[156:159], v[54:57]
	v_mfma_f32_16x16x32_bf16 v[50:53], v[180:183], v[164:167], v[50:53]
	v_mfma_f32_16x16x32_bf16 v[46:49], v[188:191], v[156:159], v[46:49]
	v_mfma_f32_16x16x32_bf16 v[42:45], v[188:191], v[164:167], v[42:45]
	v_mfma_f32_16x16x32_bf16 v[38:41], v[196:199], v[156:159], v[38:41]
	v_mfma_f32_16x16x32_bf16 v[34:37], v[196:199], v[164:167], v[34:37]
	v_mfma_f32_16x16x32_bf16 v[62:65], v[176:179], v[160:163], v[62:65]
	v_mfma_f32_16x16x32_bf16 v[58:61], v[176:179], v[168:171], v[58:61]
	v_mfma_f32_16x16x32_bf16 v[54:57], v[184:187], v[160:163], v[54:57]
	v_mfma_f32_16x16x32_bf16 v[50:53], v[184:187], v[168:171], v[50:53]
	v_mfma_f32_16x16x32_bf16 v[46:49], v[192:195], v[160:163], v[46:49]
	v_mfma_f32_16x16x32_bf16 v[42:45], v[192:195], v[168:171], v[42:45]
	v_mfma_f32_16x16x32_bf16 v[38:41], v[200:203], v[160:163], v[38:41]
	v_mfma_f32_16x16x32_bf16 v[34:37], v[200:203], v[168:171], v[34:37]
	s_barrier
	v_readfirstlane_b32 s9, v151
	s_add_i32 s3, s2, 0xffffff80
	s_mov_b32 m0, s9
	v_readfirstlane_b32 s9, v152
	buffer_load_dwordx4 v136, s[4:7], s3 offen lds
	s_mov_b32 m0, s9
	s_nop 0
	buffer_load_dwordx4 v135, s[4:7], s3 offen lds
	s_waitcnt vmcnt(6)
	s_barrier
; #define WAIT_V(n) asm volatile("s_waitcnt vmcnt(" #n ")" ::: "memory")
; #define WAIT_L(n) asm volatile("s_waitcnt lgkmcnt(" #n ")" ::: "memory")
; #define BAR __builtin_amdgcn_s_barrier()
; #define SCHED __builtin_amdgcn_sched_barrier(0)
; __device__ __forceinline__ void mainloop_8phase(const u16* __restrict__ A, const u16* __restrict__ Bt, int K,
;                                                 f32x4 (&acc)[2][2][4][2], int wid_s, int ld) {
;     ...
;     WAIT_V(6); BAR; MMA(1, 1, At, B1); BAR;
;     LDB(B0, 1, 0); SCHED; LDA(At, 1, 0); STAGE(SA(0, 1), A, brow + G_HALF, t + 2);
;     WAIT_L(8); BAR; WAIT_L(0); MMA(0, 0, At, B0); BAR; SCHED;
;     LDB(B1, 1, 1); STAGE(SB(1, 0), Bt, bcol, t + 3);
;     BAR; WAIT_L(0); MMA(0, 1, At, B1); BAR;
;     LDA(At, 1, 1); STAGE(SA(1, 0), A, brow, t + 3);
	v_mfma_f32_16x16x32_bf16 v[30:33], v[172:175], v[204:207], v[30:33]
	v_mfma_f32_16x16x32_bf16 v[26:29], v[172:175], v[212:215], v[26:29]
	v_mfma_f32_16x16x32_bf16 v[22:25], v[180:183], v[204:207], v[22:25]
	v_mfma_f32_16x16x32_bf16 v[18:21], v[180:183], v[212:215], v[18:21]
	v_mfma_f32_16x16x32_bf16 v[14:17], v[188:191], v[204:207], v[14:17]
	v_mfma_f32_16x16x32_bf16 v[10:13], v[188:191], v[212:215], v[10:13]
	v_mfma_f32_16x16x32_bf16 v[6:9], v[196:199], v[204:207], v[6:9]
	v_mfma_f32_16x16x32_bf16 v[2:5], v[196:199], v[212:215], v[2:5]
	v_mfma_f32_16x16x32_bf16 v[30:33], v[176:179], v[208:211], v[30:33]
	v_mfma_f32_16x16x32_bf16 v[26:29], v[176:179], v[216:219], v[26:29]
	v_mfma_f32_16x16x32_bf16 v[22:25], v[184:187], v[208:211], v[22:25]
	v_mfma_f32_16x16x32_bf16 v[18:21], v[184:187], v[216:219], v[18:21]
	v_mfma_f32_16x16x32_bf16 v[14:17], v[192:195], v[208:211], v[14:17]
	v_mfma_f32_16x16x32_bf16 v[10:13], v[192:195], v[216:219], v[10:13]
	v_mfma_f32_16x16x32_bf16 v[6:9], v[200:203], v[208:211], v[6:9]
	v_mfma_f32_16x16x32_bf16 v[2:5], v[200:203], v[216:219], v[2:5]
	s_barrier
	ds_read_b128 v[156:159], v137
	ds_read_b128 v[160:163], v137 offset:1024
	ds_read_b128 v[164:167], v137 offset:2048
	ds_read_b128 v[168:171], v137 offset:3072
	v_readfirstlane_b32 s9, v153
	s_mov_b32 m0, s9
	v_readfirstlane_b32 s9, v154
	ds_read_b128 v[172:175], v133 offset:32768
	ds_read_b128 v[176:179], v133 offset:33792
	ds_read_b128 v[180:183], v132 offset:32768
	ds_read_b128 v[184:187], v132 offset:33792
	ds_read_b128 v[188:191], v131 offset:32768
	ds_read_b128 v[192:195], v131 offset:33792
	ds_read_b128 v[196:199], v130 offset:32768
	ds_read_b128 v[200:203], v130 offset:33792
	buffer_load_dwordx4 v136, s[88:91], s3 offen lds
	s_mov_b32 m0, s9
	s_nop 0
	buffer_load_dwordx4 v135, s[88:91], s3 offen lds
	s_waitcnt lgkmcnt(8)
	s_barrier
	s_waitcnt lgkmcnt(0)
	v_mfma_f32_16x16x32_bf16 v[126:129], v[172:175], v[156:159], v[126:129]
	v_mfma_f32_16x16x32_bf16 v[122:125], v[172:175], v[164:167], v[122:125]
	v_mfma_f32_16x16x32_bf16 v[118:121], v[180:183], v[156:159], v[118:121]
	v_mfma_f32_16x16x32_bf16 v[114:117], v[180:183], v[164:167], v[114:117]
	v_mfma_f32_16x16x32_bf16 v[110:113], v[188:191], v[156:159], v[110:113]
	v_mfma_f32_16x16x32_bf16 v[106:109], v[188:191], v[164:167], v[106:109]
	v_mfma_f32_16x16x32_bf16 v[102:105], v[196:199], v[156:159], v[102:105]
	v_mfma_f32_16x16x32_bf16 v[98:101], v[196:199], v[164:167], v[98:101]
	v_mfma_f32_16x16x32_bf16 v[126:129], v[176:179], v[160:163], v[126:129]
	v_mfma_f32_16x16x32_bf16 v[122:125], v[176:179], v[168:171], v[122:125]
	v_mfma_f32_16x16x32_bf16 v[118:121], v[184:187], v[160:163], v[118:121]
	v_mfma_f32_16x16x32_bf16 v[114:117], v[184:187], v[168:171], v[114:117]
	v_mfma_f32_16x16x32_bf16 v[110:113], v[192:195], v[160:163], v[110:113]
	v_mfma_f32_16x16x32_bf16 v[106:109], v[192:195], v[168:171], v[106:109]
	v_mfma_f32_16x16x32_bf16 v[102:105], v[200:203], v[160:163], v[102:105]
	v_mfma_f32_16x16x32_bf16 v[98:101], v[200:203], v[168:171], v[98:101]
	s_barrier
	v_readfirstlane_b32 s9, v138
	s_add_i32 s3, s2, 0xfff80000
	s_mov_b32 m0, s9
	v_readfirstlane_b32 s9, v139
	ds_read_b128 v[204:207], v134
	ds_read_b128 v[208:211], v134 offset:1024
	ds_read_b128 v[212:215], v134 offset:2048
	ds_read_b128 v[216:219], v134 offset:3072
	buffer_load_dwordx4 v136, s[4:7], s3 offen lds
	s_mov_b32 m0, s9
	s_nop 0
	buffer_load_dwordx4 v135, s[4:7], s3 offen lds
	s_barrier
	s_waitcnt lgkmcnt(0)
	v_mfma_f32_16x16x32_bf16 v[94:97], v[172:175], v[204:207], v[94:97]
	v_mfma_f32_16x16x32_bf16 v[90:93], v[172:175], v[212:215], v[90:93]
	v_mfma_f32_16x16x32_bf16 v[86:89], v[180:183], v[204:207], v[86:89]
	v_mfma_f32_16x16x32_bf16 v[82:85], v[180:183], v[212:215], v[82:85]
	v_mfma_f32_16x16x32_bf16 v[78:81], v[188:191], v[204:207], v[78:81]
	v_mfma_f32_16x16x32_bf16 v[74:77], v[188:191], v[212:215], v[74:77]
	v_mfma_f32_16x16x32_bf16 v[70:73], v[196:199], v[204:207], v[70:73]
	v_mfma_f32_16x16x32_bf16 v[66:69], v[196:199], v[212:215], v[66:69]
	v_mfma_f32_16x16x32_bf16 v[94:97], v[176:179], v[208:211], v[94:97]
	v_mfma_f32_16x16x32_bf16 v[90:93], v[176:179], v[216:219], v[90:93]
	v_mfma_f32_16x16x32_bf16 v[86:89], v[184:187], v[208:211], v[86:89]
	v_mfma_f32_16x16x32_bf16 v[82:85], v[184:187], v[216:219], v[82:85]
	v_mfma_f32_16x16x32_bf16 v[78:81], v[192:195], v[208:211], v[78:81]
	v_mfma_f32_16x16x32_bf16 v[74:77], v[192:195], v[216:219], v[74:77]
	v_mfma_f32_16x16x32_bf16 v[70:73], v[200:203], v[208:211], v[70:73]
	v_mfma_f32_16x16x32_bf16 v[66:69], v[200:203], v[216:219], v[66:69]
	v_readfirstlane_b32 s9, v141
	s_mov_b32 m0, s9
	v_readfirstlane_b32 s9, v142
	s_barrier
	ds_read_b128 v[172:175], v133 offset:49152
	ds_read_b128 v[176:179], v133 offset:50176
	ds_read_b128 v[180:183], v132 offset:49152
	ds_read_b128 v[184:187], v132 offset:50176
	ds_read_b128 v[188:191], v131 offset:49152
	ds_read_b128 v[192:195], v131 offset:50176
	ds_read_b128 v[196:199], v130 offset:49152
	ds_read_b128 v[200:203], v130 offset:50176
	buffer_load_dwordx4 v136, s[88:91], s3 offen lds
	s_mov_b32 m0, s9
	s_nop 0
	buffer_load_dwordx4 v135, s[88:91], s3 offen lds
	s_barrier
; #define WAIT_V(n) asm volatile("s_waitcnt vmcnt(" #n ")" ::: "memory")
; #define WAIT_L(n) asm volatile("s_waitcnt lgkmcnt(" #n ")" ::: "memory")
; #define BAR __builtin_amdgcn_s_barrier()
; #define SCHED __builtin_amdgcn_sched_barrier(0)
; __device__ __forceinline__ void mainloop_8phase(const u16* __restrict__ A, const u16* __restrict__ Bt, int K,
;                                                 f32x4 (&acc)[2][2][4][2], int wid_s, int ld) {
;     ...
;     BAR; WAIT_L(0); MMA(1, 0, At, B0); BAR; SCHED;
;     STAGE(SB(1, 1), Bt, bcol + G_HALF, t + 3);
;     WAIT_V(6); BAR; MMA(1, 1, At, B1); BAR;
;   }
;   { LDB(B0, 0, 0); LDA(At, 0, 0); STAGE(SA(1, 1), A, brow + G_HALF, nt - 1);
;     BAR; WAIT_L(0); MMA(0, 0, At, B0); BAR;
;     LDB(B1, 0, 1); BAR; WAIT_L(0); MMA(0, 1, At, B1); BAR;
	s_waitcnt lgkmcnt(0)
	v_mfma_f32_16x16x32_bf16 v[62:65], v[172:175], v[156:159], v[62:65]
	v_mfma_f32_16x16x32_bf16 v[58:61], v[172:175], v[164:167], v[58:61]
	v_mfma_f32_16x16x32_bf16 v[54:57], v[180:183], v[156:159], v[54:57]
	v_mfma_f32_16x16x32_bf16 v[50:53], v[180:183], v[164:167], v[50:53]
	v_mfma_f32_16x16x32_bf16 v[46:49], v[188:191], v[156:159], v[46:49]
	v_mfma_f32_16x16x32_bf16 v[42:45], v[188:191], v[164:167], v[42:45]
	v_mfma_f32_16x16x32_bf16 v[38:41], v[196:199], v[156:159], v[38:41]
	v_mfma_f32_16x16x32_bf16 v[34:37], v[196:199], v[164:167], v[34:37]
	v_mfma_f32_16x16x32_bf16 v[62:65], v[176:179], v[160:163], v[62:65]
	v_mfma_f32_16x16x32_bf16 v[58:61], v[176:179], v[168:171], v[58:61]
	v_mfma_f32_16x16x32_bf16 v[54:57], v[184:187], v[160:163], v[54:57]
	v_mfma_f32_16x16x32_bf16 v[50:53], v[184:187], v[168:171], v[50:53]
	v_mfma_f32_16x16x32_bf16 v[46:49], v[192:195], v[160:163], v[46:49]
	v_mfma_f32_16x16x32_bf16 v[42:45], v[192:195], v[168:171], v[42:45]
	v_mfma_f32_16x16x32_bf16 v[38:41], v[200:203], v[160:163], v[38:41]
	v_mfma_f32_16x16x32_bf16 v[34:37], v[200:203], v[168:171], v[34:37]
	s_barrier
	v_readfirstlane_b32 s3, v143
	s_mov_b32 m0, s3
	v_readfirstlane_b32 s3, v146
	buffer_load_dwordx4 v136, s[4:7], s2 offen lds
	s_mov_b32 m0, s3
	s_nop 0
	buffer_load_dwordx4 v135, s[4:7], s2 offen lds
	s_waitcnt vmcnt(6)
	s_barrier
	v_mfma_f32_16x16x32_bf16 v[30:33], v[172:175], v[204:207], v[30:33]
	v_mfma_f32_16x16x32_bf16 v[26:29], v[172:175], v[212:215], v[26:29]
	v_mfma_f32_16x16x32_bf16 v[22:25], v[180:183], v[204:207], v[22:25]
	v_mfma_f32_16x16x32_bf16 v[18:21], v[180:183], v[212:215], v[18:21]
	v_mfma_f32_16x16x32_bf16 v[14:17], v[188:191], v[204:207], v[14:17]
	v_mfma_f32_16x16x32_bf16 v[10:13], v[188:191], v[212:215], v[10:13]
	v_mfma_f32_16x16x32_bf16 v[6:9], v[196:199], v[204:207], v[6:9]
	v_mfma_f32_16x16x32_bf16 v[2:5], v[196:199], v[212:215], v[2:5]
	v_mfma_f32_16x16x32_bf16 v[30:33], v[176:179], v[208:211], v[30:33]
	v_mfma_f32_16x16x32_bf16 v[26:29], v[176:179], v[216:219], v[26:29]
	v_mfma_f32_16x16x32_bf16 v[22:25], v[184:187], v[208:211], v[22:25]
	v_mfma_f32_16x16x32_bf16 v[18:21], v[184:187], v[216:219], v[18:21]
	v_mfma_f32_16x16x32_bf16 v[14:17], v[192:195], v[208:211], v[14:17]
	v_mfma_f32_16x16x32_bf16 v[10:13], v[192:195], v[216:219], v[10:13]
	v_mfma_f32_16x16x32_bf16 v[6:9], v[200:203], v[208:211], v[6:9]
	v_mfma_f32_16x16x32_bf16 v[2:5], v[200:203], v[216:219], v[2:5]
	s_add_i32 s1, s1, 2
	s_addk_i32 s2, 0x100
	s_cmp_lt_u32 s1, 28
	s_barrier
	s_cbranch_scc1 .LBB0_342
	v_readfirstlane_b32 s1, v145
	s_mov_b32 m0, s1
	s_mov_b32 s2, 0x80f80
	v_readfirstlane_b32 s1, v144
	ds_read_b128 v[138:141], v155
	ds_read_b128 v[148:151], v155 offset:1024
	ds_read_b128 v[156:159], v155 offset:2048
	ds_read_b128 v[152:155], v155 offset:3072
	ds_read_b128 v[160:163], v133
	ds_read_b128 v[164:167], v133 offset:1024
	ds_read_b128 v[168:171], v132
	ds_read_b128 v[172:175], v132 offset:1024
	ds_read_b128 v[176:179], v131
	ds_read_b128 v[180:183], v131 offset:1024
	ds_read_b128 v[184:187], v130
	ds_read_b128 v[188:191], v130 offset:1024
	buffer_load_dwordx4 v136, s[88:91], s2 offen lds
	s_mov_b32 m0, s1
	s_nop 0
	buffer_load_dwordx4 v135, s[88:91], s2 offen lds
	s_barrier
	s_waitcnt lgkmcnt(0)
	v_mfma_f32_16x16x32_bf16 v[126:129], v[160:163], v[138:141], v[126:129]
	v_mfma_f32_16x16x32_bf16 v[118:121], v[168:171], v[138:141], v[118:121]
	v_mfma_f32_16x16x32_bf16 v[110:113], v[176:179], v[138:141], v[110:113]
	v_mfma_f32_16x16x32_bf16 v[102:105], v[184:187], v[138:141], v[102:105]
	v_mfma_f32_16x16x32_bf16 v[126:129], v[164:167], v[148:151], v[126:129]
	v_mfma_f32_16x16x32_bf16 v[122:125], v[160:163], v[156:159], v[122:125]
	v_mfma_f32_16x16x32_bf16 v[118:121], v[172:175], v[148:151], v[118:121]
	v_mfma_f32_16x16x32_bf16 v[114:117], v[168:171], v[156:159], v[114:117]
	v_mfma_f32_16x16x32_bf16 v[110:113], v[180:183], v[148:151], v[110:113]
	v_mfma_f32_16x16x32_bf16 v[106:109], v[176:179], v[156:159], v[106:109]
	v_mfma_f32_16x16x32_bf16 v[102:105], v[188:191], v[148:151], v[102:105]
	v_mfma_f32_16x16x32_bf16 v[98:101], v[184:187], v[156:159], v[98:101]
	v_mfma_f32_16x16x32_bf16 v[142:145], v[164:167], v[152:155], v[122:125]
	v_mfma_f32_16x16x32_bf16 v[192:195], v[172:175], v[152:155], v[114:117]
	v_mfma_f32_16x16x32_bf16 v[196:199], v[180:183], v[152:155], v[106:109]
	v_mfma_f32_16x16x32_bf16 v[200:203], v[188:191], v[152:155], v[98:101]
	s_barrier
	s_nop 1
	ds_read_b128 v[98:101], v147
	ds_read_b128 v[106:109], v147 offset:1024
	ds_read_b128 v[114:117], v147 offset:2048
	ds_read_b128 v[122:125], v147 offset:3072
	s_barrier
	s_waitcnt lgkmcnt(0)
	v_mfma_f32_16x16x32_bf16 v[94:97], v[160:163], v[98:101], v[94:97]
	v_mfma_f32_16x16x32_bf16 v[90:93], v[160:163], v[114:117], v[90:93]
	v_mfma_f32_16x16x32_bf16 v[86:89], v[168:171], v[98:101], v[86:89]
	v_mfma_f32_16x16x32_bf16 v[82:85], v[168:171], v[114:117], v[82:85]
	v_mfma_f32_16x16x32_bf16 v[78:81], v[176:179], v[98:101], v[78:81]
	v_mfma_f32_16x16x32_bf16 v[74:77], v[176:179], v[114:117], v[74:77]
	v_mfma_f32_16x16x32_bf16 v[70:73], v[184:187], v[98:101], v[70:73]
	v_mfma_f32_16x16x32_bf16 v[66:69], v[184:187], v[114:117], v[66:69]
	v_mfma_f32_16x16x32_bf16 v[94:97], v[164:167], v[106:109], v[94:97]
	v_mfma_f32_16x16x32_bf16 v[90:93], v[164:167], v[122:125], v[90:93]
	v_mfma_f32_16x16x32_bf16 v[86:89], v[172:175], v[106:109], v[86:89]
	v_mfma_f32_16x16x32_bf16 v[82:85], v[172:175], v[122:125], v[82:85]
	v_mfma_f32_16x16x32_bf16 v[78:81], v[180:183], v[106:109], v[78:81]
	v_mfma_f32_16x16x32_bf16 v[74:77], v[180:183], v[122:125], v[74:77]
	v_mfma_f32_16x16x32_bf16 v[70:73], v[188:191], v[106:109], v[70:73]
	v_mfma_f32_16x16x32_bf16 v[66:69], v[188:191], v[122:125], v[66:69]
	s_barrier
; #define WAIT_V(n) asm volatile("s_waitcnt vmcnt(" #n ")" ::: "memory")
; #define WAIT_L(n) asm volatile("s_waitcnt lgkmcnt(" #n ")" ::: "memory")
; #define BAR __builtin_amdgcn_s_barrier()
; __device__ __forceinline__ void mainloop_8phase(const u16* __restrict__ A, const u16* __restrict__ Bt, int K,
;                                                 f32x4 (&acc)[2][2][4][2], int wid_s, int ld) {
;     ...
;     LDA(At, 0, 1); WAIT_V(4); BAR; WAIT_L(0); MMA(1, 0, At, B0); MMA(1, 1, At, B1); BAR; }
;   { LDB(B0, 1, 0); LDA(At, 1, 0); WAIT_V(2); BAR; WAIT_L(0); MMA(0, 0, At, B0); BAR;
	ds_read_b128 v[160:163], v133 offset:16384
	ds_read_b128 v[164:167], v133 offset:17408
	ds_read_b128 v[168:171], v132 offset:16384
	ds_read_b128 v[172:175], v132 offset:17408
	ds_read_b128 v[176:179], v131 offset:16384
	ds_read_b128 v[180:183], v131 offset:17408
	ds_read_b128 v[184:187], v130 offset:16384
	ds_read_b128 v[188:191], v130 offset:17408
	s_waitcnt vmcnt(4)
	s_barrier
	s_waitcnt lgkmcnt(0)
	v_mfma_f32_16x16x32_bf16 v[62:65], v[160:163], v[138:141], v[62:65]
	v_mfma_f32_16x16x32_bf16 v[58:61], v[160:163], v[156:159], v[58:61]
	v_mfma_f32_16x16x32_bf16 v[54:57], v[168:171], v[138:141], v[54:57]
	v_mfma_f32_16x16x32_bf16 v[50:53], v[168:171], v[156:159], v[50:53]
	v_mfma_f32_16x16x32_bf16 v[46:49], v[176:179], v[138:141], v[46:49]
	v_mfma_f32_16x16x32_bf16 v[42:45], v[176:179], v[156:159], v[42:45]
	v_mfma_f32_16x16x32_bf16 v[38:41], v[184:187], v[138:141], v[38:41]
	v_mfma_f32_16x16x32_bf16 v[34:37], v[184:187], v[156:159], v[34:37]
	v_mfma_f32_16x16x32_bf16 v[204:207], v[164:167], v[148:151], v[62:65]
	v_mfma_f32_16x16x32_bf16 v[208:211], v[164:167], v[152:155], v[58:61]
	v_mfma_f32_16x16x32_bf16 v[212:215], v[172:175], v[148:151], v[54:57]
	v_mfma_f32_16x16x32_bf16 v[216:219], v[172:175], v[152:155], v[50:53]
	v_mfma_f32_16x16x32_bf16 v[220:223], v[180:183], v[148:151], v[46:49]
	v_mfma_f32_16x16x32_bf16 v[224:227], v[180:183], v[152:155], v[42:45]
	v_mfma_f32_16x16x32_bf16 v[138:141], v[188:191], v[148:151], v[38:41]
	v_mfma_f32_16x16x32_bf16 v[146:149], v[188:191], v[152:155], v[34:37]
	v_mfma_f32_16x16x32_bf16 v[30:33], v[160:163], v[98:101], v[30:33]
	v_mfma_f32_16x16x32_bf16 v[22:25], v[168:171], v[98:101], v[22:25]
	v_mfma_f32_16x16x32_bf16 v[14:17], v[176:179], v[98:101], v[14:17]
	v_mfma_f32_16x16x32_bf16 v[6:9], v[184:187], v[98:101], v[6:9]
	v_mfma_f32_16x16x32_bf16 v[30:33], v[164:167], v[106:109], v[30:33]
	v_mfma_f32_16x16x32_bf16 v[26:29], v[160:163], v[114:117], v[26:29]
	v_mfma_f32_16x16x32_bf16 v[22:25], v[172:175], v[106:109], v[22:25]
	v_mfma_f32_16x16x32_bf16 v[18:21], v[168:171], v[114:117], v[18:21]
	v_mfma_f32_16x16x32_bf16 v[14:17], v[180:183], v[106:109], v[14:17]
	v_mfma_f32_16x16x32_bf16 v[10:13], v[176:179], v[114:117], v[10:13]
	v_mfma_f32_16x16x32_bf16 v[6:9], v[188:191], v[106:109], v[6:9]
	v_mfma_f32_16x16x32_bf16 v[2:5], v[184:187], v[114:117], v[2:5]
	v_mfma_f32_16x16x32_bf16 v[150:153], v[164:167], v[122:125], v[26:29]
	v_mfma_f32_16x16x32_bf16 v[154:157], v[172:175], v[122:125], v[18:21]
	v_mfma_f32_16x16x32_bf16 v[158:161], v[180:183], v[122:125], v[10:13]
	v_mfma_f32_16x16x32_bf16 v[162:165], v[188:191], v[122:125], v[2:5]
	s_barrier
	s_nop 1
	ds_read_b128 v[2:5], v137
	ds_read_b128 v[166:169], v137 offset:1024
	ds_read_b128 v[170:173], v137 offset:2048
	ds_read_b128 v[174:177], v137 offset:3072
	ds_read_b128 v[10:13], v133 offset:32768
	ds_read_b128 v[18:21], v133 offset:33792
	ds_read_b128 v[26:29], v132 offset:32768
	ds_read_b128 v[38:41], v132 offset:33792
	ds_read_b128 v[46:49], v131 offset:32768
	ds_read_b128 v[178:181], v131 offset:33792
	ds_read_b128 v[182:185], v130 offset:32768
	ds_read_b128 v[186:189], v130 offset:33792
	s_waitcnt vmcnt(2)
	s_barrier
	s_waitcnt lgkmcnt(0)
	v_mfma_f32_16x16x32_bf16 v[34:37], v[10:13], v[2:5], v[126:129]
	v_mfma_f32_16x16x32_bf16 v[122:125], v[18:21], v[166:169], v[34:37]
	v_mfma_f32_16x16x32_bf16 v[34:37], v[10:13], v[170:173], v[142:145]
	v_mfma_f32_16x16x32_bf16 v[58:61], v[18:21], v[174:177], v[34:37]
	v_mfma_f32_16x16x32_bf16 v[34:37], v[26:29], v[2:5], v[118:121]
	v_mfma_f32_16x16x32_bf16 v[114:117], v[38:41], v[166:169], v[34:37]
	v_mfma_f32_16x16x32_bf16 v[34:37], v[26:29], v[170:173], v[192:195]
	v_mfma_f32_16x16x32_bf16 v[50:53], v[38:41], v[174:177], v[34:37]
	v_mfma_f32_16x16x32_bf16 v[34:37], v[46:49], v[2:5], v[110:113]
	v_mfma_f32_16x16x32_bf16 v[106:109], v[178:181], v[166:169], v[34:37]
	v_mfma_f32_16x16x32_bf16 v[34:37], v[46:49], v[170:173], v[196:199]
	v_mfma_f32_16x16x32_bf16 v[42:45], v[178:181], v[174:177], v[34:37]
	v_mfma_f32_16x16x32_bf16 v[34:37], v[182:185], v[2:5], v[102:105]
	v_mfma_f32_16x16x32_bf16 v[98:101], v[186:189], v[166:169], v[34:37]
	v_mfma_f32_16x16x32_bf16 v[34:37], v[182:185], v[170:173], v[200:203]
	v_mfma_f32_16x16x32_bf16 v[34:37], v[186:189], v[174:177], v[34:37]
	s_barrier
; #define WAIT_V(n) asm volatile("s_waitcnt vmcnt(" #n ")" ::: "memory")
; #define WAIT_L(n) asm volatile("s_waitcnt lgkmcnt(" #n ")" ::: "memory")
; #define BAR __builtin_amdgcn_s_barrier()
; __device__ __forceinline__ void mainloop_8phase(const u16* __restrict__ A, const u16* __restrict__ Bt, int K,
;                                                 f32x4 (&acc)[2][2][4][2], int wid_s, int ld) {
;     ...
;     LDB(B1, 1, 1); WAIT_V(0); BAR; WAIT_L(0); MMA(0, 1, At, B1); BAR;
;     LDA(At, 1, 1); BAR; WAIT_L(0); MMA(1, 0, At, B0); MMA(1, 1, At, B1); BAR; }
;   if (wr == 0) BAR;
	ds_read_b128 v[142:145], v134
	ds_read_b128 v[190:193], v134 offset:1024
	ds_read_b128 v[194:197], v134 offset:2048
	ds_read_b128 v[134:137], v134 offset:3072
	s_waitcnt vmcnt(0)
	s_barrier
	s_waitcnt lgkmcnt(0)
	v_mfma_f32_16x16x32_bf16 v[54:57], v[10:13], v[142:145], v[94:97]
	v_mfma_f32_16x16x32_bf16 v[10:13], v[10:13], v[194:197], v[90:93]
	v_mfma_f32_16x16x32_bf16 v[62:65], v[18:21], v[134:137], v[10:13]
	v_mfma_f32_16x16x32_bf16 v[10:13], v[26:29], v[142:145], v[86:89]
	v_mfma_f32_16x16x32_bf16 v[118:121], v[38:41], v[190:193], v[10:13]
	v_mfma_f32_16x16x32_bf16 v[10:13], v[26:29], v[194:197], v[82:85]
	v_mfma_f32_16x16x32_bf16 v[126:129], v[18:21], v[190:193], v[54:57]
	v_mfma_f32_16x16x32_bf16 v[54:57], v[38:41], v[134:137], v[10:13]
	v_mfma_f32_16x16x32_bf16 v[10:13], v[46:49], v[142:145], v[78:81]
	v_mfma_f32_16x16x32_bf16 v[110:113], v[178:181], v[190:193], v[10:13]
	v_mfma_f32_16x16x32_bf16 v[10:13], v[46:49], v[194:197], v[74:77]
	v_mfma_f32_16x16x32_bf16 v[46:49], v[178:181], v[134:137], v[10:13]
	v_mfma_f32_16x16x32_bf16 v[10:13], v[182:185], v[142:145], v[70:73]
	v_mfma_f32_16x16x32_bf16 v[102:105], v[186:189], v[190:193], v[10:13]
	v_mfma_f32_16x16x32_bf16 v[10:13], v[182:185], v[194:197], v[66:69]
	v_mfma_f32_16x16x32_bf16 v[38:41], v[186:189], v[134:137], v[10:13]
	s_barrier
	ds_read_b128 v[66:69], v133 offset:49152
	ds_read_b128 v[78:81], v133 offset:50176
	ds_read_b128 v[178:181], v132 offset:49152
	ds_read_b128 v[182:185], v132 offset:50176
	ds_read_b128 v[186:189], v131 offset:49152
	ds_read_b128 v[198:201], v131 offset:50176
	ds_read_b128 v[228:231], v130 offset:49152
	ds_read_b128 v[130:133], v130 offset:50176
	s_barrier
	s_waitcnt lgkmcnt(0)
	v_mfma_f32_16x16x32_bf16 v[10:13], v[66:69], v[2:5], v[204:207]
	v_mfma_f32_16x16x32_bf16 v[90:93], v[78:81], v[166:169], v[10:13]
	v_mfma_f32_16x16x32_bf16 v[10:13], v[66:69], v[170:173], v[208:211]
	v_mfma_f32_16x16x32_bf16 v[26:29], v[78:81], v[174:177], v[10:13]
	v_mfma_f32_16x16x32_bf16 v[10:13], v[178:181], v[2:5], v[212:215]
	v_mfma_f32_16x16x32_bf16 v[82:85], v[182:185], v[166:169], v[10:13]
	v_mfma_f32_16x16x32_bf16 v[10:13], v[178:181], v[170:173], v[216:219]
	v_mfma_f32_16x16x32_bf16 v[18:21], v[182:185], v[174:177], v[10:13]
	v_mfma_f32_16x16x32_bf16 v[10:13], v[186:189], v[2:5], v[220:223]
	v_mfma_f32_16x16x32_bf16 v[2:5], v[228:231], v[2:5], v[138:141]
	v_mfma_f32_16x16x32_bf16 v[74:77], v[198:201], v[166:169], v[10:13]
	v_mfma_f32_16x16x32_bf16 v[10:13], v[186:189], v[170:173], v[224:227]
	v_mfma_f32_16x16x32_bf16 v[70:73], v[130:133], v[166:169], v[2:5]
	v_mfma_f32_16x16x32_bf16 v[2:5], v[228:231], v[170:173], v[146:149]
	v_mfma_f32_16x16x32_bf16 v[10:13], v[198:201], v[174:177], v[10:13]
	v_mfma_f32_16x16x32_bf16 v[2:5], v[130:133], v[174:177], v[2:5]
	v_mfma_f32_16x16x32_bf16 v[30:33], v[66:69], v[142:145], v[30:33]
	v_mfma_f32_16x16x32_bf16 v[94:97], v[78:81], v[190:193], v[30:33]
	v_mfma_f32_16x16x32_bf16 v[30:33], v[66:69], v[194:197], v[150:153]
	v_mfma_f32_16x16x32_bf16 v[22:25], v[178:181], v[142:145], v[22:25]
	v_mfma_f32_16x16x32_bf16 v[14:17], v[186:189], v[142:145], v[14:17]
	v_mfma_f32_16x16x32_bf16 v[6:9], v[228:231], v[142:145], v[6:9]
	v_mfma_f32_16x16x32_bf16 v[30:33], v[78:81], v[134:137], v[30:33]
	v_mfma_f32_16x16x32_bf16 v[86:89], v[182:185], v[190:193], v[22:25]
	v_mfma_f32_16x16x32_bf16 v[22:25], v[178:181], v[194:197], v[154:157]
	v_mfma_f32_16x16x32_bf16 v[78:81], v[198:201], v[190:193], v[14:17]
	v_mfma_f32_16x16x32_bf16 v[14:17], v[186:189], v[194:197], v[158:161]
	v_mfma_f32_16x16x32_bf16 v[66:69], v[130:133], v[190:193], v[6:9]
	v_mfma_f32_16x16x32_bf16 v[6:9], v[228:231], v[194:197], v[162:165]
	v_mfma_f32_16x16x32_bf16 v[22:25], v[182:185], v[134:137], v[22:25]
	v_mfma_f32_16x16x32_bf16 v[14:17], v[198:201], v[134:137], v[14:17]
	v_mfma_f32_16x16x32_bf16 v[6:9], v[130:133], v[134:137], v[6:9]
	s_movk_i32 s1, 0x100
	v_cmp_gt_u32_e32 vcc, s1, v0
	s_barrier
	s_and_saveexec_b64 s[2:3], vcc
	s_cbranch_execz .LBB0_345
	s_barrier

; #define WAIT_V(n) asm volatile("s_waitcnt vmcnt(" #n ")" ::: "memory")
; #define WAIT_L(n) asm volatile("s_waitcnt lgkmcnt(" #n ")" ::: "memory")
; #define BAR __builtin_amdgcn_s_barrier()
; #define SCHED __builtin_amdgcn_sched_barrier(0)
; __device__ __forceinline__ void mainloop_8phase(const u16* __restrict__ A, const u16* __restrict__ Bt, int K,
;                                                 f32x4 (&acc)[2][2][4][2], int wid_s, int ld) {
;     ...
;     LDB(B0, 0, 0); SCHED; LDA(At, 0, 0); STAGE(SA(1, 1), A, brow + G_HALF, t + 1);
;     WAIT_L(8); BAR; WAIT_L(0); MMA(0, 0, At, B0); BAR; SCHED;
;     LDB(B1, 0, 1); STAGE(SB(0, 0), Bt, bcol, t + 2);
;     BAR; WAIT_L(0); MMA(0, 1, At, B1); BAR;
;     LDA(At, 0, 1); STAGE(SA(0, 0), A, brow, t + 2);
;     BAR; WAIT_L(0); MMA(1, 0, At, B0); BAR; SCHED;
;     STAGE(SB(0, 1), Bt, bcol + G_HALF, t + 2);
;     WAIT_V(6); BAR; MMA(1, 1, At, B1); BAR;
.LBB0_565:
	ds_read_b128 v[158:161], v156
	ds_read_b128 v[162:165], v156 offset:1024
	ds_read_b128 v[166:169], v156 offset:2048
	ds_read_b128 v[170:173], v156 offset:3072
	s_add_i32 s15, s27, s3
	v_readfirstlane_b32 s7, v146
	s_add_i32 s6, s15, 0x80
	s_mov_b32 m0, s7
	v_readfirstlane_b32 s7, v145
	ds_read_b128 v[174:177], v134
	ds_read_b128 v[178:181], v134 offset:1024
	ds_read_b128 v[182:185], v133
	ds_read_b128 v[186:189], v133 offset:1024
	ds_read_b128 v[190:193], v132
	ds_read_b128 v[194:197], v132 offset:1024
	ds_read_b128 v[198:201], v131
	ds_read_b128 v[202:205], v131 offset:1024
	buffer_load_dwordx4 v137, s[76:79], s6 offen lds
	s_mov_b32 m0, s7
	s_nop 0
	buffer_load_dwordx4 v138, s[76:79], s6 offen lds
	s_waitcnt lgkmcnt(8)
	s_barrier
	s_waitcnt lgkmcnt(0)
	v_mfma_f32_16x16x32_bf16 v[126:129], v[174:177], v[158:161], v[126:129]
	v_mfma_f32_16x16x32_bf16 v[122:125], v[174:177], v[166:169], v[122:125]
	v_mfma_f32_16x16x32_bf16 v[118:121], v[182:185], v[158:161], v[118:121]
	v_mfma_f32_16x16x32_bf16 v[114:117], v[182:185], v[166:169], v[114:117]
	v_mfma_f32_16x16x32_bf16 v[110:113], v[190:193], v[158:161], v[110:113]
	v_mfma_f32_16x16x32_bf16 v[106:109], v[190:193], v[166:169], v[106:109]
	v_mfma_f32_16x16x32_bf16 v[102:105], v[198:201], v[158:161], v[102:105]
	v_mfma_f32_16x16x32_bf16 v[98:101], v[198:201], v[166:169], v[98:101]
	v_mfma_f32_16x16x32_bf16 v[126:129], v[178:181], v[162:165], v[126:129]
	v_mfma_f32_16x16x32_bf16 v[122:125], v[178:181], v[170:173], v[122:125]
	v_mfma_f32_16x16x32_bf16 v[118:121], v[186:189], v[162:165], v[118:121]
	v_mfma_f32_16x16x32_bf16 v[114:117], v[186:189], v[170:173], v[114:117]
	v_mfma_f32_16x16x32_bf16 v[110:113], v[194:197], v[162:165], v[110:113]
	v_mfma_f32_16x16x32_bf16 v[106:109], v[194:197], v[170:173], v[106:109]
	v_mfma_f32_16x16x32_bf16 v[102:105], v[202:205], v[162:165], v[102:105]
	v_mfma_f32_16x16x32_bf16 v[98:101], v[202:205], v[170:173], v[98:101]
	s_barrier
	v_readfirstlane_b32 s34, v149
	s_add_i32 s14, s3, 0x100
	s_mov_b32 s6, s78
	s_mov_b32 s7, s79
	s_mov_b32 m0, s34
	v_readfirstlane_b32 s34, v150
	ds_read_b128 v[206:209], v148
	ds_read_b128 v[210:213], v148 offset:1024
	ds_read_b128 v[214:217], v148 offset:2048
	ds_read_b128 v[218:221], v148 offset:3072
	buffer_load_dwordx4 v137, s[4:7], s14 offen lds
	s_mov_b32 m0, s34
	s_add_i32 s2, s2, 2
	buffer_load_dwordx4 v138, s[4:7], s14 offen lds
	s_barrier
	s_waitcnt lgkmcnt(0)
	v_mfma_f32_16x16x32_bf16 v[94:97], v[174:177], v[206:209], v[94:97]
	v_mfma_f32_16x16x32_bf16 v[90:93], v[174:177], v[214:217], v[90:93]
	v_mfma_f32_16x16x32_bf16 v[86:89], v[182:185], v[206:209], v[86:89]
	v_mfma_f32_16x16x32_bf16 v[82:85], v[182:185], v[214:217], v[82:85]
	v_mfma_f32_16x16x32_bf16 v[78:81], v[190:193], v[206:209], v[78:81]
	v_mfma_f32_16x16x32_bf16 v[74:77], v[190:193], v[214:217], v[74:77]
	v_mfma_f32_16x16x32_bf16 v[70:73], v[198:201], v[206:209], v[70:73]
	v_mfma_f32_16x16x32_bf16 v[66:69], v[198:201], v[214:217], v[66:69]
	v_mfma_f32_16x16x32_bf16 v[94:97], v[178:181], v[210:213], v[94:97]
	v_mfma_f32_16x16x32_bf16 v[90:93], v[178:181], v[218:221], v[90:93]
	v_mfma_f32_16x16x32_bf16 v[86:89], v[186:189], v[210:213], v[86:89]
	v_mfma_f32_16x16x32_bf16 v[82:85], v[186:189], v[218:221], v[82:85]
	v_mfma_f32_16x16x32_bf16 v[78:81], v[194:197], v[210:213], v[78:81]
	v_mfma_f32_16x16x32_bf16 v[74:77], v[194:197], v[218:221], v[74:77]
	v_mfma_f32_16x16x32_bf16 v[70:73], v[202:205], v[210:213], v[70:73]
	v_mfma_f32_16x16x32_bf16 v[66:69], v[202:205], v[218:221], v[66:69]
	v_readfirstlane_b32 s34, v141
	s_mov_b32 m0, s34
	v_readfirstlane_b32 s34, v151
	s_barrier
	ds_read_b128 v[174:177], v134 offset:16384
	ds_read_b128 v[178:181], v134 offset:17408
	ds_read_b128 v[182:185], v133 offset:16384
	ds_read_b128 v[186:189], v133 offset:17408
	ds_read_b128 v[190:193], v132 offset:16384
	ds_read_b128 v[194:197], v132 offset:17408
	ds_read_b128 v[198:201], v131 offset:16384
	ds_read_b128 v[202:205], v131 offset:17408
	buffer_load_dwordx4 v137, s[76:79], s14 offen lds
	s_mov_b32 m0, s34
	s_nop 0
	buffer_load_dwordx4 v138, s[76:79], s14 offen lds
	s_barrier
	s_waitcnt lgkmcnt(0)
	v_mfma_f32_16x16x32_bf16 v[62:65], v[174:177], v[158:161], v[62:65]
	v_mfma_f32_16x16x32_bf16 v[58:61], v[174:177], v[166:169], v[58:61]
	v_mfma_f32_16x16x32_bf16 v[54:57], v[182:185], v[158:161], v[54:57]
	v_mfma_f32_16x16x32_bf16 v[50:53], v[182:185], v[166:169], v[50:53]
	v_mfma_f32_16x16x32_bf16 v[46:49], v[190:193], v[158:161], v[46:49]
	v_mfma_f32_16x16x32_bf16 v[42:45], v[190:193], v[166:169], v[42:45]
	v_mfma_f32_16x16x32_bf16 v[38:41], v[198:201], v[158:161], v[38:41]
	v_mfma_f32_16x16x32_bf16 v[34:37], v[198:201], v[166:169], v[34:37]
	v_mfma_f32_16x16x32_bf16 v[62:65], v[178:181], v[162:165], v[62:65]
	v_mfma_f32_16x16x32_bf16 v[58:61], v[178:181], v[170:173], v[58:61]
	v_mfma_f32_16x16x32_bf16 v[54:57], v[186:189], v[162:165], v[54:57]
	v_mfma_f32_16x16x32_bf16 v[50:53], v[186:189], v[170:173], v[50:53]
	v_mfma_f32_16x16x32_bf16 v[46:49], v[194:197], v[162:165], v[46:49]
	v_mfma_f32_16x16x32_bf16 v[42:45], v[194:197], v[170:173], v[42:45]
	v_mfma_f32_16x16x32_bf16 v[38:41], v[202:205], v[162:165], v[38:41]
	v_mfma_f32_16x16x32_bf16 v[34:37], v[202:205], v[170:173], v[34:37]
	s_barrier
	v_readfirstlane_b32 s35, v152
	s_add_i32 s34, s15, 0x100
	s_mov_b32 m0, s35
	v_readfirstlane_b32 s35, v153
	buffer_load_dwordx4 v137, s[4:7], s34 offen lds
	s_mov_b32 m0, s35
	s_nop 0
	buffer_load_dwordx4 v138, s[4:7], s34 offen lds
	s_waitcnt vmcnt(6)
	s_barrier
; #define WAIT_V(n) asm volatile("s_waitcnt vmcnt(" #n ")" ::: "memory")
; #define WAIT_L(n) asm volatile("s_waitcnt lgkmcnt(" #n ")" ::: "memory")
; #define BAR __builtin_amdgcn_s_barrier()
; #define SCHED __builtin_amdgcn_sched_barrier(0)
; __device__ __forceinline__ void mainloop_8phase(const u16* __restrict__ A, const u16* __restrict__ Bt, int K,
;                                                 f32x4 (&acc)[2][2][4][2], int wid_s, int ld) {
;     ...
;     WAIT_V(6); BAR; MMA(1, 1, At, B1); BAR;
;     LDB(B0, 1, 0); SCHED; LDA(At, 1, 0); STAGE(SA(0, 1), A, brow + G_HALF, t + 2);
;     WAIT_L(8); BAR; WAIT_L(0); MMA(0, 0, At, B0); BAR; SCHED;
;     LDB(B1, 1, 1); STAGE(SB(1, 0), Bt, bcol, t + 3);
;     BAR; WAIT_L(0); MMA(0, 1, At, B1); BAR;
;     LDA(At, 1, 1); STAGE(SA(1, 0), A, brow, t + 3);
	v_mfma_f32_16x16x32_bf16 v[30:33], v[174:177], v[206:209], v[30:33]
	v_mfma_f32_16x16x32_bf16 v[26:29], v[174:177], v[214:217], v[26:29]
	v_mfma_f32_16x16x32_bf16 v[22:25], v[182:185], v[206:209], v[22:25]
	v_mfma_f32_16x16x32_bf16 v[18:21], v[182:185], v[214:217], v[18:21]
	v_mfma_f32_16x16x32_bf16 v[14:17], v[190:193], v[206:209], v[14:17]
	v_mfma_f32_16x16x32_bf16 v[10:13], v[190:193], v[214:217], v[10:13]
	v_mfma_f32_16x16x32_bf16 v[6:9], v[198:201], v[206:209], v[6:9]
	v_mfma_f32_16x16x32_bf16 v[2:5], v[198:201], v[214:217], v[2:5]
	v_mfma_f32_16x16x32_bf16 v[30:33], v[178:181], v[210:213], v[30:33]
	v_mfma_f32_16x16x32_bf16 v[26:29], v[178:181], v[218:221], v[26:29]
	v_mfma_f32_16x16x32_bf16 v[22:25], v[186:189], v[210:213], v[22:25]
	v_mfma_f32_16x16x32_bf16 v[18:21], v[186:189], v[218:221], v[18:21]
	v_mfma_f32_16x16x32_bf16 v[14:17], v[194:197], v[210:213], v[14:17]
	v_mfma_f32_16x16x32_bf16 v[10:13], v[194:197], v[218:221], v[10:13]
	v_mfma_f32_16x16x32_bf16 v[6:9], v[202:205], v[210:213], v[6:9]
	v_mfma_f32_16x16x32_bf16 v[2:5], v[202:205], v[218:221], v[2:5]
	s_barrier
	ds_read_b128 v[158:161], v136
	ds_read_b128 v[162:165], v136 offset:1024
	ds_read_b128 v[166:169], v136 offset:2048
	ds_read_b128 v[170:173], v136 offset:3072
	v_readfirstlane_b32 s35, v154
	s_mov_b32 m0, s35
	v_readfirstlane_b32 s35, v155
	ds_read_b128 v[174:177], v134 offset:32768
	ds_read_b128 v[178:181], v134 offset:33792
	ds_read_b128 v[182:185], v133 offset:32768
	ds_read_b128 v[186:189], v133 offset:33792
	ds_read_b128 v[190:193], v132 offset:32768
	ds_read_b128 v[194:197], v132 offset:33792
	ds_read_b128 v[198:201], v131 offset:32768
	ds_read_b128 v[202:205], v131 offset:33792
	buffer_load_dwordx4 v137, s[76:79], s34 offen lds
	s_mov_b32 m0, s35
	s_nop 0
	buffer_load_dwordx4 v138, s[76:79], s34 offen lds
	s_waitcnt lgkmcnt(8)
	s_barrier
	s_waitcnt lgkmcnt(0)
	v_mfma_f32_16x16x32_bf16 v[126:129], v[174:177], v[158:161], v[126:129]
	v_mfma_f32_16x16x32_bf16 v[122:125], v[174:177], v[166:169], v[122:125]
	v_mfma_f32_16x16x32_bf16 v[118:121], v[182:185], v[158:161], v[118:121]
	v_mfma_f32_16x16x32_bf16 v[114:117], v[182:185], v[166:169], v[114:117]
	v_mfma_f32_16x16x32_bf16 v[110:113], v[190:193], v[158:161], v[110:113]
	v_mfma_f32_16x16x32_bf16 v[106:109], v[190:193], v[166:169], v[106:109]
	v_mfma_f32_16x16x32_bf16 v[102:105], v[198:201], v[158:161], v[102:105]
	v_mfma_f32_16x16x32_bf16 v[98:101], v[198:201], v[166:169], v[98:101]
	v_mfma_f32_16x16x32_bf16 v[126:129], v[178:181], v[162:165], v[126:129]
	v_mfma_f32_16x16x32_bf16 v[122:125], v[178:181], v[170:173], v[122:125]
	v_mfma_f32_16x16x32_bf16 v[118:121], v[186:189], v[162:165], v[118:121]
	v_mfma_f32_16x16x32_bf16 v[114:117], v[186:189], v[170:173], v[114:117]
	v_mfma_f32_16x16x32_bf16 v[110:113], v[194:197], v[162:165], v[110:113]
	v_mfma_f32_16x16x32_bf16 v[106:109], v[194:197], v[170:173], v[106:109]
	v_mfma_f32_16x16x32_bf16 v[102:105], v[202:205], v[162:165], v[102:105]
	v_mfma_f32_16x16x32_bf16 v[98:101], v[202:205], v[170:173], v[98:101]
	s_barrier
	v_readfirstlane_b32 s34, v139
	s_addk_i32 s3, 0x180
	s_mov_b32 m0, s34
	v_readfirstlane_b32 s34, v140
	ds_read_b128 v[206:209], v135
	ds_read_b128 v[210:213], v135 offset:1024
	ds_read_b128 v[214:217], v135 offset:2048
	ds_read_b128 v[218:221], v135 offset:3072
	buffer_load_dwordx4 v137, s[4:7], s3 offen lds
	s_mov_b32 m0, s34
	s_nop 0
	buffer_load_dwordx4 v138, s[4:7], s3 offen lds
	s_barrier
	s_waitcnt lgkmcnt(0)
	v_mfma_f32_16x16x32_bf16 v[94:97], v[174:177], v[206:209], v[94:97]
	v_mfma_f32_16x16x32_bf16 v[90:93], v[174:177], v[214:217], v[90:93]
	v_mfma_f32_16x16x32_bf16 v[86:89], v[182:185], v[206:209], v[86:89]
	v_mfma_f32_16x16x32_bf16 v[82:85], v[182:185], v[214:217], v[82:85]
	v_mfma_f32_16x16x32_bf16 v[78:81], v[190:193], v[206:209], v[78:81]
	v_mfma_f32_16x16x32_bf16 v[74:77], v[190:193], v[214:217], v[74:77]
	v_mfma_f32_16x16x32_bf16 v[70:73], v[198:201], v[206:209], v[70:73]
	v_mfma_f32_16x16x32_bf16 v[66:69], v[198:201], v[214:217], v[66:69]
	v_mfma_f32_16x16x32_bf16 v[94:97], v[178:181], v[210:213], v[94:97]
	v_mfma_f32_16x16x32_bf16 v[90:93], v[178:181], v[218:221], v[90:93]
	v_mfma_f32_16x16x32_bf16 v[86:89], v[186:189], v[210:213], v[86:89]
	v_mfma_f32_16x16x32_bf16 v[82:85], v[186:189], v[218:221], v[82:85]
	v_mfma_f32_16x16x32_bf16 v[78:81], v[194:197], v[210:213], v[78:81]
	v_mfma_f32_16x16x32_bf16 v[74:77], v[194:197], v[218:221], v[74:77]
	v_mfma_f32_16x16x32_bf16 v[70:73], v[202:205], v[210:213], v[70:73]
	v_mfma_f32_16x16x32_bf16 v[66:69], v[202:205], v[218:221], v[66:69]
	v_readfirstlane_b32 s34, v142
	s_mov_b32 m0, s34
	v_readfirstlane_b32 s34, v143
	s_barrier
	ds_read_b128 v[174:177], v134 offset:49152
	ds_read_b128 v[178:181], v134 offset:50176
	ds_read_b128 v[182:185], v133 offset:49152
	ds_read_b128 v[186:189], v133 offset:50176
	ds_read_b128 v[190:193], v132 offset:49152
	ds_read_b128 v[194:197], v132 offset:50176
	ds_read_b128 v[198:201], v131 offset:49152
	ds_read_b128 v[202:205], v131 offset:50176
	buffer_load_dwordx4 v137, s[76:79], s3 offen lds
	s_mov_b32 m0, s34
	s_nop 0
	buffer_load_dwordx4 v138, s[76:79], s3 offen lds
	s_barrier
; #define WAIT_V(n) asm volatile("s_waitcnt vmcnt(" #n ")" ::: "memory")
; #define WAIT_L(n) asm volatile("s_waitcnt lgkmcnt(" #n ")" ::: "memory")
; #define BAR __builtin_amdgcn_s_barrier()
; #define SCHED __builtin_amdgcn_sched_barrier(0)
; __device__ __forceinline__ void mainloop_8phase(const u16* __restrict__ A, const u16* __restrict__ Bt, int K,
;                                                 f32x4 (&acc)[2][2][4][2], int wid_s, int ld) {
;     ...
;     BAR; WAIT_L(0); MMA(1, 0, At, B0); BAR; SCHED;
;     STAGE(SB(1, 1), Bt, bcol + G_HALF, t + 3);
;     WAIT_V(6); BAR; MMA(1, 1, At, B1); BAR;
;   }
;   { LDB(B0, 0, 0); LDA(At, 0, 0); STAGE(SA(1, 1), A, brow + G_HALF, nt - 1);
;     BAR; WAIT_L(0); MMA(0, 0, At, B0); BAR;
;     LDB(B1, 0, 1); BAR; WAIT_L(0); MMA(0, 1, At, B1); BAR;
	s_waitcnt lgkmcnt(0)
	v_mfma_f32_16x16x32_bf16 v[62:65], v[174:177], v[158:161], v[62:65]
	v_mfma_f32_16x16x32_bf16 v[58:61], v[174:177], v[166:169], v[58:61]
	v_mfma_f32_16x16x32_bf16 v[54:57], v[182:185], v[158:161], v[54:57]
	v_mfma_f32_16x16x32_bf16 v[50:53], v[182:185], v[166:169], v[50:53]
	v_mfma_f32_16x16x32_bf16 v[46:49], v[190:193], v[158:161], v[46:49]
	v_mfma_f32_16x16x32_bf16 v[42:45], v[190:193], v[166:169], v[42:45]
	v_mfma_f32_16x16x32_bf16 v[38:41], v[198:201], v[158:161], v[38:41]
	v_mfma_f32_16x16x32_bf16 v[34:37], v[198:201], v[166:169], v[34:37]
	v_mfma_f32_16x16x32_bf16 v[62:65], v[178:181], v[162:165], v[62:65]
	v_mfma_f32_16x16x32_bf16 v[58:61], v[178:181], v[170:173], v[58:61]
	v_mfma_f32_16x16x32_bf16 v[54:57], v[186:189], v[162:165], v[54:57]
	v_mfma_f32_16x16x32_bf16 v[50:53], v[186:189], v[170:173], v[50:53]
	v_mfma_f32_16x16x32_bf16 v[46:49], v[194:197], v[162:165], v[46:49]
	v_mfma_f32_16x16x32_bf16 v[42:45], v[194:197], v[170:173], v[42:45]
	v_mfma_f32_16x16x32_bf16 v[38:41], v[202:205], v[162:165], v[38:41]
	v_mfma_f32_16x16x32_bf16 v[34:37], v[202:205], v[170:173], v[34:37]
	s_barrier
	v_readfirstlane_b32 s3, v144
	s_addk_i32 s15, 0x180
	s_mov_b32 m0, s3
	v_readfirstlane_b32 s3, v147
	buffer_load_dwordx4 v137, s[4:7], s15 offen lds
	s_mov_b32 m0, s3
	s_nop 0
	buffer_load_dwordx4 v138, s[4:7], s15 offen lds
	s_waitcnt vmcnt(6)
	s_barrier
	v_mfma_f32_16x16x32_bf16 v[30:33], v[174:177], v[206:209], v[30:33]
	v_mfma_f32_16x16x32_bf16 v[26:29], v[174:177], v[214:217], v[26:29]
	v_mfma_f32_16x16x32_bf16 v[22:25], v[182:185], v[206:209], v[22:25]
	v_mfma_f32_16x16x32_bf16 v[18:21], v[182:185], v[214:217], v[18:21]
	v_mfma_f32_16x16x32_bf16 v[14:17], v[190:193], v[206:209], v[14:17]
	v_mfma_f32_16x16x32_bf16 v[10:13], v[190:193], v[214:217], v[10:13]
	v_mfma_f32_16x16x32_bf16 v[6:9], v[198:201], v[206:209], v[6:9]
	v_mfma_f32_16x16x32_bf16 v[2:5], v[198:201], v[214:217], v[2:5]
	v_mfma_f32_16x16x32_bf16 v[30:33], v[178:181], v[210:213], v[30:33]
	v_mfma_f32_16x16x32_bf16 v[26:29], v[178:181], v[218:221], v[26:29]
	v_mfma_f32_16x16x32_bf16 v[22:25], v[186:189], v[210:213], v[22:25]
	v_mfma_f32_16x16x32_bf16 v[18:21], v[186:189], v[218:221], v[18:21]
	v_mfma_f32_16x16x32_bf16 v[14:17], v[194:197], v[210:213], v[14:17]
	v_mfma_f32_16x16x32_bf16 v[10:13], v[194:197], v[218:221], v[10:13]
	v_mfma_f32_16x16x32_bf16 v[6:9], v[202:205], v[210:213], v[6:9]
	v_mfma_f32_16x16x32_bf16 v[2:5], v[202:205], v[218:221], v[2:5]
	s_cmp_lt_u32 s2, s29
	s_mov_b32 s3, s14
	s_barrier
	s_cbranch_scc1 .LBB0_565
	v_readfirstlane_b32 s2, v146
	s_mov_b32 m0, s2
	v_readfirstlane_b32 s2, v145
	ds_read_b128 v[140:143], v156
	ds_read_b128 v[150:153], v156 offset:1024
	ds_read_b128 v[158:161], v156 offset:2048
	ds_read_b128 v[154:157], v156 offset:3072
	ds_read_b128 v[162:165], v134
	ds_read_b128 v[166:169], v134 offset:1024
	ds_read_b128 v[170:173], v133
	ds_read_b128 v[174:177], v133 offset:1024
	ds_read_b128 v[178:181], v132
	ds_read_b128 v[182:185], v132 offset:1024
	ds_read_b128 v[186:189], v131
	ds_read_b128 v[190:193], v131 offset:1024
	buffer_load_dwordx4 v137, s[76:79], s30 offen lds
	s_mov_b32 m0, s2
	s_nop 0
	buffer_load_dwordx4 v138, s[76:79], s30 offen lds
	s_barrier
	s_waitcnt lgkmcnt(0)
	v_mfma_f32_16x16x32_bf16 v[126:129], v[162:165], v[140:143], v[126:129]
	v_mfma_f32_16x16x32_bf16 v[118:121], v[170:173], v[140:143], v[118:121]
	v_mfma_f32_16x16x32_bf16 v[110:113], v[178:181], v[140:143], v[110:113]
	v_mfma_f32_16x16x32_bf16 v[102:105], v[186:189], v[140:143], v[102:105]
	v_mfma_f32_16x16x32_bf16 v[126:129], v[166:169], v[150:153], v[126:129]
	v_mfma_f32_16x16x32_bf16 v[122:125], v[162:165], v[158:161], v[122:125]
	v_mfma_f32_16x16x32_bf16 v[118:121], v[174:177], v[150:153], v[118:121]
	v_mfma_f32_16x16x32_bf16 v[114:117], v[170:173], v[158:161], v[114:117]
	v_mfma_f32_16x16x32_bf16 v[110:113], v[182:185], v[150:153], v[110:113]
	v_mfma_f32_16x16x32_bf16 v[106:109], v[178:181], v[158:161], v[106:109]
	v_mfma_f32_16x16x32_bf16 v[102:105], v[190:193], v[150:153], v[102:105]
	v_mfma_f32_16x16x32_bf16 v[98:101], v[186:189], v[158:161], v[98:101]
	v_mfma_f32_16x16x32_bf16 v[144:147], v[166:169], v[154:157], v[122:125]
	v_mfma_f32_16x16x32_bf16 v[194:197], v[174:177], v[154:157], v[114:117]
	v_mfma_f32_16x16x32_bf16 v[198:201], v[182:185], v[154:157], v[106:109]
	v_mfma_f32_16x16x32_bf16 v[202:205], v[190:193], v[154:157], v[98:101]
	s_barrier
	s_nop 1
	ds_read_b128 v[98:101], v148
	ds_read_b128 v[106:109], v148 offset:1024
	ds_read_b128 v[114:117], v148 offset:2048
	ds_read_b128 v[122:125], v148 offset:3072
	s_barrier
	s_waitcnt lgkmcnt(0)
	v_mfma_f32_16x16x32_bf16 v[94:97], v[162:165], v[98:101], v[94:97]
	v_mfma_f32_16x16x32_bf16 v[86:89], v[170:173], v[98:101], v[86:89]
	v_mfma_f32_16x16x32_bf16 v[78:81], v[178:181], v[98:101], v[78:81]
	v_mfma_f32_16x16x32_bf16 v[70:73], v[186:189], v[98:101], v[70:73]
	v_mfma_f32_16x16x32_bf16 v[94:97], v[166:169], v[106:109], v[94:97]
	v_mfma_f32_16x16x32_bf16 v[90:93], v[162:165], v[114:117], v[90:93]
	v_mfma_f32_16x16x32_bf16 v[86:89], v[174:177], v[106:109], v[86:89]
	v_mfma_f32_16x16x32_bf16 v[82:85], v[170:173], v[114:117], v[82:85]
	v_mfma_f32_16x16x32_bf16 v[78:81], v[182:185], v[106:109], v[78:81]
	v_mfma_f32_16x16x32_bf16 v[74:77], v[178:181], v[114:117], v[74:77]
	v_mfma_f32_16x16x32_bf16 v[70:73], v[190:193], v[106:109], v[70:73]
	v_mfma_f32_16x16x32_bf16 v[66:69], v[186:189], v[114:117], v[66:69]
	v_mfma_f32_16x16x32_bf16 v[162:165], v[166:169], v[122:125], v[90:93]
	v_mfma_f32_16x16x32_bf16 v[166:169], v[174:177], v[122:125], v[82:85]
	v_mfma_f32_16x16x32_bf16 v[170:173], v[182:185], v[122:125], v[74:77]
	v_mfma_f32_16x16x32_bf16 v[174:177], v[190:193], v[122:125], v[66:69]
	s_barrier
; #define WAIT_V(n) asm volatile("s_waitcnt vmcnt(" #n ")" ::: "memory")
; #define WAIT_L(n) asm volatile("s_waitcnt lgkmcnt(" #n ")" ::: "memory")
; #define BAR __builtin_amdgcn_s_barrier()
; __device__ __forceinline__ void mainloop_8phase(const u16* __restrict__ A, const u16* __restrict__ Bt, int K,
;                                                 f32x4 (&acc)[2][2][4][2], int wid_s, int ld) {
;     ...
;     LDA(At, 0, 1); WAIT_V(4); BAR; WAIT_L(0); MMA(1, 0, At, B0); MMA(1, 1, At, B1); BAR; }
;   { LDB(B0, 1, 0); LDA(At, 1, 0); WAIT_V(2); BAR; WAIT_L(0); MMA(0, 0, At, B0); BAR;
	s_nop 0
	ds_read_b128 v[66:69], v134 offset:16384
	ds_read_b128 v[74:77], v134 offset:17408
	ds_read_b128 v[82:85], v133 offset:16384
	ds_read_b128 v[90:93], v133 offset:17408
	ds_read_b128 v[178:181], v132 offset:16384
	ds_read_b128 v[182:185], v132 offset:17408
	ds_read_b128 v[186:189], v131 offset:16384
	ds_read_b128 v[190:193], v131 offset:17408
	s_waitcnt vmcnt(4)
	s_barrier
	s_waitcnt lgkmcnt(0)
	v_mfma_f32_16x16x32_bf16 v[62:65], v[66:69], v[140:143], v[62:65]
	v_mfma_f32_16x16x32_bf16 v[54:57], v[82:85], v[140:143], v[54:57]
	v_mfma_f32_16x16x32_bf16 v[46:49], v[178:181], v[140:143], v[46:49]
	v_mfma_f32_16x16x32_bf16 v[38:41], v[186:189], v[140:143], v[38:41]
	v_mfma_f32_16x16x32_bf16 v[62:65], v[74:77], v[150:153], v[62:65]
	v_mfma_f32_16x16x32_bf16 v[58:61], v[66:69], v[158:161], v[58:61]
	v_mfma_f32_16x16x32_bf16 v[54:57], v[90:93], v[150:153], v[54:57]
	v_mfma_f32_16x16x32_bf16 v[50:53], v[82:85], v[158:161], v[50:53]
	v_mfma_f32_16x16x32_bf16 v[46:49], v[182:185], v[150:153], v[46:49]
	v_mfma_f32_16x16x32_bf16 v[42:45], v[178:181], v[158:161], v[42:45]
	v_mfma_f32_16x16x32_bf16 v[38:41], v[190:193], v[150:153], v[38:41]
	v_mfma_f32_16x16x32_bf16 v[34:37], v[186:189], v[158:161], v[34:37]
	v_mfma_f32_16x16x32_bf16 v[206:209], v[74:77], v[154:157], v[58:61]
	v_mfma_f32_16x16x32_bf16 v[210:213], v[90:93], v[154:157], v[50:53]
	v_mfma_f32_16x16x32_bf16 v[214:217], v[182:185], v[154:157], v[42:45]
	v_mfma_f32_16x16x32_bf16 v[138:141], v[190:193], v[154:157], v[34:37]
	v_mfma_f32_16x16x32_bf16 v[30:33], v[66:69], v[98:101], v[30:33]
	v_mfma_f32_16x16x32_bf16 v[22:25], v[82:85], v[98:101], v[22:25]
	v_mfma_f32_16x16x32_bf16 v[14:17], v[178:181], v[98:101], v[14:17]
	v_mfma_f32_16x16x32_bf16 v[6:9], v[186:189], v[98:101], v[6:9]
	v_mfma_f32_16x16x32_bf16 v[30:33], v[74:77], v[106:109], v[30:33]
	v_mfma_f32_16x16x32_bf16 v[26:29], v[66:69], v[114:117], v[26:29]
	v_mfma_f32_16x16x32_bf16 v[22:25], v[90:93], v[106:109], v[22:25]
	v_mfma_f32_16x16x32_bf16 v[18:21], v[82:85], v[114:117], v[18:21]
	v_mfma_f32_16x16x32_bf16 v[14:17], v[182:185], v[106:109], v[14:17]
	v_mfma_f32_16x16x32_bf16 v[10:13], v[178:181], v[114:117], v[10:13]
	v_mfma_f32_16x16x32_bf16 v[6:9], v[190:193], v[106:109], v[6:9]
	v_mfma_f32_16x16x32_bf16 v[2:5], v[186:189], v[114:117], v[2:5]
	v_mfma_f32_16x16x32_bf16 v[148:151], v[74:77], v[122:125], v[26:29]
	v_mfma_f32_16x16x32_bf16 v[152:155], v[90:93], v[122:125], v[18:21]
	v_mfma_f32_16x16x32_bf16 v[156:159], v[182:185], v[122:125], v[10:13]
	v_mfma_f32_16x16x32_bf16 v[178:181], v[190:193], v[122:125], v[2:5]
	s_barrier
	s_nop 1
	ds_read_b128 v[2:5], v136
	ds_read_b128 v[10:13], v136 offset:1024
	ds_read_b128 v[18:21], v136 offset:2048
	ds_read_b128 v[26:29], v136 offset:3072
	ds_read_b128 v[34:37], v134 offset:32768
	ds_read_b128 v[42:45], v134 offset:33792
	ds_read_b128 v[50:53], v133 offset:32768
	ds_read_b128 v[58:61], v133 offset:33792
	ds_read_b128 v[66:69], v132 offset:32768
	ds_read_b128 v[182:185], v132 offset:33792
	ds_read_b128 v[186:189], v131 offset:32768
	ds_read_b128 v[190:193], v131 offset:33792
	s_waitcnt vmcnt(2)
	s_barrier
	s_waitcnt lgkmcnt(0)
	v_mfma_f32_16x16x32_bf16 v[74:77], v[34:37], v[2:5], v[126:129]
	v_mfma_f32_16x16x32_bf16 v[122:125], v[42:45], v[10:13], v[74:77]
	v_mfma_f32_16x16x32_bf16 v[74:77], v[34:37], v[18:21], v[144:147]
	v_mfma_f32_16x16x32_bf16 v[126:129], v[42:45], v[26:29], v[74:77]
	v_mfma_f32_16x16x32_bf16 v[74:77], v[50:53], v[2:5], v[118:121]
	v_mfma_f32_16x16x32_bf16 v[114:117], v[58:61], v[10:13], v[74:77]
	v_mfma_f32_16x16x32_bf16 v[74:77], v[50:53], v[18:21], v[194:197]
	v_mfma_f32_16x16x32_bf16 v[118:121], v[58:61], v[26:29], v[74:77]
	v_mfma_f32_16x16x32_bf16 v[74:77], v[66:69], v[2:5], v[110:113]
	v_mfma_f32_16x16x32_bf16 v[106:109], v[182:185], v[10:13], v[74:77]
	v_mfma_f32_16x16x32_bf16 v[74:77], v[66:69], v[18:21], v[198:201]
	v_mfma_f32_16x16x32_bf16 v[110:113], v[182:185], v[26:29], v[74:77]
	v_mfma_f32_16x16x32_bf16 v[74:77], v[186:189], v[2:5], v[102:105]
	v_mfma_f32_16x16x32_bf16 v[98:101], v[190:193], v[10:13], v[74:77]
	v_mfma_f32_16x16x32_bf16 v[74:77], v[186:189], v[18:21], v[202:205]
	v_mfma_f32_16x16x32_bf16 v[102:105], v[190:193], v[26:29], v[74:77]
	s_barrier
; #define WAIT_V(n) asm volatile("s_waitcnt vmcnt(" #n ")" ::: "memory")
; #define WAIT_L(n) asm volatile("s_waitcnt lgkmcnt(" #n ")" ::: "memory")
; #define BAR __builtin_amdgcn_s_barrier()
; __device__ __forceinline__ void mainloop_8phase(const u16* __restrict__ A, const u16* __restrict__ Bt, int K,
;                                                 f32x4 (&acc)[2][2][4][2], int wid_s, int ld) {
;     ...
;     LDB(B1, 1, 1); WAIT_V(0); BAR; WAIT_L(0); MMA(0, 1, At, B1); BAR;
;     LDA(At, 1, 1); BAR; WAIT_L(0); MMA(1, 0, At, B0); MMA(1, 1, At, B1); BAR; }
;   if (wr == 0) BAR;
	ds_read_b128 v[142:145], v135
	ds_read_b128 v[194:197], v135 offset:1024
	ds_read_b128 v[198:201], v135 offset:2048
	ds_read_b128 v[202:205], v135 offset:3072
	s_waitcnt vmcnt(0)
	s_barrier
	s_waitcnt lgkmcnt(0)
	v_mfma_f32_16x16x32_bf16 v[74:77], v[34:37], v[142:145], v[94:97]
	v_mfma_f32_16x16x32_bf16 v[34:37], v[34:37], v[198:201], v[162:165]
	v_mfma_f32_16x16x32_bf16 v[94:97], v[42:45], v[202:205], v[34:37]
	v_mfma_f32_16x16x32_bf16 v[34:37], v[50:53], v[142:145], v[86:89]
	v_mfma_f32_16x16x32_bf16 v[82:85], v[58:61], v[194:197], v[34:37]
	v_mfma_f32_16x16x32_bf16 v[34:37], v[50:53], v[198:201], v[166:169]
	v_mfma_f32_16x16x32_bf16 v[86:89], v[58:61], v[202:205], v[34:37]
	v_mfma_f32_16x16x32_bf16 v[34:37], v[66:69], v[142:145], v[78:81]
	v_mfma_f32_16x16x32_bf16 v[90:93], v[42:45], v[194:197], v[74:77]
	v_mfma_f32_16x16x32_bf16 v[74:77], v[182:185], v[194:197], v[34:37]
	v_mfma_f32_16x16x32_bf16 v[34:37], v[66:69], v[198:201], v[170:173]
	v_mfma_f32_16x16x32_bf16 v[78:81], v[182:185], v[202:205], v[34:37]
	v_mfma_f32_16x16x32_bf16 v[34:37], v[186:189], v[142:145], v[70:73]
	v_mfma_f32_16x16x32_bf16 v[66:69], v[190:193], v[194:197], v[34:37]
	v_mfma_f32_16x16x32_bf16 v[34:37], v[186:189], v[198:201], v[174:177]
	v_mfma_f32_16x16x32_bf16 v[70:73], v[190:193], v[202:205], v[34:37]
	s_barrier
	ds_read_b128 v[160:163], v134 offset:49152
	ds_read_b128 v[134:137], v134 offset:50176
	ds_read_b128 v[164:167], v133 offset:49152
	ds_read_b128 v[168:171], v133 offset:50176
	ds_read_b128 v[172:175], v132 offset:49152
	ds_read_b128 v[182:185], v132 offset:50176
	ds_read_b128 v[186:189], v131 offset:49152
	ds_read_b128 v[190:193], v131 offset:50176
	s_barrier
	s_waitcnt lgkmcnt(0)
	v_mfma_f32_16x16x32_bf16 v[34:37], v[160:163], v[2:5], v[62:65]
	v_mfma_f32_16x16x32_bf16 v[58:61], v[134:137], v[10:13], v[34:37]
	v_mfma_f32_16x16x32_bf16 v[34:37], v[160:163], v[18:21], v[206:209]
	v_mfma_f32_16x16x32_bf16 v[62:65], v[134:137], v[26:29], v[34:37]
	v_mfma_f32_16x16x32_bf16 v[34:37], v[164:167], v[2:5], v[54:57]
	v_mfma_f32_16x16x32_bf16 v[50:53], v[168:171], v[10:13], v[34:37]
	v_mfma_f32_16x16x32_bf16 v[34:37], v[164:167], v[18:21], v[210:213]
	v_mfma_f32_16x16x32_bf16 v[54:57], v[168:171], v[26:29], v[34:37]
	v_mfma_f32_16x16x32_bf16 v[34:37], v[172:175], v[2:5], v[46:49]
	v_mfma_f32_16x16x32_bf16 v[42:45], v[182:185], v[10:13], v[34:37]
	v_mfma_f32_16x16x32_bf16 v[34:37], v[172:175], v[18:21], v[214:217]
	v_mfma_f32_16x16x32_bf16 v[2:5], v[186:189], v[2:5], v[38:41]
	v_mfma_f32_16x16x32_bf16 v[46:49], v[182:185], v[26:29], v[34:37]
	v_mfma_f32_16x16x32_bf16 v[34:37], v[190:193], v[10:13], v[2:5]
	v_mfma_f32_16x16x32_bf16 v[2:5], v[186:189], v[18:21], v[138:141]
	v_mfma_f32_16x16x32_bf16 v[38:41], v[190:193], v[26:29], v[2:5]
	v_mfma_f32_16x16x32_bf16 v[2:5], v[160:163], v[142:145], v[30:33]
	v_mfma_f32_16x16x32_bf16 v[26:29], v[134:137], v[194:197], v[2:5]
	v_mfma_f32_16x16x32_bf16 v[2:5], v[160:163], v[198:201], v[148:151]
	v_mfma_f32_16x16x32_bf16 v[30:33], v[134:137], v[202:205], v[2:5]
	v_mfma_f32_16x16x32_bf16 v[2:5], v[164:167], v[142:145], v[22:25]
	v_mfma_f32_16x16x32_bf16 v[18:21], v[168:171], v[194:197], v[2:5]
	v_mfma_f32_16x16x32_bf16 v[2:5], v[164:167], v[198:201], v[152:155]
	v_mfma_f32_16x16x32_bf16 v[22:25], v[168:171], v[202:205], v[2:5]
	v_mfma_f32_16x16x32_bf16 v[2:5], v[172:175], v[142:145], v[14:17]
	v_mfma_f32_16x16x32_bf16 v[10:13], v[182:185], v[194:197], v[2:5]
	v_mfma_f32_16x16x32_bf16 v[2:5], v[172:175], v[198:201], v[156:159]
	v_mfma_f32_16x16x32_bf16 v[14:17], v[182:185], v[202:205], v[2:5]
	v_mfma_f32_16x16x32_bf16 v[2:5], v[186:189], v[142:145], v[6:9]
	v_mfma_f32_16x16x32_bf16 v[6:9], v[186:189], v[198:201], v[178:181]
	v_mfma_f32_16x16x32_bf16 v[2:5], v[190:193], v[194:197], v[2:5]
	v_mfma_f32_16x16x32_bf16 v[6:9], v[190:193], v[202:205], v[6:9]
	s_movk_i32 s2, 0x100
	v_cmp_gt_u32_e32 vcc, s2, v0
	s_barrier
	s_and_saveexec_b64 s[2:3], vcc
	s_cbranch_execz .LBB0_568
	s_barrier

; __device__ __forceinline__ unsigned xb_add(unsigned* p, unsigned v) { return __hip_atomic_fetch_add(p, v, __ATOMIC_RELAXED, __HIP_MEMORY_SCOPE_AGENT); }
; __device__ __forceinline__ void xcd_barrier(XcdBarrier& b, int tid) {
;   asm volatile("s_waitcnt vmcnt(0)" ::: "memory");
;   __syncthreads();
;   if (tid == 0) {
;     unsigned* bar = b.bar;
;     __builtin_amdgcn_s_waitcnt(0);
;     const unsigned old = xb_add(&bar[XB_XSUB(b.x)], 1u);
.LBB0_664:
	s_cmp_eq_u32 s12, 24
	s_cbranch_scc1 .LBB0_678
	v_mbcnt_lo_u32_b32 v0, -1, 0
	v_mbcnt_hi_u32_b32 v0, -1, v0
	s_waitcnt vmcnt(0)
	s_waitcnt lgkmcnt(0)
	v_or_b32_e32 v0, s33, v0
	v_cmp_eq_u32_e32 vcc, 0, v0
	s_barrier
	s_and_saveexec_b64 s[0:1], vcc
	s_cbranch_execz .LBB0_705
	s_mov_b64 s[2:3], exec
	v_mbcnt_lo_u32_b32 v0, s2, 0
	v_mbcnt_hi_u32_b32 v0, s3, v0
	v_cmp_eq_u32_e32 vcc, 0, v0
	s_waitcnt expcnt(0)
	s_and_saveexec_b64 s[4:5], vcc
	s_cbranch_execz .LBB0_668
	s_bcnt1_i32_b64 s2, s[2:3]
	v_mov_b32_e32 v2, s2
	v_readlane_b32 s2, v253, 9
	v_readlane_b32 s3, v253, 10
	s_nop 4
	global_atomic_add v2, v1, v2, s[2:3] sc0
